# ds_bpermute rotate-within-16-lanes shuffles in the P6 (conv3) and P1 (conv4) epilogues replaced by DPP row_ror movs (no LDS crossbar round trips)
# speedup vs baseline: 1.0100x; 1.0059x over previous
;     __device__ __forceinline__ void operator()(EPI_ARGS) const {
;     ...
;         if (pn >= 4 && pn < 12) {
;             const int lane = fq * 16 + fr, s1 = (lane & 48) | ((fr - 1) & 15), s2 = (lane & 48) | ((fr - 2) & 15), s3 = (lane & 48) | ((fr - 3) & 15);
; #pragma unroll
;             for (int bj = 0; bj < 2; ++bj) {
;                 const int c0 = (pn - 4) * 256 + bj * 128 + wc * 32 + 8 * fq;
;                 f32x4 w0[2], w1[2], w2[2], w3[2], bb[2];
; #pragma unroll
;                 for (int n = 0; n < 2; ++n) { w0[n] = *(const f32x4*)(cw + c0 + 4 * n); w1[n] = *(const f32x4*)(cw + LW + c0 + 4 * n); w2[n] = *(const f32x4*)(cw + 2 * LW + c0 + 4 * n); w3[n] = *(const f32x4*)(cw + 3 * LW + c0 + 4 * n); bb[n] = *(const f32x4*)(cb + c0 + 4 * n); }
; #pragma unroll
;                 for (int ai = 0; ai < 2; ++ai) {
;                     const int blk = u.pm * 4 + ai * 2 + wr;
;                     f32x4 q1[2], q2[2], q3[2];
; #pragma unroll
;                     for (int n = 0; n < 2; ++n) { q1[n] = (f32x4){0.f, 0.f, 0.f, 0.f}; q2[n] = q1[n]; q3[n] = q1[n]; }
; #pragma unroll
;                     for (int m = 0; m < 4; ++m) {
;                         const int row = ROW_OF(ai, m);
;                         f32x4 o[2];
; #pragma unroll
;                         for (int n = 0; n < 2; ++n) {
;                             const f32x4 gv = acc[ai][bj][m][n];
;                             f32x4 r1, r2, r3, p1, p2, p3;
; #pragma unroll
;                             for (int j = 0; j < 4; ++j) { r1[j] = __shfl(gv[j], s1); r2[j] = __shfl(gv[j], s2); r3[j] = __shfl(gv[j], s3); }
; #pragma unroll
;                             for (int j = 0; j < 4; ++j) { p1[j] = fr >= 1 ? r1[j] : q1[n][j]; p2[j] = fr >= 2 ? r2[j] : q2[n][j]; p3[j] = fr >= 3 ? r3[j] : q3[n][j]; }
;                             q1[n] = r1; q2[n] = r2; q3[n] = r3;
;                             o[n] = bb[n] + w0[n] * p3 + w1[n] * p2 + w2[n] * p1 + w3[n] * gv;
;                             if (m == 0 && fr < 3) *(f32x4*)(headu + ((size_t)blk * 3 + fr) * LW + c0 + 4 * n) = gv;
;                             if (m == 3 && fr >= 13) *(f32x4*)(tailu + ((size_t)blk * 3 + (fr - 13)) * LW + c0 + 4 * n) = gv;
;                         }
;                         if (!(m == 0 && fr < 3)) {
.LBB0_135:
	s_and_b64 vcc, exec, s[0:1]
	s_cbranch_vccz .LBB0_339
	s_lshl_b32 s0, s13, 8
	s_add_i32 s0, s19, s0
	v_lshl_add_u32 v184, v176, 3, s0
	v_ashrrev_i32_e32 v185, 31, v184
	v_lshlrev_b64 v[128:129], 2, v[184:185]
	v_lshl_add_u64 v[192:193], s[64:65], 0, v[128:129]
	v_lshl_add_u64 v[130:131], s[56:57], 0, v[128:129]
	v_lshl_add_u64 v[132:133], s[60:61], 0, v[128:129]
	v_lshl_add_u64 v[144:145], s[16:17], 0, v[128:129]
	v_lshl_add_u64 v[190:191], s[66:67], 0, v[128:129]
	global_load_dwordx4 v[160:163], v[192:193], off offset:16
	global_load_dwordx4 v[140:143], v[192:193], off
	global_load_dwordx4 v[156:159], v[130:131], off offset:16
	global_load_dwordx4 v[136:139], v[130:131], off
	global_load_dwordx4 v[152:155], v[132:133], off offset:16
	s_nop 0
	global_load_dwordx4 v[132:135], v[132:133], off
	s_nop 0
	global_load_dwordx4 v[148:151], v[144:145], off offset:16
	global_load_dwordx4 v[128:131], v[144:145], off
	global_load_dwordx4 v[164:167], v[190:191], off offset:16
	s_nop 0
	global_load_dwordx4 v[144:147], v[190:191], off
	v_lshl_add_u32 v176, v176, 4, v182
	v_add_u32_e32 v183, -1, v182
	v_and_b32_e32 v176, 48, v176
	v_and_b32_e32 v183, 15, v183
	v_add_u32_e32 v186, 14, v182
	v_add_u32_e32 v187, 13, v182
	v_and_b32_e32 v186, 15, v186
	v_and_b32_e32 v187, 15, v187
	v_or3_b32 v183, v176, v183, v214
	v_lshlrev_b32_e32 v216, 2, v183
	v_or3_b32 v183, v176, v186, v214
	v_or3_b32 v176, v176, v187, v214
	s_lshl_b32 s34, s12, 2
	v_lshlrev_b32_e32 v217, 2, v183
	v_lshlrev_b32_e32 v218, 2, v176
	s_add_i32 s34, s34, s45
	v_ashrrev_i32_e32 v183, 31, v182
	s_nop 1
	v_mov_b32_dpp v219, v124 row_ror:1 row_mask:0xf bank_mask:0xf
	v_mov_b32_dpp v220, v124 row_ror:2 row_mask:0xf bank_mask:0xf
	v_mov_b32_dpp v221, v124 row_ror:3 row_mask:0xf bank_mask:0xf
	v_mov_b32_dpp v222, v125 row_ror:1 row_mask:0xf bank_mask:0xf
	v_mov_b32_dpp v223, v125 row_ror:2 row_mask:0xf bank_mask:0xf
	v_mov_b32_dpp v224, v125 row_ror:3 row_mask:0xf bank_mask:0xf
	v_mov_b32_dpp v225, v126 row_ror:1 row_mask:0xf bank_mask:0xf
	v_mov_b32_dpp v226, v126 row_ror:2 row_mask:0xf bank_mask:0xf
	v_mov_b32_dpp v227, v126 row_ror:3 row_mask:0xf bank_mask:0xf
	v_mov_b32_dpp v228, v127 row_ror:1 row_mask:0xf bank_mask:0xf
	v_mov_b32_dpp v229, v127 row_ror:2 row_mask:0xf bank_mask:0xf
	v_mov_b32_dpp v230, v127 row_ror:3 row_mask:0xf bank_mask:0xf
	v_mad_i64_i32 v[186:187], s[0:1], s34, 3, v[182:183]
	v_lshlrev_b64 v[186:187], 13, v[186:187]
	v_lshl_add_u64 v[186:187], s[50:51], 0, v[186:187]
	v_cmp_lt_i32_e64 s[8:9], 2, v182
	v_cmp_gt_i32_e64 s[10:11], 3, v182
	v_lshl_add_u64 v[188:189], v[184:185], 2, v[186:187]
	s_and_saveexec_b64 s[0:1], s[10:11]
	s_cbranch_execz .LBB0_138
	global_store_dwordx4 v[188:189], v[124:127], off
.LBB0_138:
	s_or_b64 exec, exec, s[0:1]
	s_nop 1
	v_mov_b32_dpp v194, v120 row_ror:1 row_mask:0xf bank_mask:0xf
	v_mov_b32_dpp v198, v120 row_ror:2 row_mask:0xf bank_mask:0xf
	v_mov_b32_dpp v202, v120 row_ror:3 row_mask:0xf bank_mask:0xf
	v_mov_b32_dpp v195, v121 row_ror:1 row_mask:0xf bank_mask:0xf
	v_mov_b32_dpp v199, v121 row_ror:2 row_mask:0xf bank_mask:0xf
	v_mov_b32_dpp v203, v121 row_ror:3 row_mask:0xf bank_mask:0xf
	v_mov_b32_dpp v196, v122 row_ror:1 row_mask:0xf bank_mask:0xf
	v_mov_b32_dpp v200, v122 row_ror:2 row_mask:0xf bank_mask:0xf
	v_mov_b32_dpp v204, v122 row_ror:3 row_mask:0xf bank_mask:0xf
	v_mov_b32_dpp v197, v123 row_ror:1 row_mask:0xf bank_mask:0xf
	v_mov_b32_dpp v201, v123 row_ror:2 row_mask:0xf bank_mask:0xf
	v_mov_b32_dpp v205, v123 row_ror:3 row_mask:0xf bank_mask:0xf
	s_lshl_b32 s0, s12, 8
	s_add_i32 s0, s0, s24
	v_add_u32_e32 v186, s0, v182
	v_cmp_lt_i32_e32 vcc, 0, v182
	v_cmp_lt_i32_e64 s[0:1], 1, v182
	v_cmp_lt_i32_e64 s[4:5], 2, v182
	v_ashrrev_i32_e32 v187, 31, v186
	s_and_saveexec_b64 s[6:7], s[8:9]
	s_xor_b64 s[6:7], exec, s[6:7]
	s_cbranch_execz .LBB0_140
	s_waitcnt lgkmcnt(0)
	v_cndmask_b32_e64 v236, 0, v221, s[4:5]
	v_cndmask_b32_e64 v237, 0, v224, s[4:5]
	v_cndmask_b32_e64 v234, 0, v220, s[0:1]
	v_cndmask_b32_e64 v235, 0, v223, s[0:1]
	v_cndmask_b32_e64 v242, 0, v227, s[4:5]
	v_cndmask_b32_e64 v243, 0, v230, s[4:5]
	s_waitcnt vmcnt(0)
	v_pk_fma_f32 v[236:237], v[140:141], v[236:237], v[144:145]
	v_cndmask_b32_e32 v232, 0, v219, vcc
	v_cndmask_b32_e32 v233, 0, v222, vcc
	v_cndmask_b32_e64 v240, 0, v226, s[0:1]
	v_cndmask_b32_e64 v241, 0, v229, s[0:1]
	v_pk_fma_f32 v[242:243], v[142:143], v[242:243], v[146:147]
	v_pk_fma_f32 v[234:235], v[136:137], v[234:235], v[236:237]
	v_cndmask_b32_e32 v238, 0, v225, vcc
	v_cndmask_b32_e32 v239, 0, v228, vcc
	v_pk_fma_f32 v[240:241], v[138:139], v[240:241], v[242:243]
	v_pk_fma_f32 v[232:233], v[132:133], v[232:233], v[234:235]
	v_pk_fma_f32 v[234:235], v[134:135], v[238:239], v[240:241]
	v_pk_fma_f32 v[124:125], v[124:125], v[128:129], v[232:233]
	v_pk_fma_f32 v[232:233], v[162:163], v[204:205], v[166:167]
	v_pk_fma_f32 v[126:127], v[126:127], v[130:131], v[234:235]
	v_pk_fma_f32 v[234:235], v[160:161], v[202:203], v[164:165]
	v_pk_fma_f32 v[232:233], v[158:159], v[200:201], v[232:233]
	v_pk_fma_f32 v[234:235], v[156:157], v[198:199], v[234:235]
	v_pk_fma_f32 v[232:233], v[154:155], v[196:197], v[232:233]
	v_pk_fma_f32 v[234:235], v[152:153], v[194:195], v[234:235]
	v_pk_fma_f32 v[232:233], v[122:123], v[150:151], v[232:233]
	v_pk_fma_f32 v[234:235], v[120:121], v[148:149], v[234:235]
	v_cvt_pk_bf16_f32 v124, v124, v125
	v_cvt_pk_bf16_f32 v125, v126, v127
	s_nop 0
	v_cvt_pk_bf16_f32 v126, v234, v235
	v_cvt_pk_bf16_f32 v127, v232, v233
	v_lshlrev_b64 v[232:233], 12, v[186:187]
	v_lshl_add_u64 v[232:233], s[54:55], 0, v[232:233]
	v_lshl_add_u64 v[232:233], v[184:185], 1, v[232:233]
	global_store_dwordx4 v[232:233], v[124:127], off

; __device__ __forceinline__ unsigned cvt_pk_bf16(float lo, float hi) { unsigned r; asm volatile("v_cvt_pk_bf16_f32 %0, %1, %2" : "=v"(r) : "v"(lo), "v"(hi)); return r; }
;     __device__ __forceinline__ void operator()(EPI_ARGS) const {
;     ...
;                     for (int m = 0; m < 4; ++m) {
;                         const int row = ROW_OF(ai, m);
;                         f32x4 o[2];
; #pragma unroll
;                         for (int n = 0; n < 2; ++n) {
;                             const f32x4 gv = acc[ai][bj][m][n];
;                             f32x4 r1, r2, r3, p1, p2, p3;
; #pragma unroll
;                             for (int j = 0; j < 4; ++j) { r1[j] = __shfl(gv[j], s1); r2[j] = __shfl(gv[j], s2); r3[j] = __shfl(gv[j], s3); }
; #pragma unroll
;                             for (int j = 0; j < 4; ++j) { p1[j] = fr >= 1 ? r1[j] : q1[n][j]; p2[j] = fr >= 2 ? r2[j] : q2[n][j]; p3[j] = fr >= 3 ? r3[j] : q3[n][j]; }
;                             q1[n] = r1; q2[n] = r2; q3[n] = r3;
;                             o[n] = bb[n] + w0[n] * p3 + w1[n] * p2 + w2[n] * p1 + w3[n] * gv;
;                             if (m == 0 && fr < 3) *(f32x4*)(headu + ((size_t)blk * 3 + fr) * LW + c0 + 4 * n) = gv;
;                             if (m == 3 && fr >= 13) *(f32x4*)(tailu + ((size_t)blk * 3 + (fr - 13)) * LW + c0 + 4 * n) = gv;
;                         }
;                         if (!(m == 0 && fr < 3)) {
;                             u32x4 w; w.x = cvt_pk_bf16(o[0][0], o[0][1]); w.y = cvt_pk_bf16(o[0][2], o[0][3]); w.z = cvt_pk_bf16(o[1][0], o[1][1]); w.w = cvt_pk_bf16(o[1][2], o[1][3]);
;                             *(u32x4*)(vout + (size_t)row * LW + c0) = w;
;                         }
.LBB0_142:
	s_or_b64 exec, exec, s[6:7]
	s_nop 1
	v_mov_b32_dpp v232, v116 row_ror:2 row_mask:0xf bank_mask:0xf
	v_mov_b32_dpp v236, v117 row_ror:3 row_mask:0xf bank_mask:0xf
	v_mov_b32_dpp v237, v118 row_ror:1 row_mask:0xf bank_mask:0xf
	v_mov_b32_dpp v239, v118 row_ror:3 row_mask:0xf bank_mask:0xf
	v_mov_b32_dpp v242, v119 row_ror:3 row_mask:0xf bank_mask:0xf
	v_mov_b32_dpp v234, v117 row_ror:1 row_mask:0xf bank_mask:0xf
	v_mov_b32_dpp v235, v117 row_ror:2 row_mask:0xf bank_mask:0xf
	v_mov_b32_dpp v238, v118 row_ror:2 row_mask:0xf bank_mask:0xf
	v_mov_b32_dpp v241, v119 row_ror:2 row_mask:0xf bank_mask:0xf
	v_mov_b32_dpp v233, v116 row_ror:3 row_mask:0xf bank_mask:0xf
	v_mov_b32_dpp v240, v119 row_ror:1 row_mask:0xf bank_mask:0xf
	v_mov_b32_dpp v231, v116 row_ror:1 row_mask:0xf bank_mask:0xf
	s_waitcnt lgkmcnt(0)
	v_cndmask_b32_e64 v124, v220, v232, s[0:1]
	v_cndmask_b32_e64 v127, v224, v236, s[4:5]
	v_cndmask_b32_e32 v220, v225, v237, vcc
	v_cndmask_b32_e64 v224, v227, v239, s[4:5]
	v_cndmask_b32_e64 v225, v230, v242, s[4:5]
	v_cndmask_b32_e32 v123, v222, v234, vcc
	v_cndmask_b32_e64 v125, v223, v235, s[0:1]
	v_cndmask_b32_e64 v222, v226, v238, s[0:1]
	v_cndmask_b32_e64 v223, v229, v241, s[0:1]
	s_waitcnt vmcnt(0)
	v_pk_fma_f32 v[224:225], v[142:143], v[224:225], v[146:147]
	s_nop 1
	v_mov_b32_dpp v226, v112 row_ror:3 row_mask:0xf bank_mask:0xf
	v_mov_b32_dpp v229, v113 row_ror:3 row_mask:0xf bank_mask:0xf
	v_cndmask_b32_e64 v126, v221, v233, s[4:5]
	v_cndmask_b32_e32 v221, v228, v240, vcc
	v_pk_fma_f32 v[222:223], v[138:139], v[222:223], v[224:225]
	s_nop 1
	v_mov_b32_dpp v225, v112 row_ror:2 row_mask:0xf bank_mask:0xf
	v_mov_b32_dpp v228, v113 row_ror:2 row_mask:0xf bank_mask:0xf
	v_mov_b32_dpp v244, v114 row_ror:3 row_mask:0xf bank_mask:0xf
	v_mov_b32_dpp v247, v115 row_ror:3 row_mask:0xf bank_mask:0xf
	v_mov_b32_dpp v224, v112 row_ror:1 row_mask:0xf bank_mask:0xf
	v_mov_b32_dpp v227, v113 row_ror:1 row_mask:0xf bank_mask:0xf
	v_mov_b32_dpp v230, v114 row_ror:1 row_mask:0xf bank_mask:0xf
	v_mov_b32_dpp v243, v114 row_ror:2 row_mask:0xf bank_mask:0xf
	v_mov_b32_dpp v245, v115 row_ror:1 row_mask:0xf bank_mask:0xf
	v_mov_b32_dpp v246, v115 row_ror:2 row_mask:0xf bank_mask:0xf
	v_pk_fma_f32 v[126:127], v[140:141], v[126:127], v[144:145]
	v_cndmask_b32_e32 v122, v219, v231, vcc
	v_pk_fma_f32 v[124:125], v[136:137], v[124:125], v[126:127]
	s_waitcnt lgkmcnt(11)
	v_cndmask_b32_e64 v126, v202, v226, s[4:5]
	v_pk_fma_f32 v[122:123], v[132:133], v[122:123], v[124:125]
	v_pk_fma_f32 v[124:125], v[134:135], v[220:221], v[222:223]
	s_waitcnt lgkmcnt(10)
	v_cndmask_b32_e64 v127, v203, v229, s[4:5]
	v_pk_fma_f32 v[118:119], v[118:119], v[130:131], v[124:125]
	s_waitcnt lgkmcnt(9)
	v_cndmask_b32_e64 v124, v198, v225, s[0:1]
	s_waitcnt lgkmcnt(8)
	v_cndmask_b32_e64 v125, v199, v228, s[0:1]
	s_waitcnt lgkmcnt(7)
	v_cndmask_b32_e64 v198, v204, v244, s[4:5]
	s_waitcnt lgkmcnt(6)
	v_cndmask_b32_e64 v199, v205, v247, s[4:5]
	v_pk_fma_f32 v[126:127], v[160:161], v[126:127], v[164:165]
	v_pk_fma_f32 v[116:117], v[116:117], v[128:129], v[122:123]
	s_waitcnt lgkmcnt(5)
	v_cndmask_b32_e32 v122, v194, v224, vcc
	s_waitcnt lgkmcnt(4)
	v_cndmask_b32_e32 v123, v195, v227, vcc
	s_waitcnt lgkmcnt(3)
	v_cndmask_b32_e32 v194, v196, v230, vcc
	s_waitcnt lgkmcnt(2)
	v_cndmask_b32_e64 v196, v200, v243, s[0:1]
	s_waitcnt lgkmcnt(1)
	v_cndmask_b32_e32 v195, v197, v245, vcc
	s_waitcnt lgkmcnt(0)
	v_cndmask_b32_e64 v197, v201, v246, s[0:1]
	v_pk_fma_f32 v[198:199], v[162:163], v[198:199], v[166:167]
	v_pk_fma_f32 v[124:125], v[156:157], v[124:125], v[126:127]
	v_pk_fma_f32 v[196:197], v[158:159], v[196:197], v[198:199]
	v_pk_fma_f32 v[122:123], v[152:153], v[122:123], v[124:125]
	v_add_u32_e32 v126, 16, v186
	v_pk_fma_f32 v[124:125], v[154:155], v[194:195], v[196:197]
	v_pk_fma_f32 v[112:113], v[112:113], v[148:149], v[122:123]
	v_ashrrev_i32_e32 v127, 31, v126
	v_pk_fma_f32 v[114:115], v[114:115], v[150:151], v[124:125]
	v_cvt_pk_bf16_f32 v122, v116, v117
	v_cvt_pk_bf16_f32 v123, v118, v119
	v_cvt_pk_bf16_f32 v124, v112, v113
	v_lshlrev_b64 v[112:113], 12, v[126:127]
	v_lshl_add_u64 v[112:113], s[54:55], 0, v[112:113]
	v_lshlrev_b64 v[116:117], 1, v[184:185]
	v_cvt_pk_bf16_f32 v125, v114, v115
	v_lshl_add_u64 v[112:113], v[112:113], 0, v[116:117]
	global_store_dwordx4 v[112:113], v[122:125], off
	s_nop 1
	v_mov_b32_dpp v122, v108 row_ror:3 row_mask:0xf bank_mask:0xf
	v_mov_b32_dpp v125, v109 row_ror:3 row_mask:0xf bank_mask:0xf
	v_mov_b32_dpp v194, v110 row_ror:3 row_mask:0xf bank_mask:0xf
	v_mov_b32_dpp v197, v111 row_ror:3 row_mask:0xf bank_mask:0xf
	v_mov_b32_dpp v119, v108 row_ror:2 row_mask:0xf bank_mask:0xf
	v_mov_b32_dpp v124, v109 row_ror:2 row_mask:0xf bank_mask:0xf
	v_mov_b32_dpp v127, v110 row_ror:2 row_mask:0xf bank_mask:0xf
	v_mov_b32_dpp v196, v111 row_ror:2 row_mask:0xf bank_mask:0xf
	v_mov_b32_dpp v118, v108 row_ror:1 row_mask:0xf bank_mask:0xf
	v_mov_b32_dpp v123, v109 row_ror:1 row_mask:0xf bank_mask:0xf
	v_mov_b32_dpp v126, v110 row_ror:1 row_mask:0xf bank_mask:0xf
	v_mov_b32_dpp v195, v111 row_ror:1 row_mask:0xf bank_mask:0xf
	s_waitcnt lgkmcnt(11)
	v_cndmask_b32_e64 v200, v233, v122, s[4:5]
	s_waitcnt lgkmcnt(10)
	v_cndmask_b32_e64 v201, v236, v125, s[4:5]
	s_waitcnt lgkmcnt(9)
	v_cndmask_b32_e64 v220, v239, v194, s[4:5]
	s_waitcnt lgkmcnt(8)
	v_cndmask_b32_e64 v221, v242, v197, s[4:5]
	s_waitcnt lgkmcnt(7)
	v_cndmask_b32_e64 v198, v232, v119, s[0:1]
	s_waitcnt lgkmcnt(6)
	v_cndmask_b32_e64 v199, v235, v124, s[0:1]
	s_waitcnt lgkmcnt(5)
	v_cndmask_b32_e64 v204, v238, v127, s[0:1]
	s_waitcnt lgkmcnt(4)
; __device__ __forceinline__ unsigned cvt_pk_bf16(float lo, float hi) { unsigned r; asm volatile("v_cvt_pk_bf16_f32 %0, %1, %2" : "=v"(r) : "v"(lo), "v"(hi)); return r; }
;     __device__ __forceinline__ void operator()(EPI_ARGS) const {
;     ...
;                     for (int m = 0; m < 4; ++m) {
;                         const int row = ROW_OF(ai, m);
;                         f32x4 o[2];
; #pragma unroll
;                         for (int n = 0; n < 2; ++n) {
;                             const f32x4 gv = acc[ai][bj][m][n];
;                             f32x4 r1, r2, r3, p1, p2, p3;
; #pragma unroll
;                             for (int j = 0; j < 4; ++j) { r1[j] = __shfl(gv[j], s1); r2[j] = __shfl(gv[j], s2); r3[j] = __shfl(gv[j], s3); }
; #pragma unroll
;                             for (int j = 0; j < 4; ++j) { p1[j] = fr >= 1 ? r1[j] : q1[n][j]; p2[j] = fr >= 2 ? r2[j] : q2[n][j]; p3[j] = fr >= 3 ? r3[j] : q3[n][j]; }
;                             q1[n] = r1; q2[n] = r2; q3[n] = r3;
;                             o[n] = bb[n] + w0[n] * p3 + w1[n] * p2 + w2[n] * p1 + w3[n] * gv;
;                             if (m == 0 && fr < 3) *(f32x4*)(headu + ((size_t)blk * 3 + fr) * LW + c0 + 4 * n) = gv;
;                             if (m == 3 && fr >= 13) *(f32x4*)(tailu + ((size_t)blk * 3 + (fr - 13)) * LW + c0 + 4 * n) = gv;
;                         }
;                         if (!(m == 0 && fr < 3)) {
;                             u32x4 w; w.x = cvt_pk_bf16(o[0][0], o[0][1]); w.y = cvt_pk_bf16(o[0][2], o[0][3]); w.z = cvt_pk_bf16(o[1][0], o[1][1]); w.w = cvt_pk_bf16(o[1][2], o[1][3]);
;                             *(u32x4*)(vout + (size_t)row * LW + c0) = w;
;                         }
	v_cndmask_b32_e64 v205, v241, v196, s[0:1]
	v_pk_fma_f32 v[200:201], v[140:141], v[200:201], v[144:145]
	v_pk_fma_f32 v[220:221], v[142:143], v[220:221], v[146:147]
	s_waitcnt lgkmcnt(3)
	v_cndmask_b32_e32 v114, v231, v118, vcc
	s_waitcnt lgkmcnt(2)
	v_cndmask_b32_e32 v115, v234, v123, vcc
	s_waitcnt lgkmcnt(1)
	v_cndmask_b32_e32 v202, v237, v126, vcc
	s_waitcnt lgkmcnt(0)
	v_cndmask_b32_e32 v203, v240, v195, vcc
	v_pk_fma_f32 v[204:205], v[138:139], v[204:205], v[220:221]
	v_pk_fma_f32 v[198:199], v[136:137], v[198:199], v[200:201]
	s_nop 1
	v_mov_b32_dpp v201, v105 row_ror:3 row_mask:0xf bank_mask:0xf
	v_pk_fma_f32 v[114:115], v[132:133], v[114:115], v[198:199]
	v_pk_fma_f32 v[198:199], v[134:135], v[202:203], v[204:205]
	s_nop 1
	v_mov_b32_dpp v200, v105 row_ror:2 row_mask:0xf bank_mask:0xf
	v_pk_fma_f32 v[222:223], v[110:111], v[130:131], v[198:199]
	s_nop 1
	v_mov_b32_dpp v198, v104 row_ror:3 row_mask:0xf bank_mask:0xf
	v_mov_b32_dpp v199, v105 row_ror:1 row_mask:0xf bank_mask:0xf
	v_mov_b32_dpp v110, v104 row_ror:1 row_mask:0xf bank_mask:0xf
	v_mov_b32_dpp v111, v104 row_ror:2 row_mask:0xf bank_mask:0xf
	v_mov_b32_dpp v204, v106 row_ror:3 row_mask:0xf bank_mask:0xf
	v_mov_b32_dpp v220, v107 row_ror:3 row_mask:0xf bank_mask:0xf
	v_mov_b32_dpp v202, v106 row_ror:1 row_mask:0xf bank_mask:0xf
	v_mov_b32_dpp v203, v106 row_ror:2 row_mask:0xf bank_mask:0xf
	v_mov_b32_dpp v219, v107 row_ror:2 row_mask:0xf bank_mask:0xf
	v_mov_b32_dpp v205, v107 row_ror:1 row_mask:0xf bank_mask:0xf
	v_pk_fma_f32 v[108:109], v[108:109], v[128:129], v[114:115]
	s_waitcnt lgkmcnt(9)
	v_cndmask_b32_e64 v226, v226, v198, s[4:5]
	s_waitcnt lgkmcnt(8)
	v_cndmask_b32_e32 v115, v227, v199, vcc
	v_cndmask_b32_e64 v227, v229, v201, s[4:5]
	s_waitcnt lgkmcnt(7)
	v_cndmask_b32_e32 v114, v224, v110, vcc
	s_waitcnt lgkmcnt(6)
	v_cndmask_b32_e64 v224, v225, v111, s[0:1]
	v_cndmask_b32_e64 v225, v228, v200, s[0:1]
	v_pk_fma_f32 v[226:227], v[160:161], v[226:227], v[164:165]
	s_waitcnt lgkmcnt(5)
	v_cndmask_b32_e64 v232, v244, v204, s[4:5]
	s_waitcnt lgkmcnt(4)
	v_cndmask_b32_e64 v233, v247, v220, s[4:5]
	v_pk_fma_f32 v[224:225], v[156:157], v[224:225], v[226:227]
	s_waitcnt lgkmcnt(3)
	v_cndmask_b32_e32 v228, v230, v202, vcc
	s_waitcnt lgkmcnt(2)
	v_cndmask_b32_e64 v230, v243, v203, s[0:1]
	s_waitcnt lgkmcnt(1)
	v_cndmask_b32_e64 v231, v246, v219, s[0:1]
	v_pk_fma_f32 v[232:233], v[162:163], v[232:233], v[166:167]
	v_pk_fma_f32 v[114:115], v[152:153], v[114:115], v[224:225]
	s_waitcnt lgkmcnt(0)
	v_cndmask_b32_e32 v229, v245, v205, vcc
	v_pk_fma_f32 v[230:231], v[158:159], v[230:231], v[232:233]
	v_pk_fma_f32 v[104:105], v[104:105], v[148:149], v[114:115]
	v_add_u32_e32 v114, 32, v186
	v_pk_fma_f32 v[224:225], v[154:155], v[228:229], v[230:231]
	v_ashrrev_i32_e32 v115, 31, v114
	v_pk_fma_f32 v[106:107], v[106:107], v[150:151], v[224:225]
	v_cvt_pk_bf16_f32 v230, v108, v109
	v_cvt_pk_bf16_f32 v231, v222, v223
	v_cvt_pk_bf16_f32 v232, v104, v105
	v_lshlrev_b64 v[104:105], 12, v[114:115]
	s_mul_hi_i32 s13, s34, 3
	s_mul_i32 s12, s34, 3
	v_add_u32_e32 v176, -13, v182
	v_cvt_pk_bf16_f32 v233, v106, v107
	v_lshl_add_u64 v[108:109], s[54:55], 0, v[104:105]
	s_nop 1
	v_mov_b32_dpp v104, v96 row_ror:1 row_mask:0xf bank_mask:0xf
	v_mov_b32_dpp v105, v96 row_ror:2 row_mask:0xf bank_mask:0xf
	v_mov_b32_dpp v106, v96 row_ror:3 row_mask:0xf bank_mask:0xf
	v_mov_b32_dpp v107, v97 row_ror:1 row_mask:0xf bank_mask:0xf
	v_mov_b32_dpp v221, v97 row_ror:2 row_mask:0xf bank_mask:0xf
	v_mov_b32_dpp v222, v97 row_ror:3 row_mask:0xf bank_mask:0xf
	v_mov_b32_dpp v223, v98 row_ror:1 row_mask:0xf bank_mask:0xf
	v_mov_b32_dpp v224, v98 row_ror:2 row_mask:0xf bank_mask:0xf
	v_mov_b32_dpp v225, v98 row_ror:3 row_mask:0xf bank_mask:0xf
	v_mov_b32_dpp v226, v99 row_ror:1 row_mask:0xf bank_mask:0xf
	v_mov_b32_dpp v227, v99 row_ror:2 row_mask:0xf bank_mask:0xf
	v_mov_b32_dpp v228, v99 row_ror:3 row_mask:0xf bank_mask:0xf
	v_lshl_add_u64 v[120:121], s[12:13], 0, v[176:177]
	v_lshlrev_b64 v[120:121], 13, v[120:121]
	v_lshl_add_u64 v[114:115], v[108:109], 0, v[116:117]
	v_lshl_add_u64 v[108:109], s[74:75], 0, v[120:121]
	v_cmp_lt_i32_e64 s[6:7], 12, v182
	v_lshl_add_u64 v[108:109], v[184:185], 2, v[108:109]
	global_store_dwordx4 v[114:115], v[230:233], off
	s_and_saveexec_b64 s[12:13], s[6:7]
	s_cbranch_execz .LBB0_144
	global_store_dwordx4 v[108:109], v[96:99], off
.LBB0_144:
	s_or_b64 exec, exec, s[12:13]
	s_nop 1
	v_mov_b32_dpp v120, v100 row_ror:1 row_mask:0xf bank_mask:0xf
	v_mov_b32_dpp v121, v100 row_ror:2 row_mask:0xf bank_mask:0xf
	v_mov_b32_dpp v229, v100 row_ror:3 row_mask:0xf bank_mask:0xf
	v_mov_b32_dpp v230, v101 row_ror:1 row_mask:0xf bank_mask:0xf
	v_mov_b32_dpp v231, v101 row_ror:2 row_mask:0xf bank_mask:0xf
	v_mov_b32_dpp v232, v101 row_ror:3 row_mask:0xf bank_mask:0xf
	v_mov_b32_dpp v233, v102 row_ror:1 row_mask:0xf bank_mask:0xf
	v_mov_b32_dpp v234, v102 row_ror:2 row_mask:0xf bank_mask:0xf
	v_mov_b32_dpp v235, v102 row_ror:3 row_mask:0xf bank_mask:0xf
	v_mov_b32_dpp v236, v103 row_ror:1 row_mask:0xf bank_mask:0xf
	v_mov_b32_dpp v237, v103 row_ror:2 row_mask:0xf bank_mask:0xf
	v_mov_b32_dpp v238, v103 row_ror:3 row_mask:0xf bank_mask:0xf
	s_and_saveexec_b64 s[12:13], s[6:7]
	s_cbranch_execz .LBB0_146
	global_store_dwordx4 v[108:109], v[100:103], off offset:16
; __device__ __forceinline__ unsigned cvt_pk_bf16(float lo, float hi) { unsigned r; asm volatile("v_cvt_pk_bf16_f32 %0, %1, %2" : "=v"(r) : "v"(lo), "v"(hi)); return r; }
;     __device__ __forceinline__ void operator()(EPI_ARGS) const {
;     ...
;                     for (int m = 0; m < 4; ++m) {
;                         const int row = ROW_OF(ai, m);
;                         f32x4 o[2];
; #pragma unroll
;                         for (int n = 0; n < 2; ++n) {
;                             const f32x4 gv = acc[ai][bj][m][n];
;                             f32x4 r1, r2, r3, p1, p2, p3;
; #pragma unroll
;                             for (int j = 0; j < 4; ++j) { r1[j] = __shfl(gv[j], s1); r2[j] = __shfl(gv[j], s2); r3[j] = __shfl(gv[j], s3); }
; #pragma unroll
;                             for (int j = 0; j < 4; ++j) { p1[j] = fr >= 1 ? r1[j] : q1[n][j]; p2[j] = fr >= 2 ? r2[j] : q2[n][j]; p3[j] = fr >= 3 ? r3[j] : q3[n][j]; }
;                             q1[n] = r1; q2[n] = r2; q3[n] = r3;
;                             o[n] = bb[n] + w0[n] * p3 + w1[n] * p2 + w2[n] * p1 + w3[n] * gv;
;                             if (m == 0 && fr < 3) *(f32x4*)(headu + ((size_t)blk * 3 + fr) * LW + c0 + 4 * n) = gv;
;                             if (m == 3 && fr >= 13) *(f32x4*)(tailu + ((size_t)blk * 3 + (fr - 13)) * LW + c0 + 4 * n) = gv;
;                         }
;                         if (!(m == 0 && fr < 3)) {
;                             u32x4 w; w.x = cvt_pk_bf16(o[0][0], o[0][1]); w.y = cvt_pk_bf16(o[0][2], o[0][3]); w.z = cvt_pk_bf16(o[1][0], o[1][1]); w.w = cvt_pk_bf16(o[1][2], o[1][3]);
;                             *(u32x4*)(vout + (size_t)row * LW + c0) = w;
;                         }
.LBB0_146:
	s_or_b64 exec, exec, s[12:13]
	s_waitcnt lgkmcnt(11)
	v_cndmask_b32_e32 v110, v110, v120, vcc
	s_waitcnt lgkmcnt(10)
	v_cndmask_b32_e64 v120, v111, v121, s[0:1]
	s_waitcnt lgkmcnt(9)
	v_cndmask_b32_e64 v198, v198, v229, s[4:5]
	s_waitcnt lgkmcnt(8)
	v_cndmask_b32_e32 v111, v199, v230, vcc
	s_waitcnt lgkmcnt(6)
	v_cndmask_b32_e64 v199, v201, v232, s[4:5]
	v_cndmask_b32_e64 v121, v200, v231, s[0:1]
	v_pk_fma_f32 v[198:199], v[160:161], v[198:199], v[164:165]
	s_waitcnt lgkmcnt(3)
	v_cndmask_b32_e64 v204, v204, v235, s[4:5]
	s_waitcnt lgkmcnt(2)
	v_cndmask_b32_e32 v201, v205, v236, vcc
	s_waitcnt lgkmcnt(0)
	v_cndmask_b32_e64 v205, v220, v238, s[4:5]
	v_pk_fma_f32 v[120:121], v[156:157], v[120:121], v[198:199]
	v_cndmask_b32_e32 v200, v202, v233, vcc
	v_cndmask_b32_e64 v202, v203, v234, s[0:1]
	v_cndmask_b32_e64 v203, v219, v237, s[0:1]
	v_pk_fma_f32 v[204:205], v[162:163], v[204:205], v[166:167]
	v_pk_fma_f32 v[110:111], v[152:153], v[110:111], v[120:121]
	v_pk_fma_f32 v[202:203], v[158:159], v[202:203], v[204:205]
	v_pk_fma_f32 v[100:101], v[100:101], v[148:149], v[110:111]
	v_cndmask_b32_e64 v110, v119, v105, s[0:1]
	v_cndmask_b32_e64 v106, v122, v106, s[4:5]
	v_cndmask_b32_e32 v105, v123, v107, vcc
	v_cndmask_b32_e64 v107, v125, v222, s[4:5]
	v_pk_fma_f32 v[120:121], v[154:155], v[200:201], v[202:203]
	v_cndmask_b32_e64 v111, v124, v221, s[0:1]
	v_cndmask_b32_e64 v122, v194, v225, s[4:5]
	v_cndmask_b32_e64 v123, v197, v228, s[4:5]
	v_pk_fma_f32 v[106:107], v[140:141], v[106:107], v[144:145]
	v_pk_fma_f32 v[102:103], v[102:103], v[150:151], v[120:121]
	v_cndmask_b32_e32 v104, v118, v104, vcc
	v_cndmask_b32_e64 v120, v127, v224, s[0:1]
	v_cndmask_b32_e64 v121, v196, v227, s[0:1]
	v_pk_fma_f32 v[122:123], v[142:143], v[122:123], v[146:147]
	v_pk_fma_f32 v[106:107], v[136:137], v[110:111], v[106:107]
	v_cndmask_b32_e32 v118, v126, v223, vcc
	v_cndmask_b32_e32 v119, v195, v226, vcc
	v_pk_fma_f32 v[120:121], v[138:139], v[120:121], v[122:123]
	v_pk_fma_f32 v[104:105], v[132:133], v[104:105], v[106:107]
	v_pk_fma_f32 v[106:107], v[134:135], v[118:119], v[120:121]
	v_pk_fma_f32 v[96:97], v[96:97], v[128:129], v[104:105]
	v_add_u32_e32 v104, 48, v186
	v_pk_fma_f32 v[98:99], v[98:99], v[130:131], v[106:107]
	v_ashrrev_i32_e32 v105, 31, v104
	v_cvt_pk_bf16_f32 v96, v96, v97
	v_cvt_pk_bf16_f32 v97, v98, v99
	v_cvt_pk_bf16_f32 v98, v100, v101
	v_lshlrev_b64 v[100:101], 12, v[104:105]
	v_lshl_add_u64 v[100:101], s[54:55], 0, v[100:101]
	v_lshl_add_u64 v[110:111], v[184:185], 1, v[100:101]
	s_add_i32 s87, s34, 2
	s_nop 1
	v_mov_b32_dpp v122, v92 row_ror:1 row_mask:0xf bank_mask:0xf
	v_mov_b32_dpp v123, v92 row_ror:2 row_mask:0xf bank_mask:0xf
	v_mov_b32_dpp v124, v92 row_ror:3 row_mask:0xf bank_mask:0xf
	v_mov_b32_dpp v125, v93 row_ror:1 row_mask:0xf bank_mask:0xf
	v_mov_b32_dpp v126, v93 row_ror:2 row_mask:0xf bank_mask:0xf
	v_mov_b32_dpp v127, v93 row_ror:3 row_mask:0xf bank_mask:0xf
	v_mov_b32_dpp v194, v94 row_ror:1 row_mask:0xf bank_mask:0xf
	v_mov_b32_dpp v195, v94 row_ror:2 row_mask:0xf bank_mask:0xf
	v_mov_b32_dpp v196, v94 row_ror:3 row_mask:0xf bank_mask:0xf
	v_mov_b32_dpp v197, v95 row_ror:1 row_mask:0xf bank_mask:0xf
	v_mov_b32_dpp v198, v95 row_ror:2 row_mask:0xf bank_mask:0xf
	v_mov_b32_dpp v199, v95 row_ror:3 row_mask:0xf bank_mask:0xf
	v_cvt_pk_bf16_f32 v99, v102, v103
	global_store_dwordx4 v[110:111], v[96:99], off
	s_nop 1
	v_mad_i64_i32 v[96:97], s[12:13], s87, 3, v[182:183]
	v_lshlrev_b64 v[96:97], 13, v[96:97]
	v_lshl_add_u64 v[96:97], s[50:51], 0, v[96:97]
	v_lshl_add_u64 v[106:107], v[184:185], 2, v[96:97]
	s_and_saveexec_b64 s[12:13], s[10:11]
	s_cbranch_execz .LBB0_148
	global_store_dwordx4 v[106:107], v[92:95], off
.LBB0_148:
	s_or_b64 exec, exec, s[12:13]
	s_nop 1
	v_mov_b32_dpp v96, v88 row_ror:1 row_mask:0xf bank_mask:0xf
	v_mov_b32_dpp v100, v88 row_ror:2 row_mask:0xf bank_mask:0xf
	v_mov_b32_dpp v118, v88 row_ror:3 row_mask:0xf bank_mask:0xf
	v_mov_b32_dpp v97, v89 row_ror:1 row_mask:0xf bank_mask:0xf
	v_mov_b32_dpp v101, v89 row_ror:2 row_mask:0xf bank_mask:0xf
	v_mov_b32_dpp v119, v89 row_ror:3 row_mask:0xf bank_mask:0xf
	v_mov_b32_dpp v98, v90 row_ror:1 row_mask:0xf bank_mask:0xf
	v_mov_b32_dpp v102, v90 row_ror:2 row_mask:0xf bank_mask:0xf
	v_mov_b32_dpp v120, v90 row_ror:3 row_mask:0xf bank_mask:0xf
	v_mov_b32_dpp v99, v91 row_ror:1 row_mask:0xf bank_mask:0xf
	v_mov_b32_dpp v103, v91 row_ror:2 row_mask:0xf bank_mask:0xf
	v_mov_b32_dpp v121, v91 row_ror:3 row_mask:0xf bank_mask:0xf
	v_add_u32_e32 v104, 0x80, v186
	v_ashrrev_i32_e32 v105, 31, v104
	s_and_saveexec_b64 s[12:13], s[8:9]
	s_xor_b64 s[34:35], exec, s[12:13]
	s_cbranch_execz .LBB0_150
	s_waitcnt lgkmcnt(14)
	v_cndmask_b32_e64 v202, 0, v124, s[4:5]
	v_cndmask_b32_e64 v203, 0, v127, s[4:5]
	v_cndmask_b32_e64 v200, 0, v123, s[0:1]
	v_cndmask_b32_e64 v201, 0, v126, s[0:1]
	v_cndmask_b32_e64 v222, 0, v196, s[4:5]
	s_waitcnt lgkmcnt(12)
	v_cndmask_b32_e64 v223, 0, v199, s[4:5]
	v_pk_fma_f32 v[202:203], v[140:141], v[202:203], v[144:145]
	v_cndmask_b32_e32 v182, 0, v122, vcc
	v_cndmask_b32_e32 v183, 0, v125, vcc
	v_cndmask_b32_e64 v220, 0, v195, s[0:1]
	v_cndmask_b32_e64 v221, 0, v198, s[0:1]
	v_pk_fma_f32 v[222:223], v[142:143], v[222:223], v[146:147]
	v_pk_fma_f32 v[200:201], v[136:137], v[200:201], v[202:203]
	v_cndmask_b32_e32 v204, 0, v194, vcc
	v_cndmask_b32_e32 v205, 0, v197, vcc
	v_pk_fma_f32 v[220:221], v[138:139], v[220:221], v[222:223]
	v_pk_fma_f32 v[182:183], v[132:133], v[182:183], v[200:201]
	v_pk_fma_f32 v[200:201], v[134:135], v[204:205], v[220:221]
	v_pk_fma_f32 v[92:93], v[92:93], v[128:129], v[182:183]
	s_waitcnt lgkmcnt(0)
	v_pk_fma_f32 v[182:183], v[162:163], v[120:121], v[166:167]
	v_pk_fma_f32 v[94:95], v[94:95], v[130:131], v[200:201]
	v_pk_fma_f32 v[200:201], v[160:161], v[118:119], v[164:165]
	v_pk_fma_f32 v[182:183], v[158:159], v[102:103], v[182:183]
	v_pk_fma_f32 v[200:201], v[156:157], v[100:101], v[200:201]
	v_pk_fma_f32 v[182:183], v[154:155], v[98:99], v[182:183]
	v_pk_fma_f32 v[200:201], v[152:153], v[96:97], v[200:201]
	v_pk_fma_f32 v[182:183], v[90:91], v[150:151], v[182:183]
	v_pk_fma_f32 v[200:201], v[88:89], v[148:149], v[200:201]
	v_cvt_pk_bf16_f32 v92, v92, v93
	v_cvt_pk_bf16_f32 v93, v94, v95
	s_nop 0
	v_cvt_pk_bf16_f32 v94, v200, v201
	v_cvt_pk_bf16_f32 v95, v182, v183
	v_lshlrev_b64 v[182:183], 12, v[104:105]
	v_lshl_add_u64 v[182:183], s[54:55], 0, v[182:183]
	v_lshl_add_u64 v[182:183], v[184:185], 1, v[182:183]
	global_store_dwordx4 v[182:183], v[92:95], off

; __device__ __forceinline__ unsigned cvt_pk_bf16(float lo, float hi) { unsigned r; asm volatile("v_cvt_pk_bf16_f32 %0, %1, %2" : "=v"(r) : "v"(lo), "v"(hi)); return r; }
;     __device__ __forceinline__ void operator()(EPI_ARGS) const {
;     ...
;                     for (int m = 0; m < 4; ++m) {
;                         const int row = ROW_OF(ai, m);
;                         f32x4 o[2];
; #pragma unroll
;                         for (int n = 0; n < 2; ++n) {
;                             const f32x4 gv = acc[ai][bj][m][n];
;                             f32x4 r1, r2, r3, p1, p2, p3;
; #pragma unroll
;                             for (int j = 0; j < 4; ++j) { r1[j] = __shfl(gv[j], s1); r2[j] = __shfl(gv[j], s2); r3[j] = __shfl(gv[j], s3); }
; #pragma unroll
;                             for (int j = 0; j < 4; ++j) { p1[j] = fr >= 1 ? r1[j] : q1[n][j]; p2[j] = fr >= 2 ? r2[j] : q2[n][j]; p3[j] = fr >= 3 ? r3[j] : q3[n][j]; }
;                             q1[n] = r1; q2[n] = r2; q3[n] = r3;
;                             o[n] = bb[n] + w0[n] * p3 + w1[n] * p2 + w2[n] * p1 + w3[n] * gv;
;                             if (m == 0 && fr < 3) *(f32x4*)(headu + ((size_t)blk * 3 + fr) * LW + c0 + 4 * n) = gv;
;                             if (m == 3 && fr >= 13) *(f32x4*)(tailu + ((size_t)blk * 3 + (fr - 13)) * LW + c0 + 4 * n) = gv;
;                         }
;                         if (!(m == 0 && fr < 3)) {
;                             u32x4 w; w.x = cvt_pk_bf16(o[0][0], o[0][1]); w.y = cvt_pk_bf16(o[0][2], o[0][3]); w.z = cvt_pk_bf16(o[1][0], o[1][1]); w.w = cvt_pk_bf16(o[1][2], o[1][3]);
;                             *(u32x4*)(vout + (size_t)row * LW + c0) = w;
;                         }
.LBB0_152:
	s_or_b64 exec, exec, s[12:13]
	s_nop 1
	v_mov_b32_dpp v183, v84 row_ror:3 row_mask:0xf bank_mask:0xf
	v_mov_b32_dpp v201, v85 row_ror:2 row_mask:0xf bank_mask:0xf
	v_mov_b32_dpp v202, v85 row_ror:3 row_mask:0xf bank_mask:0xf
	v_mov_b32_dpp v205, v86 row_ror:3 row_mask:0xf bank_mask:0xf
	v_mov_b32_dpp v221, v87 row_ror:3 row_mask:0xf bank_mask:0xf
	s_mul_hi_i32 s13, s87, 3
	s_mul_i32 s12, s87, 3
	s_nop 1
	v_mov_b32_dpp v182, v84 row_ror:2 row_mask:0xf bank_mask:0xf
	v_mov_b32_dpp v200, v85 row_ror:1 row_mask:0xf bank_mask:0xf
	v_mov_b32_dpp v204, v86 row_ror:2 row_mask:0xf bank_mask:0xf
	v_mov_b32_dpp v220, v87 row_ror:2 row_mask:0xf bank_mask:0xf
	v_lshl_add_u64 v[88:89], s[12:13], 0, v[176:177]
	s_nop 1
	v_mov_b32_dpp v176, v84 row_ror:1 row_mask:0xf bank_mask:0xf
	v_mov_b32_dpp v203, v86 row_ror:1 row_mask:0xf bank_mask:0xf
	v_mov_b32_dpp v219, v87 row_ror:1 row_mask:0xf bank_mask:0xf
	s_waitcnt lgkmcnt(11)
	v_cndmask_b32_e64 v94, v124, v183, s[4:5]
	s_waitcnt lgkmcnt(10)
	v_cndmask_b32_e64 v93, v126, v201, s[0:1]
	s_waitcnt lgkmcnt(9)
	v_cndmask_b32_e64 v95, v127, v202, s[4:5]
	s_waitcnt lgkmcnt(8)
	v_cndmask_b32_e64 v126, v196, v205, s[4:5]
	s_waitcnt lgkmcnt(7)
	v_cndmask_b32_e64 v127, v199, v221, s[4:5]
	s_waitcnt lgkmcnt(6)
	v_cndmask_b32_e64 v92, v123, v182, s[0:1]
	s_waitcnt lgkmcnt(5)
	v_cndmask_b32_e32 v91, v125, v200, vcc
	s_waitcnt lgkmcnt(4)
	v_cndmask_b32_e64 v124, v195, v204, s[0:1]
	s_waitcnt lgkmcnt(3)
	v_cndmask_b32_e64 v125, v198, v220, s[0:1]
	v_pk_fma_f32 v[94:95], v[140:141], v[94:95], v[144:145]
	v_pk_fma_f32 v[126:127], v[142:143], v[126:127], v[146:147]
	s_waitcnt lgkmcnt(2)
	v_cndmask_b32_e32 v90, v122, v176, vcc
	s_waitcnt lgkmcnt(1)
	v_cndmask_b32_e32 v122, v194, v203, vcc
	s_waitcnt lgkmcnt(0)
	v_cndmask_b32_e32 v123, v197, v219, vcc
	v_pk_fma_f32 v[124:125], v[138:139], v[124:125], v[126:127]
	v_pk_fma_f32 v[92:93], v[136:137], v[92:93], v[94:95]
	s_nop 1
	v_mov_b32_dpp v194, v81 row_ror:2 row_mask:0xf bank_mask:0xf
	v_pk_fma_f32 v[90:91], v[132:133], v[90:91], v[92:93]
	v_pk_fma_f32 v[92:93], v[134:135], v[122:123], v[124:125]
	s_nop 1
	v_mov_b32_dpp v123, v80 row_ror:2 row_mask:0xf bank_mask:0xf
	v_mov_b32_dpp v125, v80 row_ror:3 row_mask:0xf bank_mask:0xf
	v_mov_b32_dpp v195, v81 row_ror:3 row_mask:0xf bank_mask:0xf
	v_mov_b32_dpp v198, v82 row_ror:3 row_mask:0xf bank_mask:0xf
	v_mov_b32_dpp v223, v83 row_ror:3 row_mask:0xf bank_mask:0xf
	v_mov_b32_dpp v122, v80 row_ror:1 row_mask:0xf bank_mask:0xf
	v_mov_b32_dpp v127, v81 row_ror:1 row_mask:0xf bank_mask:0xf
	v_mov_b32_dpp v196, v82 row_ror:1 row_mask:0xf bank_mask:0xf
	v_mov_b32_dpp v197, v82 row_ror:2 row_mask:0xf bank_mask:0xf
	v_mov_b32_dpp v199, v83 row_ror:1 row_mask:0xf bank_mask:0xf
	v_mov_b32_dpp v222, v83 row_ror:2 row_mask:0xf bank_mask:0xf
	v_pk_fma_f32 v[86:87], v[86:87], v[130:131], v[92:93]
	s_waitcnt lgkmcnt(10)
	v_cndmask_b32_e64 v92, v100, v123, s[0:1]
	s_waitcnt lgkmcnt(9)
	v_cndmask_b32_e64 v94, v118, v125, s[4:5]
	v_cndmask_b32_e64 v93, v101, v194, s[0:1]
	s_waitcnt lgkmcnt(8)
	v_cndmask_b32_e64 v95, v119, v195, s[4:5]
	s_waitcnt lgkmcnt(7)
	v_cndmask_b32_e64 v100, v120, v198, s[4:5]
	s_waitcnt lgkmcnt(6)
	v_cndmask_b32_e64 v101, v121, v223, s[4:5]
	v_pk_fma_f32 v[84:85], v[84:85], v[128:129], v[90:91]
	s_waitcnt lgkmcnt(5)
	v_cndmask_b32_e32 v90, v96, v122, vcc
	s_waitcnt lgkmcnt(4)
	v_cndmask_b32_e32 v91, v97, v127, vcc
	s_waitcnt lgkmcnt(3)
	v_cndmask_b32_e32 v96, v98, v196, vcc
	s_waitcnt lgkmcnt(2)
	v_cndmask_b32_e64 v98, v102, v197, s[0:1]
	s_waitcnt lgkmcnt(1)
	v_cndmask_b32_e32 v97, v99, v199, vcc
	s_waitcnt lgkmcnt(0)
	v_cndmask_b32_e64 v99, v103, v222, s[0:1]
	v_pk_fma_f32 v[94:95], v[160:161], v[94:95], v[164:165]
	v_pk_fma_f32 v[100:101], v[162:163], v[100:101], v[166:167]
	v_pk_fma_f32 v[92:93], v[156:157], v[92:93], v[94:95]
	v_pk_fma_f32 v[98:99], v[158:159], v[98:99], v[100:101]
	v_pk_fma_f32 v[90:91], v[152:153], v[90:91], v[92:93]
	v_pk_fma_f32 v[92:93], v[154:155], v[96:97], v[98:99]
	v_lshlrev_b64 v[88:89], 13, v[88:89]
	v_pk_fma_f32 v[92:93], v[82:83], v[150:151], v[92:93]
	v_pk_fma_f32 v[82:83], v[80:81], v[148:149], v[90:91]
	v_add_u32_e32 v90, 0x90, v186
	v_ashrrev_i32_e32 v91, 31, v90
	v_cvt_pk_bf16_f32 v80, v84, v85
	v_lshlrev_b64 v[84:85], 12, v[90:91]
	v_lshl_add_u64 v[84:85], s[54:55], 0, v[84:85]
	v_cvt_pk_bf16_f32 v81, v86, v87
	v_cvt_pk_bf16_f32 v82, v82, v83
	v_lshl_add_u64 v[118:119], v[84:85], 0, v[116:117]
	v_cvt_pk_bf16_f32 v83, v92, v93
	global_store_dwordx4 v[118:119], v[80:83], off
	s_nop 1
	v_mov_b32_dpp v82, v76 row_ror:3 row_mask:0xf bank_mask:0xf
	v_mov_b32_dpp v85, v77 row_ror:3 row_mask:0xf bank_mask:0xf
	v_mov_b32_dpp v90, v78 row_ror:3 row_mask:0xf bank_mask:0xf
	v_mov_b32_dpp v93, v79 row_ror:3 row_mask:0xf bank_mask:0xf
	v_mov_b32_dpp v81, v76 row_ror:2 row_mask:0xf bank_mask:0xf
	v_mov_b32_dpp v84, v77 row_ror:2 row_mask:0xf bank_mask:0xf
	v_mov_b32_dpp v87, v78 row_ror:2 row_mask:0xf bank_mask:0xf
	v_mov_b32_dpp v92, v79 row_ror:2 row_mask:0xf bank_mask:0xf
	v_mov_b32_dpp v80, v76 row_ror:1 row_mask:0xf bank_mask:0xf
	v_mov_b32_dpp v83, v77 row_ror:1 row_mask:0xf bank_mask:0xf
	v_mov_b32_dpp v86, v78 row_ror:1 row_mask:0xf bank_mask:0xf
	v_mov_b32_dpp v91, v79 row_ror:1 row_mask:0xf bank_mask:0xf
	s_waitcnt lgkmcnt(11)
	v_cndmask_b32_e64 v98, v183, v82, s[4:5]
	s_waitcnt lgkmcnt(10)
	v_cndmask_b32_e64 v99, v202, v85, s[4:5]
	s_waitcnt lgkmcnt(9)
	v_cndmask_b32_e64 v120, v205, v90, s[4:5]
	s_waitcnt lgkmcnt(8)
	v_cndmask_b32_e64 v121, v221, v93, s[4:5]
	s_waitcnt lgkmcnt(7)
	v_cndmask_b32_e64 v96, v182, v81, s[0:1]
	s_waitcnt lgkmcnt(6)
; __device__ __forceinline__ unsigned cvt_pk_bf16(float lo, float hi) { unsigned r; asm volatile("v_cvt_pk_bf16_f32 %0, %1, %2" : "=v"(r) : "v"(lo), "v"(hi)); return r; }
;     __device__ __forceinline__ void operator()(EPI_ARGS) const {
;     ...
;                     for (int m = 0; m < 4; ++m) {
;                         const int row = ROW_OF(ai, m);
;                         f32x4 o[2];
; #pragma unroll
;                         for (int n = 0; n < 2; ++n) {
;                             const f32x4 gv = acc[ai][bj][m][n];
;                             f32x4 r1, r2, r3, p1, p2, p3;
; #pragma unroll
;                             for (int j = 0; j < 4; ++j) { r1[j] = __shfl(gv[j], s1); r2[j] = __shfl(gv[j], s2); r3[j] = __shfl(gv[j], s3); }
; #pragma unroll
;                             for (int j = 0; j < 4; ++j) { p1[j] = fr >= 1 ? r1[j] : q1[n][j]; p2[j] = fr >= 2 ? r2[j] : q2[n][j]; p3[j] = fr >= 3 ? r3[j] : q3[n][j]; }
;                             q1[n] = r1; q2[n] = r2; q3[n] = r3;
;                             o[n] = bb[n] + w0[n] * p3 + w1[n] * p2 + w2[n] * p1 + w3[n] * gv;
;                             if (m == 0 && fr < 3) *(f32x4*)(headu + ((size_t)blk * 3 + fr) * LW + c0 + 4 * n) = gv;
;                             if (m == 3 && fr >= 13) *(f32x4*)(tailu + ((size_t)blk * 3 + (fr - 13)) * LW + c0 + 4 * n) = gv;
;                         }
;                         if (!(m == 0 && fr < 3)) {
;                             u32x4 w; w.x = cvt_pk_bf16(o[0][0], o[0][1]); w.y = cvt_pk_bf16(o[0][2], o[0][3]); w.z = cvt_pk_bf16(o[1][0], o[1][1]); w.w = cvt_pk_bf16(o[1][2], o[1][3]);
;                             *(u32x4*)(vout + (size_t)row * LW + c0) = w;
;                         }
	v_cndmask_b32_e64 v97, v201, v84, s[0:1]
	s_waitcnt lgkmcnt(5)
	v_cndmask_b32_e64 v102, v204, v87, s[0:1]
	s_waitcnt lgkmcnt(4)
	v_cndmask_b32_e64 v103, v220, v92, s[0:1]
	v_pk_fma_f32 v[98:99], v[140:141], v[98:99], v[144:145]
	v_pk_fma_f32 v[120:121], v[142:143], v[120:121], v[146:147]
	s_waitcnt lgkmcnt(3)
	v_cndmask_b32_e32 v94, v176, v80, vcc
	s_waitcnt lgkmcnt(2)
	v_cndmask_b32_e32 v95, v200, v83, vcc
	s_waitcnt lgkmcnt(1)
	v_cndmask_b32_e32 v100, v203, v86, vcc
	s_waitcnt lgkmcnt(0)
	v_cndmask_b32_e32 v101, v219, v91, vcc
	v_pk_fma_f32 v[102:103], v[138:139], v[102:103], v[120:121]
	v_pk_fma_f32 v[96:97], v[136:137], v[96:97], v[98:99]
	s_nop 1
	v_mov_b32_dpp v98, v74 row_ror:3 row_mask:0xf bank_mask:0xf
	v_pk_fma_f32 v[94:95], v[132:133], v[94:95], v[96:97]
	v_pk_fma_f32 v[96:97], v[134:135], v[100:101], v[102:103]
	v_pk_fma_f32 v[120:121], v[76:77], v[128:129], v[94:95]
	v_pk_fma_f32 v[102:103], v[78:79], v[130:131], v[96:97]
	s_nop 1
	v_mov_b32_dpp v77, v72 row_ror:2 row_mask:0xf bank_mask:0xf
	v_mov_b32_dpp v78, v72 row_ror:3 row_mask:0xf bank_mask:0xf
	v_mov_b32_dpp v79, v73 row_ror:1 row_mask:0xf bank_mask:0xf
	v_mov_b32_dpp v95, v73 row_ror:3 row_mask:0xf bank_mask:0xf
	v_mov_b32_dpp v94, v73 row_ror:2 row_mask:0xf bank_mask:0xf
	v_mov_b32_dpp v76, v72 row_ror:1 row_mask:0xf bank_mask:0xf
	v_mov_b32_dpp v96, v74 row_ror:1 row_mask:0xf bank_mask:0xf
	v_mov_b32_dpp v97, v74 row_ror:2 row_mask:0xf bank_mask:0xf
	v_mov_b32_dpp v101, v75 row_ror:3 row_mask:0xf bank_mask:0xf
	v_mov_b32_dpp v100, v75 row_ror:2 row_mask:0xf bank_mask:0xf
	v_mov_b32_dpp v99, v75 row_ror:1 row_mask:0xf bank_mask:0xf
	s_waitcnt lgkmcnt(10)
	v_cndmask_b32_e64 v124, v123, v77, s[0:1]
	s_waitcnt lgkmcnt(9)
	v_cndmask_b32_e64 v126, v125, v78, s[4:5]
	s_waitcnt lgkmcnt(8)
	v_cndmask_b32_e32 v123, v127, v79, vcc
	s_waitcnt lgkmcnt(7)
	v_cndmask_b32_e64 v127, v195, v95, s[4:5]
	s_waitcnt lgkmcnt(6)
	v_cndmask_b32_e64 v125, v194, v94, s[0:1]
	v_pk_fma_f32 v[126:127], v[160:161], v[126:127], v[164:165]
	s_waitcnt lgkmcnt(5)
	v_cndmask_b32_e32 v122, v122, v76, vcc
	s_waitcnt lgkmcnt(4)
	v_cndmask_b32_e32 v182, v196, v96, vcc
	s_waitcnt lgkmcnt(3)
	v_cndmask_b32_e64 v194, v197, v97, s[0:1]
	v_cndmask_b32_e64 v196, v198, v98, s[4:5]
	s_waitcnt lgkmcnt(2)
	v_cndmask_b32_e64 v197, v223, v101, s[4:5]
	v_pk_fma_f32 v[124:125], v[156:157], v[124:125], v[126:127]
	s_waitcnt lgkmcnt(1)
	v_cndmask_b32_e64 v195, v222, v100, s[0:1]
	v_pk_fma_f32 v[196:197], v[162:163], v[196:197], v[166:167]
	v_pk_fma_f32 v[122:123], v[152:153], v[122:123], v[124:125]
	s_waitcnt lgkmcnt(0)
	v_cndmask_b32_e32 v183, v199, v99, vcc
	v_pk_fma_f32 v[194:195], v[158:159], v[194:195], v[196:197]
	v_pk_fma_f32 v[72:73], v[72:73], v[148:149], v[122:123]
	v_add_u32_e32 v122, 0xa0, v186
	v_pk_fma_f32 v[124:125], v[154:155], v[182:183], v[194:195]
	v_ashrrev_i32_e32 v123, 31, v122
	v_pk_fma_f32 v[74:75], v[74:75], v[150:151], v[124:125]
	v_cvt_pk_bf16_f32 v194, v120, v121
	v_cvt_pk_bf16_f32 v195, v102, v103
	v_cvt_pk_bf16_f32 v196, v72, v73
	v_lshlrev_b64 v[72:73], 12, v[122:123]
	v_cvt_pk_bf16_f32 v197, v74, v75
	v_lshl_add_u64 v[120:121], s[54:55], 0, v[72:73]
	s_nop 1
	v_mov_b32_dpp v72, v64 row_ror:1 row_mask:0xf bank_mask:0xf
	v_mov_b32_dpp v73, v64 row_ror:2 row_mask:0xf bank_mask:0xf
	v_mov_b32_dpp v74, v64 row_ror:3 row_mask:0xf bank_mask:0xf
	v_mov_b32_dpp v75, v65 row_ror:1 row_mask:0xf bank_mask:0xf
	v_mov_b32_dpp v102, v65 row_ror:2 row_mask:0xf bank_mask:0xf
	v_mov_b32_dpp v103, v65 row_ror:3 row_mask:0xf bank_mask:0xf
	v_mov_b32_dpp v122, v66 row_ror:1 row_mask:0xf bank_mask:0xf
	v_mov_b32_dpp v123, v66 row_ror:2 row_mask:0xf bank_mask:0xf
	v_mov_b32_dpp v124, v66 row_ror:3 row_mask:0xf bank_mask:0xf
	v_mov_b32_dpp v125, v67 row_ror:1 row_mask:0xf bank_mask:0xf
	v_mov_b32_dpp v126, v67 row_ror:2 row_mask:0xf bank_mask:0xf
	v_mov_b32_dpp v127, v67 row_ror:3 row_mask:0xf bank_mask:0xf
	v_lshl_add_u64 v[88:89], s[74:75], 0, v[88:89]
	v_lshl_add_u64 v[120:121], v[120:121], 0, v[116:117]
	v_lshl_add_u64 v[116:117], v[184:185], 2, v[88:89]
	global_store_dwordx4 v[120:121], v[194:197], off
	s_and_saveexec_b64 s[12:13], s[6:7]
	s_cbranch_execz .LBB0_154
	global_store_dwordx4 v[116:117], v[64:67], off
.LBB0_154:
	s_or_b64 exec, exec, s[12:13]
	s_nop 1
	v_mov_b32_dpp v88, v68 row_ror:1 row_mask:0xf bank_mask:0xf
	v_mov_b32_dpp v89, v68 row_ror:2 row_mask:0xf bank_mask:0xf
	v_mov_b32_dpp v176, v68 row_ror:3 row_mask:0xf bank_mask:0xf
	v_mov_b32_dpp v182, v69 row_ror:1 row_mask:0xf bank_mask:0xf
	v_mov_b32_dpp v183, v69 row_ror:2 row_mask:0xf bank_mask:0xf
	v_mov_b32_dpp v194, v69 row_ror:3 row_mask:0xf bank_mask:0xf
	v_mov_b32_dpp v195, v70 row_ror:1 row_mask:0xf bank_mask:0xf
	v_mov_b32_dpp v196, v70 row_ror:2 row_mask:0xf bank_mask:0xf
	v_mov_b32_dpp v197, v70 row_ror:3 row_mask:0xf bank_mask:0xf
	v_mov_b32_dpp v198, v71 row_ror:1 row_mask:0xf bank_mask:0xf
	v_mov_b32_dpp v199, v71 row_ror:2 row_mask:0xf bank_mask:0xf
	v_mov_b32_dpp v200, v71 row_ror:3 row_mask:0xf bank_mask:0xf
	s_and_saveexec_b64 s[12:13], s[6:7]
	s_cbranch_execz .LBB0_156
	global_store_dwordx4 v[116:117], v[68:71], off offset:16
; __device__ __forceinline__ unsigned cvt_pk_bf16(float lo, float hi) { unsigned r; asm volatile("v_cvt_pk_bf16_f32 %0, %1, %2" : "=v"(r) : "v"(lo), "v"(hi)); return r; }
;     __device__ __forceinline__ void operator()(EPI_ARGS) const {
;     ...
;                     for (int m = 0; m < 4; ++m) {
;                         const int row = ROW_OF(ai, m);
;                         f32x4 o[2];
; #pragma unroll
;                         for (int n = 0; n < 2; ++n) {
;                             const f32x4 gv = acc[ai][bj][m][n];
;                             f32x4 r1, r2, r3, p1, p2, p3;
; #pragma unroll
;                             for (int j = 0; j < 4; ++j) { r1[j] = __shfl(gv[j], s1); r2[j] = __shfl(gv[j], s2); r3[j] = __shfl(gv[j], s3); }
; #pragma unroll
;                             for (int j = 0; j < 4; ++j) { p1[j] = fr >= 1 ? r1[j] : q1[n][j]; p2[j] = fr >= 2 ? r2[j] : q2[n][j]; p3[j] = fr >= 3 ? r3[j] : q3[n][j]; }
;                             q1[n] = r1; q2[n] = r2; q3[n] = r3;
;                             o[n] = bb[n] + w0[n] * p3 + w1[n] * p2 + w2[n] * p1 + w3[n] * gv;
;                             if (m == 0 && fr < 3) *(f32x4*)(headu + ((size_t)blk * 3 + fr) * LW + c0 + 4 * n) = gv;
;                             if (m == 3 && fr >= 13) *(f32x4*)(tailu + ((size_t)blk * 3 + (fr - 13)) * LW + c0 + 4 * n) = gv;
;                         }
;                         if (!(m == 0 && fr < 3)) {
;                             u32x4 w; w.x = cvt_pk_bf16(o[0][0], o[0][1]); w.y = cvt_pk_bf16(o[0][2], o[0][3]); w.z = cvt_pk_bf16(o[1][0], o[1][1]); w.w = cvt_pk_bf16(o[1][2], o[1][3]);
;                             *(u32x4*)(vout + (size_t)row * LW + c0) = w;
;                         }
.LBB0_156:
	s_or_b64 exec, exec, s[12:13]
	s_waitcnt lgkmcnt(11)
	v_cndmask_b32_e32 v76, v76, v88, vcc
	s_waitcnt lgkmcnt(10)
	v_cndmask_b32_e64 v88, v77, v89, s[0:1]
	s_waitcnt lgkmcnt(9)
	v_cndmask_b32_e64 v78, v78, v176, s[4:5]
	s_waitcnt lgkmcnt(8)
	v_cndmask_b32_e32 v77, v79, v182, vcc
	s_waitcnt lgkmcnt(6)
	v_cndmask_b32_e64 v79, v95, v194, s[4:5]
	v_cndmask_b32_e64 v89, v94, v183, s[0:1]
	v_pk_fma_f32 v[78:79], v[160:161], v[78:79], v[164:165]
	s_waitcnt lgkmcnt(3)
	v_cndmask_b32_e64 v98, v98, v197, s[4:5]
	v_pk_fma_f32 v[78:79], v[156:157], v[88:89], v[78:79]
	s_waitcnt lgkmcnt(2)
	v_cndmask_b32_e32 v95, v99, v198, vcc
	s_waitcnt lgkmcnt(0)
	v_cndmask_b32_e64 v99, v101, v200, s[4:5]
	v_pk_fma_f32 v[76:77], v[152:153], v[76:77], v[78:79]
	v_cndmask_b32_e32 v94, v96, v195, vcc
	v_cndmask_b32_e64 v96, v97, v196, s[0:1]
	v_cndmask_b32_e64 v97, v100, v199, s[0:1]
	v_pk_fma_f32 v[98:99], v[162:163], v[98:99], v[166:167]
	v_pk_fma_f32 v[68:69], v[68:69], v[148:149], v[76:77]
	v_cndmask_b32_e64 v76, v81, v73, s[0:1]
	v_cndmask_b32_e64 v74, v82, v74, s[4:5]
	v_cndmask_b32_e32 v73, v83, v75, vcc
	v_cndmask_b32_e64 v75, v85, v103, s[4:5]
	v_pk_fma_f32 v[96:97], v[158:159], v[96:97], v[98:99]
	v_cndmask_b32_e64 v77, v84, v102, s[0:1]
	v_cndmask_b32_e64 v82, v90, v124, s[4:5]
	v_cndmask_b32_e64 v83, v93, v127, s[4:5]
	v_pk_fma_f32 v[74:75], v[140:141], v[74:75], v[144:145]
	v_pk_fma_f32 v[78:79], v[154:155], v[94:95], v[96:97]
	v_cndmask_b32_e32 v72, v80, v72, vcc
	v_cndmask_b32_e64 v80, v87, v123, s[0:1]
	v_cndmask_b32_e64 v81, v92, v126, s[0:1]
	v_pk_fma_f32 v[82:83], v[142:143], v[82:83], v[146:147]
	v_pk_fma_f32 v[74:75], v[136:137], v[76:77], v[74:75]
	v_pk_fma_f32 v[70:71], v[70:71], v[150:151], v[78:79]
	v_cndmask_b32_e32 v78, v86, v122, vcc
	v_cndmask_b32_e32 v79, v91, v125, vcc
	v_pk_fma_f32 v[80:81], v[138:139], v[80:81], v[82:83]
	v_pk_fma_f32 v[72:73], v[132:133], v[72:73], v[74:75]
	v_pk_fma_f32 v[74:75], v[134:135], v[78:79], v[80:81]
	v_pk_fma_f32 v[64:65], v[64:65], v[128:129], v[72:73]
	v_add_u32_e32 v72, 0xb0, v186
	v_pk_fma_f32 v[66:67], v[66:67], v[130:131], v[74:75]
	v_ashrrev_i32_e32 v73, 31, v72
	v_cvt_pk_bf16_f32 v64, v64, v65
	v_cvt_pk_bf16_f32 v65, v66, v67
	v_cvt_pk_bf16_f32 v66, v68, v69
	v_lshlrev_b64 v[68:69], 12, v[72:73]
	v_lshl_add_u64 v[68:69], s[54:55], 0, v[68:69]
	v_lshl_add_u64 v[122:123], v[184:185], 1, v[68:69]
	v_cvt_pk_bf16_f32 v67, v70, v71
	global_store_dwordx4 v[122:123], v[64:67], off
	s_nop 1
	v_mov_b32_dpp v136, v60 row_ror:1 row_mask:0xf bank_mask:0xf
	v_mov_b32_dpp v137, v60 row_ror:2 row_mask:0xf bank_mask:0xf
	v_add_u32_e32 v64, 0x80, v184
	v_ashrrev_i32_e32 v65, 31, v64
	v_lshlrev_b64 v[64:65], 2, v[64:65]
	v_lshl_add_u64 v[66:67], s[56:57], 0, v[64:65]
	v_lshl_add_u64 v[68:69], s[60:61], 0, v[64:65]
	v_lshl_add_u64 v[64:65], s[16:17], 0, v[64:65]
	global_load_dwordx4 v[96:99], v[192:193], off offset:528
	global_load_dwordx4 v[76:79], v[192:193], off offset:512
	global_load_dwordx4 v[92:95], v[66:67], off offset:16
	global_load_dwordx4 v[72:75], v[66:67], off
	global_load_dwordx4 v[88:91], v[68:69], off offset:16
	s_nop 0
	global_load_dwordx4 v[68:71], v[68:69], off
	s_nop 0
	global_load_dwordx4 v[84:87], v[64:65], off offset:16
	s_nop 0
	global_load_dwordx4 v[64:67], v[64:65], off
	s_nop 0
	global_load_dwordx4 v[100:103], v[190:191], off offset:528
	global_load_dwordx4 v[80:83], v[190:191], off offset:512
	s_nop 1
	v_mov_b32_dpp v138, v60 row_ror:3 row_mask:0xf bank_mask:0xf
	v_mov_b32_dpp v139, v61 row_ror:1 row_mask:0xf bank_mask:0xf
	v_mov_b32_dpp v140, v61 row_ror:2 row_mask:0xf bank_mask:0xf
	v_mov_b32_dpp v141, v61 row_ror:3 row_mask:0xf bank_mask:0xf
	v_mov_b32_dpp v142, v62 row_ror:1 row_mask:0xf bank_mask:0xf
	v_mov_b32_dpp v143, v62 row_ror:2 row_mask:0xf bank_mask:0xf
	v_mov_b32_dpp v144, v62 row_ror:3 row_mask:0xf bank_mask:0xf
	v_mov_b32_dpp v145, v63 row_ror:1 row_mask:0xf bank_mask:0xf
	v_mov_b32_dpp v146, v63 row_ror:2 row_mask:0xf bank_mask:0xf
	v_mov_b32_dpp v147, v63 row_ror:3 row_mask:0xf bank_mask:0xf
	s_and_saveexec_b64 s[12:13], s[10:11]
	s_cbranch_execz .LBB0_158
	global_store_dwordx4 v[188:189], v[60:63], off offset:512
.LBB0_158:
	s_or_b64 exec, exec, s[12:13]
	s_nop 1
	v_mov_b32_dpp v124, v56 row_ror:1 row_mask:0xf bank_mask:0xf
	v_mov_b32_dpp v128, v56 row_ror:2 row_mask:0xf bank_mask:0xf
	v_mov_b32_dpp v132, v56 row_ror:3 row_mask:0xf bank_mask:0xf
	v_mov_b32_dpp v125, v57 row_ror:1 row_mask:0xf bank_mask:0xf
	v_mov_b32_dpp v129, v57 row_ror:2 row_mask:0xf bank_mask:0xf
	v_mov_b32_dpp v133, v57 row_ror:3 row_mask:0xf bank_mask:0xf
	v_mov_b32_dpp v126, v58 row_ror:1 row_mask:0xf bank_mask:0xf
	v_mov_b32_dpp v130, v58 row_ror:2 row_mask:0xf bank_mask:0xf
	v_mov_b32_dpp v134, v58 row_ror:3 row_mask:0xf bank_mask:0xf
	v_mov_b32_dpp v127, v59 row_ror:1 row_mask:0xf bank_mask:0xf
	v_mov_b32_dpp v131, v59 row_ror:2 row_mask:0xf bank_mask:0xf
	v_mov_b32_dpp v135, v59 row_ror:3 row_mask:0xf bank_mask:0xf
	s_and_saveexec_b64 s[12:13], s[8:9]
	s_xor_b64 s[34:35], exec, s[12:13]
	s_cbranch_execz .LBB0_160
	s_waitcnt lgkmcnt(14)
	v_cndmask_b32_e64 v152, 0, v138, s[4:5]
	v_cndmask_b32_e64 v153, 0, v141, s[4:5]
	v_cndmask_b32_e64 v150, 0, v137, s[0:1]
	v_cndmask_b32_e64 v151, 0, v140, s[0:1]
	v_cndmask_b32_e64 v158, 0, v144, s[4:5]
	s_waitcnt lgkmcnt(12)
	v_cndmask_b32_e64 v159, 0, v147, s[4:5]
	s_waitcnt vmcnt(0)
	v_pk_fma_f32 v[152:153], v[76:77], v[152:153], v[80:81]
	v_cndmask_b32_e32 v148, 0, v136, vcc
	v_cndmask_b32_e32 v149, 0, v139, vcc
	v_cndmask_b32_e64 v156, 0, v143, s[0:1]
	v_cndmask_b32_e64 v157, 0, v146, s[0:1]
	v_pk_fma_f32 v[158:159], v[78:79], v[158:159], v[82:83]
	v_pk_fma_f32 v[150:151], v[72:73], v[150:151], v[152:153]
	v_cndmask_b32_e32 v154, 0, v142, vcc
	v_cndmask_b32_e32 v155, 0, v145, vcc
	v_pk_fma_f32 v[156:157], v[74:75], v[156:157], v[158:159]
	v_pk_fma_f32 v[148:149], v[68:69], v[148:149], v[150:151]
	v_pk_fma_f32 v[150:151], v[70:71], v[154:155], v[156:157]
	v_pk_fma_f32 v[60:61], v[60:61], v[64:65], v[148:149]
	s_waitcnt lgkmcnt(0)
	v_pk_fma_f32 v[148:149], v[98:99], v[134:135], v[102:103]
	v_pk_fma_f32 v[62:63], v[62:63], v[66:67], v[150:151]
	v_pk_fma_f32 v[150:151], v[96:97], v[132:133], v[100:101]
	v_pk_fma_f32 v[148:149], v[94:95], v[130:131], v[148:149]
	v_pk_fma_f32 v[150:151], v[92:93], v[128:129], v[150:151]
	v_pk_fma_f32 v[148:149], v[90:91], v[126:127], v[148:149]
	v_pk_fma_f32 v[150:151], v[88:89], v[124:125], v[150:151]
	v_pk_fma_f32 v[148:149], v[58:59], v[86:87], v[148:149]
	v_pk_fma_f32 v[150:151], v[56:57], v[84:85], v[150:151]
	v_cvt_pk_bf16_f32 v60, v60, v61
	v_cvt_pk_bf16_f32 v61, v62, v63
	s_nop 0
	v_cvt_pk_bf16_f32 v62, v150, v151
	v_cvt_pk_bf16_f32 v63, v148, v149
	v_lshlrev_b64 v[148:149], 12, v[186:187]
	v_lshl_add_u64 v[148:149], s[54:55], 0, v[148:149]
	v_lshl_add_u64 v[148:149], v[184:185], 1, v[148:149]
	global_store_dwordx4 v[148:149], v[60:63], off offset:256

; __device__ __forceinline__ unsigned cvt_pk_bf16(float lo, float hi) { unsigned r; asm volatile("v_cvt_pk_bf16_f32 %0, %1, %2" : "=v"(r) : "v"(lo), "v"(hi)); return r; }
;     __device__ __forceinline__ void operator()(EPI_ARGS) const {
;     ...
;                     for (int m = 0; m < 4; ++m) {
;                         const int row = ROW_OF(ai, m);
;                         f32x4 o[2];
; #pragma unroll
;                         for (int n = 0; n < 2; ++n) {
;                             const f32x4 gv = acc[ai][bj][m][n];
;                             f32x4 r1, r2, r3, p1, p2, p3;
; #pragma unroll
;                             for (int j = 0; j < 4; ++j) { r1[j] = __shfl(gv[j], s1); r2[j] = __shfl(gv[j], s2); r3[j] = __shfl(gv[j], s3); }
; #pragma unroll
;                             for (int j = 0; j < 4; ++j) { p1[j] = fr >= 1 ? r1[j] : q1[n][j]; p2[j] = fr >= 2 ? r2[j] : q2[n][j]; p3[j] = fr >= 3 ? r3[j] : q3[n][j]; }
;                             q1[n] = r1; q2[n] = r2; q3[n] = r3;
;                             o[n] = bb[n] + w0[n] * p3 + w1[n] * p2 + w2[n] * p1 + w3[n] * gv;
;                             if (m == 0 && fr < 3) *(f32x4*)(headu + ((size_t)blk * 3 + fr) * LW + c0 + 4 * n) = gv;
;                             if (m == 3 && fr >= 13) *(f32x4*)(tailu + ((size_t)blk * 3 + (fr - 13)) * LW + c0 + 4 * n) = gv;
;                         }
;                         if (!(m == 0 && fr < 3)) {
;                             u32x4 w; w.x = cvt_pk_bf16(o[0][0], o[0][1]); w.y = cvt_pk_bf16(o[0][2], o[0][3]); w.z = cvt_pk_bf16(o[1][0], o[1][1]); w.w = cvt_pk_bf16(o[1][2], o[1][3]);
;                             *(u32x4*)(vout + (size_t)row * LW + c0) = w;
;                         }
.LBB0_162:
	s_or_b64 exec, exec, s[12:13]
	s_nop 1
	v_mov_b32_dpp v150, v52 row_ror:3 row_mask:0xf bank_mask:0xf
	v_mov_b32_dpp v151, v53 row_ror:1 row_mask:0xf bank_mask:0xf
	v_mov_b32_dpp v156, v54 row_ror:3 row_mask:0xf bank_mask:0xf
	v_mov_b32_dpp v159, v55 row_ror:3 row_mask:0xf bank_mask:0xf
	v_mov_b32_dpp v148, v52 row_ror:1 row_mask:0xf bank_mask:0xf
	v_mov_b32_dpp v149, v52 row_ror:2 row_mask:0xf bank_mask:0xf
	v_mov_b32_dpp v152, v53 row_ror:2 row_mask:0xf bank_mask:0xf
	v_mov_b32_dpp v155, v54 row_ror:2 row_mask:0xf bank_mask:0xf
	v_mov_b32_dpp v158, v55 row_ror:2 row_mask:0xf bank_mask:0xf
	v_mov_b32_dpp v153, v53 row_ror:3 row_mask:0xf bank_mask:0xf
	v_mov_b32_dpp v154, v54 row_ror:1 row_mask:0xf bank_mask:0xf
	v_mov_b32_dpp v157, v55 row_ror:1 row_mask:0xf bank_mask:0xf
	s_waitcnt lgkmcnt(11)
	v_cndmask_b32_e64 v60, v138, v150, s[4:5]
	s_waitcnt lgkmcnt(10)
	v_cndmask_b32_e32 v57, v139, v151, vcc
	s_waitcnt lgkmcnt(9)
	v_cndmask_b32_e64 v138, v144, v156, s[4:5]
	s_waitcnt lgkmcnt(8)
	v_cndmask_b32_e64 v139, v147, v159, s[4:5]
	s_waitcnt lgkmcnt(7)
	v_cndmask_b32_e32 v56, v136, v148, vcc
	s_waitcnt lgkmcnt(6)
	v_cndmask_b32_e64 v58, v137, v149, s[0:1]
	s_waitcnt lgkmcnt(5)
	v_cndmask_b32_e64 v59, v140, v152, s[0:1]
	s_waitcnt lgkmcnt(4)
	v_cndmask_b32_e64 v136, v143, v155, s[0:1]
	s_waitcnt lgkmcnt(3)
	v_cndmask_b32_e64 v137, v146, v158, s[0:1]
	s_waitcnt vmcnt(0)
	v_pk_fma_f32 v[138:139], v[78:79], v[138:139], v[82:83]
	s_nop 1
	v_mov_b32_dpp v140, v48 row_ror:3 row_mask:0xf bank_mask:0xf
	v_mov_b32_dpp v143, v49 row_ror:3 row_mask:0xf bank_mask:0xf
	v_mov_b32_dpp v144, v50 row_ror:1 row_mask:0xf bank_mask:0xf
	v_mov_b32_dpp v146, v50 row_ror:3 row_mask:0xf bank_mask:0xf
	v_mov_b32_dpp v147, v51 row_ror:1 row_mask:0xf bank_mask:0xf
	v_mov_b32_dpp v161, v51 row_ror:3 row_mask:0xf bank_mask:0xf
	s_waitcnt lgkmcnt(8)
	v_cndmask_b32_e64 v61, v141, v153, s[4:5]
	s_waitcnt lgkmcnt(7)
	v_cndmask_b32_e32 v62, v142, v154, vcc
	s_waitcnt lgkmcnt(6)
	v_cndmask_b32_e32 v63, v145, v157, vcc
	v_pk_fma_f32 v[136:137], v[74:75], v[136:137], v[138:139]
	s_nop 1
	v_mov_b32_dpp v138, v48 row_ror:1 row_mask:0xf bank_mask:0xf
	v_mov_b32_dpp v139, v48 row_ror:2 row_mask:0xf bank_mask:0xf
	v_mov_b32_dpp v141, v49 row_ror:1 row_mask:0xf bank_mask:0xf
	v_mov_b32_dpp v142, v49 row_ror:2 row_mask:0xf bank_mask:0xf
	v_mov_b32_dpp v145, v50 row_ror:2 row_mask:0xf bank_mask:0xf
	v_mov_b32_dpp v160, v51 row_ror:2 row_mask:0xf bank_mask:0xf
	v_pk_fma_f32 v[60:61], v[76:77], v[60:61], v[80:81]
	s_nop 0
	v_pk_fma_f32 v[58:59], v[72:73], v[58:59], v[60:61]
	s_waitcnt lgkmcnt(11)
	v_cndmask_b32_e64 v60, v132, v140, s[4:5]
	v_pk_fma_f32 v[56:57], v[68:69], v[56:57], v[58:59]
	v_pk_fma_f32 v[58:59], v[70:71], v[62:63], v[136:137]
	s_waitcnt lgkmcnt(10)
	v_cndmask_b32_e64 v61, v133, v143, s[4:5]
	s_waitcnt lgkmcnt(9)
	v_cndmask_b32_e32 v62, v126, v144, vcc
	s_waitcnt lgkmcnt(8)
	v_cndmask_b32_e64 v126, v134, v146, s[4:5]
	s_waitcnt lgkmcnt(7)
	v_cndmask_b32_e32 v63, v127, v147, vcc
	s_waitcnt lgkmcnt(6)
	v_cndmask_b32_e64 v127, v135, v161, s[4:5]
	v_pk_fma_f32 v[54:55], v[54:55], v[66:67], v[58:59]
	v_pk_fma_f32 v[52:53], v[52:53], v[64:65], v[56:57]
	s_waitcnt lgkmcnt(5)
	v_cndmask_b32_e32 v56, v124, v138, vcc
	s_waitcnt lgkmcnt(4)
	v_cndmask_b32_e64 v58, v128, v139, s[0:1]
	s_waitcnt lgkmcnt(3)
	v_cndmask_b32_e32 v57, v125, v141, vcc
	s_waitcnt lgkmcnt(2)
	v_cndmask_b32_e64 v59, v129, v142, s[0:1]
	s_waitcnt lgkmcnt(1)
	v_cndmask_b32_e64 v124, v130, v145, s[0:1]
	s_waitcnt lgkmcnt(0)
	v_cndmask_b32_e64 v125, v131, v160, s[0:1]
	v_pk_fma_f32 v[60:61], v[96:97], v[60:61], v[100:101]
	v_pk_fma_f32 v[126:127], v[98:99], v[126:127], v[102:103]
	v_pk_fma_f32 v[58:59], v[92:93], v[58:59], v[60:61]
	v_pk_fma_f32 v[124:125], v[94:95], v[124:125], v[126:127]
	v_pk_fma_f32 v[56:57], v[88:89], v[56:57], v[58:59]
	v_pk_fma_f32 v[58:59], v[90:91], v[62:63], v[124:125]
	s_nop 0
	v_pk_fma_f32 v[58:59], v[50:51], v[86:87], v[58:59]
	v_pk_fma_f32 v[50:51], v[48:49], v[84:85], v[56:57]
	v_cvt_pk_bf16_f32 v48, v52, v53
	v_cvt_pk_bf16_f32 v49, v54, v55
	s_nop 1
	v_mov_b32_dpp v53, v45 row_ror:3 row_mask:0xf bank_mask:0xf
	v_cvt_pk_bf16_f32 v50, v50, v51
	v_cvt_pk_bf16_f32 v51, v58, v59
	global_store_dwordx4 v[112:113], v[48:51], off offset:256
	s_nop 1
	v_mov_b32_dpp v50, v44 row_ror:3 row_mask:0xf bank_mask:0xf
	v_mov_b32_dpp v56, v46 row_ror:3 row_mask:0xf bank_mask:0xf
	v_mov_b32_dpp v59, v47 row_ror:3 row_mask:0xf bank_mask:0xf
	v_mov_b32_dpp v49, v44 row_ror:2 row_mask:0xf bank_mask:0xf
	v_mov_b32_dpp v52, v45 row_ror:2 row_mask:0xf bank_mask:0xf
	v_mov_b32_dpp v55, v46 row_ror:2 row_mask:0xf bank_mask:0xf
	v_mov_b32_dpp v58, v47 row_ror:2 row_mask:0xf bank_mask:0xf
	v_mov_b32_dpp v48, v44 row_ror:1 row_mask:0xf bank_mask:0xf
	v_mov_b32_dpp v51, v45 row_ror:1 row_mask:0xf bank_mask:0xf
	v_mov_b32_dpp v54, v46 row_ror:1 row_mask:0xf bank_mask:0xf
	v_mov_b32_dpp v57, v47 row_ror:1 row_mask:0xf bank_mask:0xf
	s_waitcnt lgkmcnt(10)
	v_cndmask_b32_e64 v112, v150, v50, s[4:5]
	v_cndmask_b32_e64 v113, v153, v53, s[4:5]
	s_waitcnt lgkmcnt(9)
	v_cndmask_b32_e64 v128, v156, v56, s[4:5]
	s_waitcnt lgkmcnt(8)
	v_cndmask_b32_e64 v129, v159, v59, s[4:5]
	s_waitcnt lgkmcnt(7)
	v_cndmask_b32_e64 v62, v149, v49, s[0:1]
	s_waitcnt lgkmcnt(6)
	v_cndmask_b32_e64 v63, v152, v52, s[0:1]
	s_waitcnt lgkmcnt(5)
	v_cndmask_b32_e64 v126, v155, v55, s[0:1]
	s_waitcnt lgkmcnt(4)
	v_cndmask_b32_e64 v127, v158, v58, s[0:1]
	v_pk_fma_f32 v[112:113], v[76:77], v[112:113], v[80:81]
	v_pk_fma_f32 v[128:129], v[78:79], v[128:129], v[82:83]
	s_waitcnt lgkmcnt(3)
	v_cndmask_b32_e32 v60, v148, v48, vcc
	s_waitcnt lgkmcnt(2)
; __device__ __forceinline__ unsigned cvt_pk_bf16(float lo, float hi) { unsigned r; asm volatile("v_cvt_pk_bf16_f32 %0, %1, %2" : "=v"(r) : "v"(lo), "v"(hi)); return r; }
;     __device__ __forceinline__ void operator()(EPI_ARGS) const {
;     ...
;                     for (int m = 0; m < 4; ++m) {
;                         const int row = ROW_OF(ai, m);
;                         f32x4 o[2];
; #pragma unroll
;                         for (int n = 0; n < 2; ++n) {
;                             const f32x4 gv = acc[ai][bj][m][n];
;                             f32x4 r1, r2, r3, p1, p2, p3;
; #pragma unroll
;                             for (int j = 0; j < 4; ++j) { r1[j] = __shfl(gv[j], s1); r2[j] = __shfl(gv[j], s2); r3[j] = __shfl(gv[j], s3); }
; #pragma unroll
;                             for (int j = 0; j < 4; ++j) { p1[j] = fr >= 1 ? r1[j] : q1[n][j]; p2[j] = fr >= 2 ? r2[j] : q2[n][j]; p3[j] = fr >= 3 ? r3[j] : q3[n][j]; }
;                             q1[n] = r1; q2[n] = r2; q3[n] = r3;
;                             o[n] = bb[n] + w0[n] * p3 + w1[n] * p2 + w2[n] * p1 + w3[n] * gv;
;                             if (m == 0 && fr < 3) *(f32x4*)(headu + ((size_t)blk * 3 + fr) * LW + c0 + 4 * n) = gv;
;                             if (m == 3 && fr >= 13) *(f32x4*)(tailu + ((size_t)blk * 3 + (fr - 13)) * LW + c0 + 4 * n) = gv;
;                         }
;                         if (!(m == 0 && fr < 3)) {
;                             u32x4 w; w.x = cvt_pk_bf16(o[0][0], o[0][1]); w.y = cvt_pk_bf16(o[0][2], o[0][3]); w.z = cvt_pk_bf16(o[1][0], o[1][1]); w.w = cvt_pk_bf16(o[1][2], o[1][3]);
;                             *(u32x4*)(vout + (size_t)row * LW + c0) = w;
;                         }
	v_cndmask_b32_e32 v61, v151, v51, vcc
	s_waitcnt lgkmcnt(1)
	v_cndmask_b32_e32 v124, v154, v54, vcc
	s_waitcnt lgkmcnt(0)
	v_cndmask_b32_e32 v125, v157, v57, vcc
	v_pk_fma_f32 v[126:127], v[74:75], v[126:127], v[128:129]
	v_pk_fma_f32 v[62:63], v[72:73], v[62:63], v[112:113]
	s_nop 1
	v_mov_b32_dpp v112, v42 row_ror:3 row_mask:0xf bank_mask:0xf
	v_pk_fma_f32 v[60:61], v[68:69], v[60:61], v[62:63]
	v_pk_fma_f32 v[62:63], v[70:71], v[124:125], v[126:127]
	v_pk_fma_f32 v[126:127], v[44:45], v[64:65], v[60:61]
	v_pk_fma_f32 v[136:137], v[46:47], v[66:67], v[62:63]
	s_nop 1
	v_mov_b32_dpp v46, v40 row_ror:3 row_mask:0xf bank_mask:0xf
	v_mov_b32_dpp v47, v41 row_ror:1 row_mask:0xf bank_mask:0xf
	v_mov_b32_dpp v61, v41 row_ror:3 row_mask:0xf bank_mask:0xf
	v_mov_b32_dpp v125, v43 row_ror:3 row_mask:0xf bank_mask:0xf
	v_mov_b32_dpp v44, v40 row_ror:1 row_mask:0xf bank_mask:0xf
	v_mov_b32_dpp v45, v40 row_ror:2 row_mask:0xf bank_mask:0xf
	v_mov_b32_dpp v60, v41 row_ror:2 row_mask:0xf bank_mask:0xf
	v_mov_b32_dpp v63, v42 row_ror:2 row_mask:0xf bank_mask:0xf
	v_mov_b32_dpp v124, v43 row_ror:2 row_mask:0xf bank_mask:0xf
	v_mov_b32_dpp v62, v42 row_ror:1 row_mask:0xf bank_mask:0xf
	v_mov_b32_dpp v113, v43 row_ror:1 row_mask:0xf bank_mask:0xf
	s_waitcnt lgkmcnt(10)
	v_cndmask_b32_e64 v132, v140, v46, s[4:5]
	s_waitcnt lgkmcnt(9)
	v_cndmask_b32_e32 v129, v141, v47, vcc
	s_waitcnt lgkmcnt(8)
	v_cndmask_b32_e64 v133, v143, v61, s[4:5]
	v_cndmask_b32_e64 v140, v146, v112, s[4:5]
	s_waitcnt lgkmcnt(7)
	v_cndmask_b32_e64 v141, v161, v125, s[4:5]
	s_waitcnt lgkmcnt(6)
	v_cndmask_b32_e32 v128, v138, v44, vcc
	s_waitcnt lgkmcnt(5)
	v_cndmask_b32_e64 v130, v139, v45, s[0:1]
	s_waitcnt lgkmcnt(4)
	v_cndmask_b32_e64 v131, v142, v60, s[0:1]
	s_waitcnt lgkmcnt(3)
	v_cndmask_b32_e64 v138, v145, v63, s[0:1]
	s_waitcnt lgkmcnt(2)
	v_cndmask_b32_e64 v139, v160, v124, s[0:1]
	v_pk_fma_f32 v[132:133], v[96:97], v[132:133], v[100:101]
	v_pk_fma_f32 v[140:141], v[98:99], v[140:141], v[102:103]
	s_waitcnt lgkmcnt(1)
	v_cndmask_b32_e32 v134, v144, v62, vcc
	s_waitcnt lgkmcnt(0)
	v_cndmask_b32_e32 v135, v147, v113, vcc
	v_pk_fma_f32 v[138:139], v[94:95], v[138:139], v[140:141]
	v_pk_fma_f32 v[130:131], v[92:93], v[130:131], v[132:133]
	s_nop 1
	v_mov_b32_dpp v132, v35 row_ror:2 row_mask:0xf bank_mask:0xf
	v_pk_fma_f32 v[128:129], v[88:89], v[128:129], v[130:131]
	v_pk_fma_f32 v[130:131], v[90:91], v[134:135], v[138:139]
	v_pk_fma_f32 v[140:141], v[40:41], v[84:85], v[128:129]
	v_pk_fma_f32 v[138:139], v[42:43], v[86:87], v[130:131]
	v_cvt_pk_bf16_f32 v134, v126, v127
	s_nop 1
	v_mov_b32_dpp v40, v32 row_ror:1 row_mask:0xf bank_mask:0xf
	v_mov_b32_dpp v41, v32 row_ror:2 row_mask:0xf bank_mask:0xf
	v_mov_b32_dpp v42, v32 row_ror:3 row_mask:0xf bank_mask:0xf
	v_mov_b32_dpp v43, v33 row_ror:1 row_mask:0xf bank_mask:0xf
	v_mov_b32_dpp v126, v33 row_ror:2 row_mask:0xf bank_mask:0xf
	v_mov_b32_dpp v127, v33 row_ror:3 row_mask:0xf bank_mask:0xf
	v_mov_b32_dpp v128, v34 row_ror:1 row_mask:0xf bank_mask:0xf
	v_mov_b32_dpp v129, v34 row_ror:2 row_mask:0xf bank_mask:0xf
	v_mov_b32_dpp v130, v34 row_ror:3 row_mask:0xf bank_mask:0xf
	v_mov_b32_dpp v131, v35 row_ror:1 row_mask:0xf bank_mask:0xf
	v_mov_b32_dpp v133, v35 row_ror:3 row_mask:0xf bank_mask:0xf
	v_cvt_pk_bf16_f32 v135, v136, v137
	v_cvt_pk_bf16_f32 v136, v140, v141
	v_cvt_pk_bf16_f32 v137, v138, v139
	global_store_dwordx4 v[114:115], v[134:137], off offset:256
	s_and_saveexec_b64 s[12:13], s[6:7]
	s_cbranch_execz .LBB0_164
	global_store_dwordx4 v[108:109], v[32:35], off offset:512
.LBB0_164:
	s_or_b64 exec, exec, s[12:13]
	s_nop 1
	v_mov_b32_dpp v114, v36 row_ror:1 row_mask:0xf bank_mask:0xf
	v_mov_b32_dpp v115, v36 row_ror:2 row_mask:0xf bank_mask:0xf
	v_mov_b32_dpp v134, v36 row_ror:3 row_mask:0xf bank_mask:0xf
	v_mov_b32_dpp v135, v37 row_ror:1 row_mask:0xf bank_mask:0xf
	v_mov_b32_dpp v136, v37 row_ror:2 row_mask:0xf bank_mask:0xf
	v_mov_b32_dpp v137, v37 row_ror:3 row_mask:0xf bank_mask:0xf
	v_mov_b32_dpp v138, v38 row_ror:1 row_mask:0xf bank_mask:0xf
	v_mov_b32_dpp v139, v38 row_ror:2 row_mask:0xf bank_mask:0xf
	v_mov_b32_dpp v140, v38 row_ror:3 row_mask:0xf bank_mask:0xf
	v_mov_b32_dpp v141, v39 row_ror:1 row_mask:0xf bank_mask:0xf
	v_mov_b32_dpp v142, v39 row_ror:2 row_mask:0xf bank_mask:0xf
	v_mov_b32_dpp v143, v39 row_ror:3 row_mask:0xf bank_mask:0xf
	s_and_saveexec_b64 s[12:13], s[6:7]
	s_cbranch_execz .LBB0_166
	global_store_dwordx4 v[108:109], v[36:39], off offset:528
; __device__ __forceinline__ unsigned cvt_pk_bf16(float lo, float hi) { unsigned r; asm volatile("v_cvt_pk_bf16_f32 %0, %1, %2" : "=v"(r) : "v"(lo), "v"(hi)); return r; }
;     __device__ __forceinline__ void operator()(EPI_ARGS) const {
;     ...
;                     for (int m = 0; m < 4; ++m) {
;                         const int row = ROW_OF(ai, m);
;                         f32x4 o[2];
; #pragma unroll
;                         for (int n = 0; n < 2; ++n) {
;                             const f32x4 gv = acc[ai][bj][m][n];
;                             f32x4 r1, r2, r3, p1, p2, p3;
; #pragma unroll
;                             for (int j = 0; j < 4; ++j) { r1[j] = __shfl(gv[j], s1); r2[j] = __shfl(gv[j], s2); r3[j] = __shfl(gv[j], s3); }
; #pragma unroll
;                             for (int j = 0; j < 4; ++j) { p1[j] = fr >= 1 ? r1[j] : q1[n][j]; p2[j] = fr >= 2 ? r2[j] : q2[n][j]; p3[j] = fr >= 3 ? r3[j] : q3[n][j]; }
;                             q1[n] = r1; q2[n] = r2; q3[n] = r3;
;                             o[n] = bb[n] + w0[n] * p3 + w1[n] * p2 + w2[n] * p1 + w3[n] * gv;
;                             if (m == 0 && fr < 3) *(f32x4*)(headu + ((size_t)blk * 3 + fr) * LW + c0 + 4 * n) = gv;
;                             if (m == 3 && fr >= 13) *(f32x4*)(tailu + ((size_t)blk * 3 + (fr - 13)) * LW + c0 + 4 * n) = gv;
;                         }
;                         if (!(m == 0 && fr < 3)) {
;                             u32x4 w; w.x = cvt_pk_bf16(o[0][0], o[0][1]); w.y = cvt_pk_bf16(o[0][2], o[0][3]); w.z = cvt_pk_bf16(o[1][0], o[1][1]); w.w = cvt_pk_bf16(o[1][2], o[1][3]);
;                             *(u32x4*)(vout + (size_t)row * LW + c0) = w;
;                         }
.LBB0_166:
	s_or_b64 exec, exec, s[12:13]
	s_waitcnt lgkmcnt(10)
	v_cndmask_b32_e64 v108, v45, v115, s[0:1]
	s_waitcnt lgkmcnt(9)
	v_cndmask_b32_e64 v46, v46, v134, s[4:5]
	s_waitcnt lgkmcnt(8)
	v_cndmask_b32_e32 v45, v47, v135, vcc
	s_waitcnt lgkmcnt(6)
	v_cndmask_b32_e64 v47, v61, v137, s[4:5]
	v_cndmask_b32_e64 v109, v60, v136, s[0:1]
	v_pk_fma_f32 v[46:47], v[96:97], v[46:47], v[100:101]
	v_cndmask_b32_e32 v44, v44, v114, vcc
	s_waitcnt lgkmcnt(3)
	v_cndmask_b32_e64 v112, v112, v140, s[4:5]
	s_waitcnt lgkmcnt(2)
	v_cndmask_b32_e32 v61, v113, v141, vcc
	s_waitcnt lgkmcnt(0)
	v_cndmask_b32_e64 v113, v125, v143, s[4:5]
	v_pk_fma_f32 v[46:47], v[92:93], v[108:109], v[46:47]
	v_cndmask_b32_e32 v60, v62, v138, vcc
	v_cndmask_b32_e64 v62, v63, v139, s[0:1]
	v_cndmask_b32_e64 v63, v124, v142, s[0:1]
	v_pk_fma_f32 v[112:113], v[98:99], v[112:113], v[102:103]
	v_pk_fma_f32 v[44:45], v[88:89], v[44:45], v[46:47]
	v_pk_fma_f32 v[62:63], v[94:95], v[62:63], v[112:113]
	v_pk_fma_f32 v[36:37], v[36:37], v[84:85], v[44:45]
	v_cndmask_b32_e64 v44, v49, v41, s[0:1]
	v_cndmask_b32_e64 v42, v50, v42, s[4:5]
	v_cndmask_b32_e32 v41, v51, v43, vcc
	v_cndmask_b32_e64 v43, v53, v127, s[4:5]
	v_cndmask_b32_e64 v50, v56, v130, s[4:5]
	v_cndmask_b32_e64 v51, v59, v133, s[4:5]
	v_pk_fma_f32 v[46:47], v[90:91], v[60:61], v[62:63]
	v_cndmask_b32_e32 v40, v48, v40, vcc
	v_cndmask_b32_e64 v45, v52, v126, s[0:1]
	v_cndmask_b32_e64 v48, v55, v129, s[0:1]
	v_cndmask_b32_e64 v49, v58, v132, s[0:1]
	v_pk_fma_f32 v[42:43], v[76:77], v[42:43], v[80:81]
	v_pk_fma_f32 v[50:51], v[78:79], v[50:51], v[82:83]
	v_pk_fma_f32 v[38:39], v[38:39], v[86:87], v[46:47]
	v_cndmask_b32_e32 v46, v54, v128, vcc
	v_cndmask_b32_e32 v47, v57, v131, vcc
	v_pk_fma_f32 v[48:49], v[74:75], v[48:49], v[50:51]
	v_pk_fma_f32 v[42:43], v[72:73], v[44:45], v[42:43]
	s_nop 1
	v_mov_b32_dpp v44, v28 row_ror:1 row_mask:0xf bank_mask:0xf
	v_pk_fma_f32 v[40:41], v[68:69], v[40:41], v[42:43]
	v_pk_fma_f32 v[42:43], v[70:71], v[46:47], v[48:49]
	s_nop 1
	v_mov_b32_dpp v45, v28 row_ror:2 row_mask:0xf bank_mask:0xf
	v_mov_b32_dpp v46, v28 row_ror:3 row_mask:0xf bank_mask:0xf
	v_mov_b32_dpp v47, v29 row_ror:1 row_mask:0xf bank_mask:0xf
	v_mov_b32_dpp v48, v29 row_ror:2 row_mask:0xf bank_mask:0xf
	v_mov_b32_dpp v49, v29 row_ror:3 row_mask:0xf bank_mask:0xf
	v_mov_b32_dpp v50, v30 row_ror:1 row_mask:0xf bank_mask:0xf
	v_mov_b32_dpp v51, v30 row_ror:2 row_mask:0xf bank_mask:0xf
	v_mov_b32_dpp v52, v30 row_ror:3 row_mask:0xf bank_mask:0xf
	v_mov_b32_dpp v53, v31 row_ror:1 row_mask:0xf bank_mask:0xf
	v_mov_b32_dpp v54, v31 row_ror:2 row_mask:0xf bank_mask:0xf
	v_mov_b32_dpp v55, v31 row_ror:3 row_mask:0xf bank_mask:0xf
	v_pk_fma_f32 v[34:35], v[34:35], v[66:67], v[42:43]
	v_pk_fma_f32 v[32:33], v[32:33], v[64:65], v[40:41]
	s_nop 0
	v_cvt_pk_bf16_f32 v32, v32, v33
	v_cvt_pk_bf16_f32 v33, v34, v35
	v_cvt_pk_bf16_f32 v34, v36, v37
	v_cvt_pk_bf16_f32 v35, v38, v39
	global_store_dwordx4 v[110:111], v[32:35], off offset:256
	s_and_saveexec_b64 s[12:13], s[10:11]
	s_cbranch_execz .LBB0_168
	global_store_dwordx4 v[106:107], v[28:31], off offset:512
.LBB0_168:
	s_or_b64 exec, exec, s[12:13]
	s_nop 1
	v_mov_b32_dpp v32, v24 row_ror:1 row_mask:0xf bank_mask:0xf
	v_mov_b32_dpp v36, v24 row_ror:2 row_mask:0xf bank_mask:0xf
	v_mov_b32_dpp v40, v24 row_ror:3 row_mask:0xf bank_mask:0xf
	v_mov_b32_dpp v33, v25 row_ror:1 row_mask:0xf bank_mask:0xf
	v_mov_b32_dpp v37, v25 row_ror:2 row_mask:0xf bank_mask:0xf
	v_mov_b32_dpp v41, v25 row_ror:3 row_mask:0xf bank_mask:0xf
	v_mov_b32_dpp v34, v26 row_ror:1 row_mask:0xf bank_mask:0xf
	v_mov_b32_dpp v38, v26 row_ror:2 row_mask:0xf bank_mask:0xf
	v_mov_b32_dpp v42, v26 row_ror:3 row_mask:0xf bank_mask:0xf
	v_mov_b32_dpp v35, v27 row_ror:1 row_mask:0xf bank_mask:0xf
	v_mov_b32_dpp v39, v27 row_ror:2 row_mask:0xf bank_mask:0xf
	v_mov_b32_dpp v43, v27 row_ror:3 row_mask:0xf bank_mask:0xf
	s_and_saveexec_b64 s[10:11], s[8:9]
	s_xor_b64 s[8:9], exec, s[10:11]
	s_cbranch_execz .LBB0_170
	s_waitcnt lgkmcnt(14)
	v_cndmask_b32_e64 v60, 0, v46, s[4:5]
	v_cndmask_b32_e64 v61, 0, v49, s[4:5]
	v_cndmask_b32_e64 v58, 0, v45, s[0:1]
	v_cndmask_b32_e64 v59, 0, v48, s[0:1]
	v_cndmask_b32_e64 v108, 0, v52, s[4:5]
	s_waitcnt lgkmcnt(12)
	v_cndmask_b32_e64 v109, 0, v55, s[4:5]
	v_pk_fma_f32 v[60:61], v[76:77], v[60:61], v[80:81]
	v_cndmask_b32_e32 v56, 0, v44, vcc
	v_cndmask_b32_e32 v57, 0, v47, vcc
	v_cndmask_b32_e64 v106, 0, v51, s[0:1]
	v_cndmask_b32_e64 v107, 0, v54, s[0:1]
	v_pk_fma_f32 v[108:109], v[78:79], v[108:109], v[82:83]
	v_pk_fma_f32 v[58:59], v[72:73], v[58:59], v[60:61]
	v_cndmask_b32_e32 v62, 0, v50, vcc
	v_cndmask_b32_e32 v63, 0, v53, vcc
	v_pk_fma_f32 v[106:107], v[74:75], v[106:107], v[108:109]
	v_pk_fma_f32 v[56:57], v[68:69], v[56:57], v[58:59]
	v_pk_fma_f32 v[58:59], v[70:71], v[62:63], v[106:107]
	v_pk_fma_f32 v[28:29], v[28:29], v[64:65], v[56:57]
	s_waitcnt lgkmcnt(0)
	v_pk_fma_f32 v[56:57], v[98:99], v[42:43], v[102:103]
	v_pk_fma_f32 v[30:31], v[30:31], v[66:67], v[58:59]
	v_pk_fma_f32 v[58:59], v[96:97], v[40:41], v[100:101]
	v_pk_fma_f32 v[56:57], v[94:95], v[38:39], v[56:57]
	v_pk_fma_f32 v[58:59], v[92:93], v[36:37], v[58:59]
	v_pk_fma_f32 v[56:57], v[90:91], v[34:35], v[56:57]
	v_pk_fma_f32 v[58:59], v[88:89], v[32:33], v[58:59]
	v_pk_fma_f32 v[56:57], v[26:27], v[86:87], v[56:57]
	v_pk_fma_f32 v[58:59], v[24:25], v[84:85], v[58:59]
	v_cvt_pk_bf16_f32 v28, v28, v29
	v_cvt_pk_bf16_f32 v29, v30, v31
	s_nop 0
	v_cvt_pk_bf16_f32 v30, v58, v59
	v_cvt_pk_bf16_f32 v31, v56, v57
	v_lshlrev_b64 v[56:57], 12, v[104:105]
	v_lshl_add_u64 v[56:57], s[54:55], 0, v[56:57]
	v_lshl_add_u64 v[56:57], v[184:185], 1, v[56:57]
	global_store_dwordx4 v[56:57], v[28:31], off offset:256

; __device__ __forceinline__ unsigned cvt_pk_bf16(float lo, float hi) { unsigned r; asm volatile("v_cvt_pk_bf16_f32 %0, %1, %2" : "=v"(r) : "v"(lo), "v"(hi)); return r; }
;     __device__ __forceinline__ void operator()(EPI_ARGS) const {
;     ...
;                     for (int m = 0; m < 4; ++m) {
;                         const int row = ROW_OF(ai, m);
;                         f32x4 o[2];
; #pragma unroll
;                         for (int n = 0; n < 2; ++n) {
;                             const f32x4 gv = acc[ai][bj][m][n];
;                             f32x4 r1, r2, r3, p1, p2, p3;
; #pragma unroll
;                             for (int j = 0; j < 4; ++j) { r1[j] = __shfl(gv[j], s1); r2[j] = __shfl(gv[j], s2); r3[j] = __shfl(gv[j], s3); }
; #pragma unroll
;                             for (int j = 0; j < 4; ++j) { p1[j] = fr >= 1 ? r1[j] : q1[n][j]; p2[j] = fr >= 2 ? r2[j] : q2[n][j]; p3[j] = fr >= 3 ? r3[j] : q3[n][j]; }
;                             q1[n] = r1; q2[n] = r2; q3[n] = r3;
;                             o[n] = bb[n] + w0[n] * p3 + w1[n] * p2 + w2[n] * p1 + w3[n] * gv;
;                             if (m == 0 && fr < 3) *(f32x4*)(headu + ((size_t)blk * 3 + fr) * LW + c0 + 4 * n) = gv;
;                             if (m == 3 && fr >= 13) *(f32x4*)(tailu + ((size_t)blk * 3 + (fr - 13)) * LW + c0 + 4 * n) = gv;
;                         }
;                         if (!(m == 0 && fr < 3)) {
;                             u32x4 w; w.x = cvt_pk_bf16(o[0][0], o[0][1]); w.y = cvt_pk_bf16(o[0][2], o[0][3]); w.z = cvt_pk_bf16(o[1][0], o[1][1]); w.w = cvt_pk_bf16(o[1][2], o[1][3]);
;                             *(u32x4*)(vout + (size_t)row * LW + c0) = w;
;                         }
.LBB0_172:
	s_or_b64 exec, exec, s[8:9]
	s_nop 1
	v_mov_b32_dpp v58, v20 row_ror:3 row_mask:0xf bank_mask:0xf
	v_mov_b32_dpp v59, v21 row_ror:1 row_mask:0xf bank_mask:0xf
	v_mov_b32_dpp v61, v21 row_ror:3 row_mask:0xf bank_mask:0xf
	v_mov_b32_dpp v104, v22 row_ror:3 row_mask:0xf bank_mask:0xf
	v_mov_b32_dpp v107, v23 row_ror:3 row_mask:0xf bank_mask:0xf
	v_mov_b32_dpp v56, v20 row_ror:1 row_mask:0xf bank_mask:0xf
	v_mov_b32_dpp v57, v20 row_ror:2 row_mask:0xf bank_mask:0xf
	v_mov_b32_dpp v60, v21 row_ror:2 row_mask:0xf bank_mask:0xf
	v_mov_b32_dpp v63, v22 row_ror:2 row_mask:0xf bank_mask:0xf
	v_mov_b32_dpp v106, v23 row_ror:2 row_mask:0xf bank_mask:0xf
	v_mov_b32_dpp v62, v22 row_ror:1 row_mask:0xf bank_mask:0xf
	v_mov_b32_dpp v105, v23 row_ror:1 row_mask:0xf bank_mask:0xf
	s_waitcnt lgkmcnt(11)
	v_cndmask_b32_e64 v28, v46, v58, s[4:5]
	s_waitcnt lgkmcnt(10)
	v_cndmask_b32_e32 v25, v47, v59, vcc
	s_waitcnt lgkmcnt(9)
	v_cndmask_b32_e64 v29, v49, v61, s[4:5]
	s_waitcnt lgkmcnt(8)
	v_cndmask_b32_e64 v46, v52, v104, s[4:5]
	s_waitcnt lgkmcnt(7)
	v_cndmask_b32_e64 v47, v55, v107, s[4:5]
	s_waitcnt lgkmcnt(6)
	v_cndmask_b32_e32 v24, v44, v56, vcc
	s_waitcnt lgkmcnt(5)
	v_cndmask_b32_e64 v26, v45, v57, s[0:1]
	s_waitcnt lgkmcnt(4)
	v_cndmask_b32_e64 v27, v48, v60, s[0:1]
	s_waitcnt lgkmcnt(3)
	v_cndmask_b32_e64 v44, v51, v63, s[0:1]
	s_waitcnt lgkmcnt(2)
	v_cndmask_b32_e64 v45, v54, v106, s[0:1]
	v_pk_fma_f32 v[28:29], v[76:77], v[28:29], v[80:81]
	v_pk_fma_f32 v[46:47], v[78:79], v[46:47], v[82:83]
	s_waitcnt lgkmcnt(1)
	v_cndmask_b32_e32 v30, v50, v62, vcc
	s_waitcnt lgkmcnt(0)
	v_cndmask_b32_e32 v31, v53, v105, vcc
	v_pk_fma_f32 v[44:45], v[74:75], v[44:45], v[46:47]
	v_pk_fma_f32 v[26:27], v[72:73], v[26:27], v[28:29]
	s_nop 1
	v_mov_b32_dpp v48, v16 row_ror:3 row_mask:0xf bank_mask:0xf
	v_mov_b32_dpp v51, v17 row_ror:3 row_mask:0xf bank_mask:0xf
	v_mov_b32_dpp v52, v18 row_ror:1 row_mask:0xf bank_mask:0xf
	v_mov_b32_dpp v54, v18 row_ror:3 row_mask:0xf bank_mask:0xf
	v_mov_b32_dpp v55, v19 row_ror:1 row_mask:0xf bank_mask:0xf
	v_mov_b32_dpp v109, v19 row_ror:3 row_mask:0xf bank_mask:0xf
	v_pk_fma_f32 v[24:25], v[68:69], v[24:25], v[26:27]
	v_pk_fma_f32 v[26:27], v[70:71], v[30:31], v[44:45]
	s_nop 1
	v_mov_b32_dpp v44, v16 row_ror:1 row_mask:0xf bank_mask:0xf
	v_mov_b32_dpp v45, v16 row_ror:2 row_mask:0xf bank_mask:0xf
	v_mov_b32_dpp v49, v17 row_ror:1 row_mask:0xf bank_mask:0xf
	v_mov_b32_dpp v50, v17 row_ror:2 row_mask:0xf bank_mask:0xf
	v_mov_b32_dpp v53, v18 row_ror:2 row_mask:0xf bank_mask:0xf
	v_mov_b32_dpp v108, v19 row_ror:2 row_mask:0xf bank_mask:0xf
	s_waitcnt lgkmcnt(11)
	v_cndmask_b32_e64 v28, v40, v48, s[4:5]
	s_waitcnt lgkmcnt(10)
	v_cndmask_b32_e64 v29, v41, v51, s[4:5]
	s_waitcnt lgkmcnt(9)
	v_cndmask_b32_e32 v30, v34, v52, vcc
	s_waitcnt lgkmcnt(8)
	v_cndmask_b32_e64 v34, v42, v54, s[4:5]
	s_waitcnt lgkmcnt(7)
	v_cndmask_b32_e32 v31, v35, v55, vcc
	s_waitcnt lgkmcnt(6)
	v_cndmask_b32_e64 v35, v43, v109, s[4:5]
	v_pk_fma_f32 v[22:23], v[22:23], v[66:67], v[26:27]
	v_pk_fma_f32 v[20:21], v[20:21], v[64:65], v[24:25]
	s_waitcnt lgkmcnt(5)
	v_cndmask_b32_e32 v24, v32, v44, vcc
	s_waitcnt lgkmcnt(4)
	v_cndmask_b32_e64 v26, v36, v45, s[0:1]
	s_waitcnt lgkmcnt(3)
	v_cndmask_b32_e32 v25, v33, v49, vcc
	s_waitcnt lgkmcnt(2)
	v_cndmask_b32_e64 v27, v37, v50, s[0:1]
	s_waitcnt lgkmcnt(1)
	v_cndmask_b32_e64 v32, v38, v53, s[0:1]
	s_waitcnt lgkmcnt(0)
	v_cndmask_b32_e64 v33, v39, v108, s[0:1]
	v_pk_fma_f32 v[28:29], v[96:97], v[28:29], v[100:101]
	v_pk_fma_f32 v[34:35], v[98:99], v[34:35], v[102:103]
	v_pk_fma_f32 v[26:27], v[92:93], v[26:27], v[28:29]
	v_pk_fma_f32 v[32:33], v[94:95], v[32:33], v[34:35]
	v_pk_fma_f32 v[24:25], v[88:89], v[24:25], v[26:27]
	v_pk_fma_f32 v[26:27], v[90:91], v[30:31], v[32:33]
	s_nop 0
	v_pk_fma_f32 v[26:27], v[18:19], v[86:87], v[26:27]
	v_pk_fma_f32 v[18:19], v[16:17], v[84:85], v[24:25]
	v_cvt_pk_bf16_f32 v16, v20, v21
	v_cvt_pk_bf16_f32 v17, v22, v23
	s_nop 1
	v_mov_b32_dpp v21, v13 row_ror:3 row_mask:0xf bank_mask:0xf
	v_cvt_pk_bf16_f32 v18, v18, v19
	v_cvt_pk_bf16_f32 v19, v26, v27
	global_store_dwordx4 v[118:119], v[16:19], off offset:256
	s_nop 1
	v_mov_b32_dpp v18, v12 row_ror:3 row_mask:0xf bank_mask:0xf
	v_mov_b32_dpp v24, v14 row_ror:3 row_mask:0xf bank_mask:0xf
	v_mov_b32_dpp v27, v15 row_ror:3 row_mask:0xf bank_mask:0xf
	v_mov_b32_dpp v17, v12 row_ror:2 row_mask:0xf bank_mask:0xf
	v_mov_b32_dpp v20, v13 row_ror:2 row_mask:0xf bank_mask:0xf
	v_mov_b32_dpp v23, v14 row_ror:2 row_mask:0xf bank_mask:0xf
	v_mov_b32_dpp v26, v15 row_ror:2 row_mask:0xf bank_mask:0xf
	v_mov_b32_dpp v16, v12 row_ror:1 row_mask:0xf bank_mask:0xf
	v_mov_b32_dpp v19, v13 row_ror:1 row_mask:0xf bank_mask:0xf
	v_mov_b32_dpp v22, v14 row_ror:1 row_mask:0xf bank_mask:0xf
	v_mov_b32_dpp v25, v15 row_ror:1 row_mask:0xf bank_mask:0xf
	s_waitcnt lgkmcnt(10)
; __device__ __forceinline__ unsigned cvt_pk_bf16(float lo, float hi) { unsigned r; asm volatile("v_cvt_pk_bf16_f32 %0, %1, %2" : "=v"(r) : "v"(lo), "v"(hi)); return r; }
;     __device__ __forceinline__ void operator()(EPI_ARGS) const {
;     ...
;                     for (int m = 0; m < 4; ++m) {
;                         const int row = ROW_OF(ai, m);
;                         f32x4 o[2];
; #pragma unroll
;                         for (int n = 0; n < 2; ++n) {
;                             const f32x4 gv = acc[ai][bj][m][n];
;                             f32x4 r1, r2, r3, p1, p2, p3;
; #pragma unroll
;                             for (int j = 0; j < 4; ++j) { r1[j] = __shfl(gv[j], s1); r2[j] = __shfl(gv[j], s2); r3[j] = __shfl(gv[j], s3); }
; #pragma unroll
;                             for (int j = 0; j < 4; ++j) { p1[j] = fr >= 1 ? r1[j] : q1[n][j]; p2[j] = fr >= 2 ? r2[j] : q2[n][j]; p3[j] = fr >= 3 ? r3[j] : q3[n][j]; }
;                             q1[n] = r1; q2[n] = r2; q3[n] = r3;
;                             o[n] = bb[n] + w0[n] * p3 + w1[n] * p2 + w2[n] * p1 + w3[n] * gv;
;                             if (m == 0 && fr < 3) *(f32x4*)(headu + ((size_t)blk * 3 + fr) * LW + c0 + 4 * n) = gv;
;                             if (m == 3 && fr >= 13) *(f32x4*)(tailu + ((size_t)blk * 3 + (fr - 13)) * LW + c0 + 4 * n) = gv;
;                         }
;                         if (!(m == 0 && fr < 3)) {
;                             u32x4 w; w.x = cvt_pk_bf16(o[0][0], o[0][1]); w.y = cvt_pk_bf16(o[0][2], o[0][3]); w.z = cvt_pk_bf16(o[1][0], o[1][1]); w.w = cvt_pk_bf16(o[1][2], o[1][3]);
;                             *(u32x4*)(vout + (size_t)row * LW + c0) = w;
;                         }
	v_cndmask_b32_e64 v32, v58, v18, s[4:5]
	v_cndmask_b32_e64 v33, v61, v21, s[4:5]
	s_waitcnt lgkmcnt(9)
	v_cndmask_b32_e64 v38, v104, v24, s[4:5]
	s_waitcnt lgkmcnt(8)
	v_cndmask_b32_e64 v39, v107, v27, s[4:5]
	s_waitcnt lgkmcnt(7)
	v_cndmask_b32_e64 v30, v57, v17, s[0:1]
	s_waitcnt lgkmcnt(6)
	v_cndmask_b32_e64 v31, v60, v20, s[0:1]
	s_waitcnt lgkmcnt(5)
	v_cndmask_b32_e64 v36, v63, v23, s[0:1]
	s_waitcnt lgkmcnt(4)
	v_cndmask_b32_e64 v37, v106, v26, s[0:1]
	v_pk_fma_f32 v[32:33], v[76:77], v[32:33], v[80:81]
	v_pk_fma_f32 v[38:39], v[78:79], v[38:39], v[82:83]
	s_waitcnt lgkmcnt(3)
	v_cndmask_b32_e32 v28, v56, v16, vcc
	s_waitcnt lgkmcnt(2)
	v_cndmask_b32_e32 v29, v59, v19, vcc
	s_waitcnt lgkmcnt(1)
	v_cndmask_b32_e32 v34, v62, v22, vcc
	s_waitcnt lgkmcnt(0)
	v_cndmask_b32_e32 v35, v105, v25, vcc
	v_pk_fma_f32 v[36:37], v[74:75], v[36:37], v[38:39]
	v_pk_fma_f32 v[30:31], v[72:73], v[30:31], v[32:33]
	s_nop 1
	v_mov_b32_dpp v32, v10 row_ror:3 row_mask:0xf bank_mask:0xf
	v_pk_fma_f32 v[28:29], v[68:69], v[28:29], v[30:31]
	v_pk_fma_f32 v[30:31], v[70:71], v[34:35], v[36:37]
	v_pk_fma_f32 v[36:37], v[12:13], v[64:65], v[28:29]
	v_pk_fma_f32 v[46:47], v[14:15], v[66:67], v[30:31]
	s_nop 1
	v_mov_b32_dpp v14, v8 row_ror:3 row_mask:0xf bank_mask:0xf
	v_mov_b32_dpp v28, v9 row_ror:2 row_mask:0xf bank_mask:0xf
	v_mov_b32_dpp v29, v9 row_ror:3 row_mask:0xf bank_mask:0xf
	v_mov_b32_dpp v35, v11 row_ror:3 row_mask:0xf bank_mask:0xf
	v_mov_b32_dpp v13, v8 row_ror:2 row_mask:0xf bank_mask:0xf
	v_mov_b32_dpp v15, v9 row_ror:1 row_mask:0xf bank_mask:0xf
	v_mov_b32_dpp v31, v10 row_ror:2 row_mask:0xf bank_mask:0xf
	v_mov_b32_dpp v34, v11 row_ror:2 row_mask:0xf bank_mask:0xf
	v_mov_b32_dpp v12, v8 row_ror:1 row_mask:0xf bank_mask:0xf
	v_mov_b32_dpp v30, v10 row_ror:1 row_mask:0xf bank_mask:0xf
	v_mov_b32_dpp v33, v11 row_ror:1 row_mask:0xf bank_mask:0xf
	s_waitcnt lgkmcnt(10)
	v_cndmask_b32_e64 v42, v48, v14, s[4:5]
	s_waitcnt lgkmcnt(9)
	v_cndmask_b32_e64 v41, v50, v28, s[0:1]
	s_waitcnt lgkmcnt(8)
	v_cndmask_b32_e64 v43, v51, v29, s[4:5]
	v_cndmask_b32_e64 v50, v54, v32, s[4:5]
	s_waitcnt lgkmcnt(7)
	v_cndmask_b32_e64 v51, v109, v35, s[4:5]
	s_waitcnt lgkmcnt(6)
	v_cndmask_b32_e64 v40, v45, v13, s[0:1]
	s_waitcnt lgkmcnt(5)
	v_cndmask_b32_e32 v39, v49, v15, vcc
	s_waitcnt lgkmcnt(4)
	v_cndmask_b32_e64 v48, v53, v31, s[0:1]
	s_waitcnt lgkmcnt(3)
	v_cndmask_b32_e64 v49, v108, v34, s[0:1]
	v_pk_fma_f32 v[42:43], v[96:97], v[42:43], v[100:101]
	v_pk_fma_f32 v[50:51], v[98:99], v[50:51], v[102:103]
	s_waitcnt lgkmcnt(2)
	v_cndmask_b32_e32 v38, v44, v12, vcc
	s_waitcnt lgkmcnt(1)
	v_cndmask_b32_e32 v44, v52, v30, vcc
	s_waitcnt lgkmcnt(0)
	v_cndmask_b32_e32 v45, v55, v33, vcc
	v_pk_fma_f32 v[48:49], v[94:95], v[48:49], v[50:51]
	v_pk_fma_f32 v[40:41], v[92:93], v[40:41], v[42:43]
	s_nop 1
	v_mov_b32_dpp v42, v3 row_ror:2 row_mask:0xf bank_mask:0xf
	v_pk_fma_f32 v[38:39], v[88:89], v[38:39], v[40:41]
	v_pk_fma_f32 v[40:41], v[90:91], v[44:45], v[48:49]
	v_pk_fma_f32 v[50:51], v[8:9], v[84:85], v[38:39]
	v_pk_fma_f32 v[48:49], v[10:11], v[86:87], v[40:41]
	v_cvt_pk_bf16_f32 v44, v36, v37
	s_nop 1
	v_mov_b32_dpp v8, v0 row_ror:1 row_mask:0xf bank_mask:0xf
	v_mov_b32_dpp v9, v0 row_ror:2 row_mask:0xf bank_mask:0xf
	v_mov_b32_dpp v10, v0 row_ror:3 row_mask:0xf bank_mask:0xf
	v_mov_b32_dpp v11, v1 row_ror:1 row_mask:0xf bank_mask:0xf
	v_mov_b32_dpp v36, v1 row_ror:2 row_mask:0xf bank_mask:0xf
	v_mov_b32_dpp v37, v1 row_ror:3 row_mask:0xf bank_mask:0xf
	v_mov_b32_dpp v38, v2 row_ror:1 row_mask:0xf bank_mask:0xf
	v_mov_b32_dpp v39, v2 row_ror:2 row_mask:0xf bank_mask:0xf
	v_mov_b32_dpp v40, v2 row_ror:3 row_mask:0xf bank_mask:0xf
	v_mov_b32_dpp v41, v3 row_ror:1 row_mask:0xf bank_mask:0xf
	v_mov_b32_dpp v43, v3 row_ror:3 row_mask:0xf bank_mask:0xf
	v_cvt_pk_bf16_f32 v45, v46, v47
	v_cvt_pk_bf16_f32 v46, v50, v51
	v_cvt_pk_bf16_f32 v47, v48, v49
	global_store_dwordx4 v[120:121], v[44:47], off offset:256
	s_and_saveexec_b64 s[8:9], s[6:7]
	s_cbranch_execz .LBB0_174
	global_store_dwordx4 v[116:117], v[0:3], off offset:512
.LBB0_174:
	s_or_b64 exec, exec, s[8:9]
	s_nop 1
	v_mov_b32_dpp v44, v4 row_ror:1 row_mask:0xf bank_mask:0xf
	v_mov_b32_dpp v45, v4 row_ror:2 row_mask:0xf bank_mask:0xf
	v_mov_b32_dpp v46, v4 row_ror:3 row_mask:0xf bank_mask:0xf
	v_mov_b32_dpp v47, v5 row_ror:1 row_mask:0xf bank_mask:0xf
	v_mov_b32_dpp v48, v5 row_ror:2 row_mask:0xf bank_mask:0xf
	v_mov_b32_dpp v49, v5 row_ror:3 row_mask:0xf bank_mask:0xf
	v_mov_b32_dpp v50, v6 row_ror:1 row_mask:0xf bank_mask:0xf
	v_mov_b32_dpp v51, v6 row_ror:2 row_mask:0xf bank_mask:0xf
	v_mov_b32_dpp v52, v6 row_ror:3 row_mask:0xf bank_mask:0xf
	v_mov_b32_dpp v53, v7 row_ror:1 row_mask:0xf bank_mask:0xf
	v_mov_b32_dpp v54, v7 row_ror:2 row_mask:0xf bank_mask:0xf
	v_mov_b32_dpp v55, v7 row_ror:3 row_mask:0xf bank_mask:0xf
	s_and_saveexec_b64 s[8:9], s[6:7]
	s_cbranch_execz .LBB0_176
	global_store_dwordx4 v[116:117], v[4:7], off offset:528

;     __device__ __forceinline__ void operator()(EPI_ARGS) const {
;         const int f0 = u.pn * 128 + wc * 32 + 8 * fq;
;         const int lane = fq * 16 + fr, src1 = (lane & 48) | ((fr - 1) & 15), src2 = (lane & 48) | ((fr - 2) & 15);
;         f32x4 w0[2], w1[2], w2[2], bb[2];
; #pragma unroll
;         for (int n = 0; n < 2; ++n) { w0[n] = *(const f32x4*)(cw + f0 + 4 * n); w1[n] = *(const f32x4*)(cw + FF + f0 + 4 * n); w2[n] = *(const f32x4*)(cw + 2 * FF + f0 + 4 * n); bb[n] = *(const f32x4*)(cb + f0 + 4 * n); }
;         float rsv[2][4];
; #pragma unroll
;         for (int ai = 0; ai < 2; ++ai)
; #pragma unroll
;             for (int m = 0; m < 4; ++m) rsv[ai][m] = ss2[ROW_OF(ai, m)];
; #pragma unroll
;         for (int ai = 0; ai < 2; ++ai) {
;             const int blk = u.pm * 4 + ai * 2 + wr;
;             f32x4 q1[2], q2[2];
; #pragma unroll
;             for (int n = 0; n < 2; ++n) { q1[n] = (f32x4){0.f, 0.f, 0.f, 0.f}; q2[n] = (f32x4){0.f, 0.f, 0.f, 0.f}; }
; #pragma unroll
;             for (int m = 0; m < 4; ++m) {
;                 const int row = ROW_OF(ai, m);
;                 const float rs = __builtin_amdgcn_rsqf(rsv[ai][m] * (1.0f / D) + EPS);
;                 f32x4 o[2];
; #pragma unroll
;                 for (int n = 0; n < 2; ++n) {
;                     const f32x4 gv = acc[ai][0][m][n] * rs, vv = acc[ai][1][m][n] * rs;
;                     f32x4 r1, r2;
; #pragma unroll
;                     for (int j = 0; j < 4; ++j) { r1[j] = __shfl(gv[j], src1); r2[j] = __shfl(gv[j], src2); }
;                     f32x4 p1, p2;
; #pragma unroll
;                     for (int j = 0; j < 4; ++j) { p1[j] = fr >= 1 ? r1[j] : q1[n][j]; p2[j] = fr >= 2 ? r2[j] : q2[n][j]; }
;                     q1[n] = r1; q2[n] = r2;
;                     const f32x4 cv = bb[n] + w0[n] * p2 + w1[n] * p1 + w2[n] * gv;
;                     o[n] = gelu4(cv) * vv;
;                     if (m == 0 && fr < 2) { const size_t so = ((size_t)blk * 2 + fr) * FF + f0 + 4 * n; *(f32x4*)(headg + so) = gv; *(f32x4*)(headv + so) = vv; }
;                     if (m == 3 && fr >= 14) { const size_t so = ((size_t)blk * 2 + (fr - 14)) * FF + f0 + 4 * n; *(f32x4*)(tailg + so) = gv; }
.LBB0_926:
	s_lshl_b32 s0, s9, 7
	v_mov_b32_e32 v184, v206
	v_mov_b32_e32 v168, v207
	s_or_b32 s0, s0, s35
	s_nop 0
	v_lshl_add_u32 v174, v168, 3, s0
	s_lshl_b32 s0, s8, 8
	s_add_i32 s0, s0, s34
	v_ashrrev_i32_e32 v175, 31, v174
	v_add_u32_e32 v192, s0, v184
	v_lshlrev_b64 v[64:65], 2, v[174:175]
	v_ashrrev_i32_e32 v193, 31, v192
	v_lshl_add_u64 v[66:67], s[84:85], 0, v[64:65]
	v_lshl_add_u64 v[68:69], s[16:17], 0, v[64:65]
	v_lshl_add_u64 v[70:71], s[18:19], 0, v[64:65]
	v_lshl_add_u64 v[76:77], s[86:87], 0, v[64:65]
	v_lshl_add_u64 v[176:177], v[192:193], 2, s[68:69]
	global_load_dwordx4 v[92:95], v[66:67], off offset:16
	global_load_dwordx4 v[72:75], v[66:67], off
	global_load_dwordx4 v[84:87], v[68:69], off offset:16
	s_nop 0
	global_load_dwordx4 v[64:67], v[68:69], off
	global_load_dwordx4 v[88:91], v[70:71], off offset:16
	s_nop 0
	global_load_dwordx4 v[68:71], v[70:71], off
	s_nop 0
	global_load_dwordx4 v[96:99], v[76:77], off offset:16
	s_nop 0
	global_load_dwordx4 v[76:79], v[76:77], off
	v_add_u32_e32 v190, 16, v192
	global_load_dword v220, v[176:177], off
	v_ashrrev_i32_e32 v191, 31, v190
	v_add_u32_e32 v188, 32, v192
	v_add_u32_e32 v186, 48, v192
	v_add_u32_e32 v182, 0x80, v192
	v_add_u32_e32 v180, 0x90, v192
	v_add_u32_e32 v178, 0xa0, v192
	v_add_u32_e32 v176, 0xb0, v192
	v_lshl_add_u64 v[194:195], v[190:191], 2, s[68:69]
	v_ashrrev_i32_e32 v189, 31, v188
	v_ashrrev_i32_e32 v187, 31, v186
	v_ashrrev_i32_e32 v183, 31, v182
	v_ashrrev_i32_e32 v181, 31, v180
	v_ashrrev_i32_e32 v179, 31, v178
	v_ashrrev_i32_e32 v177, 31, v176
	v_lshl_add_u64 v[196:197], v[188:189], 2, s[68:69]
	v_lshl_add_u64 v[198:199], v[186:187], 2, s[68:69]
	v_lshl_add_u64 v[200:201], v[182:183], 2, s[68:69]
	v_lshl_add_u64 v[202:203], v[180:181], 2, s[68:69]
	v_lshl_add_u64 v[204:205], v[178:179], 2, s[68:69]
	v_lshl_add_u64 v[218:219], v[176:177], 2, s[68:69]
	global_load_dword v217, v[194:195], off
	global_load_dword v193, v[196:197], off
	global_load_dword v191, v[198:199], off
	global_load_dword v189, v[200:201], off
	global_load_dword v187, v[202:203], off
	global_load_dword v183, v[204:205], off
	global_load_dword v181, v[218:219], off
	v_lshl_add_u32 v168, v168, 4, v184
	v_add_u32_e32 v177, -1, v184
	v_add_u32_e32 v179, 14, v184
	v_and_b32_e32 v177, 15, v177
	v_and_b32_e32 v179, 15, v179
	v_and_b32_e32 v168, 48, v168
	v_or3_b32 v177, v168, v177, v214
	v_or3_b32 v168, v168, v179, v214
	s_lshl_b32 s0, s8, 2
	s_add_i32 s60, s0, s29
	s_ashr_i32 s61, s60, 31
	v_lshlrev_b32_e32 v177, 2, v177
	v_ashrrev_i32_e32 v185, 31, v184
	s_lshl_b64 s[62:63], s[60:61], 1
	v_lshl_add_u64 v[194:195], s[62:63], 0, v[184:185]
	v_mad_u64_u32 v[196:197], s[0:1], v194, s65, v[174:175]
	v_mad_i32_i24 v197, v195, s65, v197
	v_cmp_lt_i32_e64 s[6:7], 1, v184
	v_cmp_gt_i32_e64 s[8:9], 2, v184
	v_lshlrev_b64 v[202:203], 2, v[196:197]
	s_waitcnt vmcnt(0)
	v_fmamk_f32 v179, v220, 0x3a000000, v215
	v_rsq_f32_e32 v204, v179
	v_lshlrev_b32_e32 v179, 2, v168
	v_pk_mul_f32 v[158:159], v[158:159], v[204:205] op_sel_hi:[1,0]
	v_pk_mul_f32 v[156:157], v[156:157], v[204:205] op_sel_hi:[1,0]
	s_nop 1
	v_mov_b32_dpp v218, v156 row_ror:1 row_mask:0xf bank_mask:0xf
	v_mov_b32_dpp v219, v156 row_ror:2 row_mask:0xf bank_mask:0xf
	v_mov_b32_dpp v220, v157 row_ror:1 row_mask:0xf bank_mask:0xf
	v_mov_b32_dpp v221, v157 row_ror:2 row_mask:0xf bank_mask:0xf
	v_mov_b32_dpp v222, v158 row_ror:1 row_mask:0xf bank_mask:0xf
	v_mov_b32_dpp v223, v158 row_ror:2 row_mask:0xf bank_mask:0xf
	v_mov_b32_dpp v224, v159 row_ror:1 row_mask:0xf bank_mask:0xf
	v_mov_b32_dpp v225, v159 row_ror:2 row_mask:0xf bank_mask:0xf
	v_pk_mul_f32 v[154:155], v[154:155], v[204:205] op_sel_hi:[1,0]
	v_pk_mul_f32 v[152:153], v[152:153], v[204:205] op_sel_hi:[1,0]
	s_and_saveexec_b64 s[0:1], s[8:9]
	s_cbranch_execz .LBB0_928
	v_lshl_add_u64 v[196:197], s[24:25], 0, v[202:203]
	v_lshl_add_u64 v[194:195], s[38:39], 0, v[202:203]
	global_store_dwordx4 v[196:197], v[156:159], off
	global_store_dwordx4 v[194:195], v[152:155], off
; __device__ __forceinline__ unsigned cvt_pk_bf16(float lo, float hi) { unsigned r; asm volatile("v_cvt_pk_bf16_f32 %0, %1, %2" : "=v"(r) : "v"(lo), "v"(hi)); return r; }
;     __device__ __forceinline__ void operator()(EPI_ARGS) const {
;     ...
;                 for (int n = 0; n < 2; ++n) {
;                     const f32x4 gv = acc[ai][0][m][n] * rs, vv = acc[ai][1][m][n] * rs;
;                     f32x4 r1, r2;
; #pragma unroll
;                     for (int j = 0; j < 4; ++j) { r1[j] = __shfl(gv[j], src1); r2[j] = __shfl(gv[j], src2); }
;                     f32x4 p1, p2;
; #pragma unroll
;                     for (int j = 0; j < 4; ++j) { p1[j] = fr >= 1 ? r1[j] : q1[n][j]; p2[j] = fr >= 2 ? r2[j] : q2[n][j]; }
;                     q1[n] = r1; q2[n] = r2;
;                     const f32x4 cv = bb[n] + w0[n] * p2 + w1[n] * p1 + w2[n] * gv;
;                     o[n] = gelu4(cv) * vv;
;                     if (m == 0 && fr < 2) { const size_t so = ((size_t)blk * 2 + fr) * FF + f0 + 4 * n; *(f32x4*)(headg + so) = gv; *(f32x4*)(headv + so) = vv; }
;                     if (m == 3 && fr >= 14) { const size_t so = ((size_t)blk * 2 + (fr - 14)) * FF + f0 + 4 * n; *(f32x4*)(tailg + so) = gv; }
;                 }
;                 if (!(m == 0 && fr < 2)) {
;                     u32x4 w; w.x = cvt_pk_bf16(o[0][0], o[0][1]); w.y = cvt_pk_bf16(o[0][2], o[0][3]); w.z = cvt_pk_bf16(o[1][0], o[1][1]); w.w = cvt_pk_bf16(o[1][2], o[1][3]);
;                     *(u32x4*)(act + (size_t)row * FF + f0) = w;
.LBB0_928:
	s_or_b64 exec, exec, s[0:1]
	v_mov_b32_e32 v205, v204
	v_mov_b32_e32 v226, v204
	v_mov_b32_e32 v227, v204
	v_pk_mul_f32 v[150:151], v[150:151], v[226:227]
	v_pk_mul_f32 v[148:149], v[148:149], v[204:205]
	s_nop 1
	v_mov_b32_dpp v194, v148 row_ror:1 row_mask:0xf bank_mask:0xf
	v_mov_b32_dpp v198, v148 row_ror:2 row_mask:0xf bank_mask:0xf
	v_mov_b32_dpp v195, v149 row_ror:1 row_mask:0xf bank_mask:0xf
	v_mov_b32_dpp v199, v149 row_ror:2 row_mask:0xf bank_mask:0xf
	v_mov_b32_dpp v196, v150 row_ror:1 row_mask:0xf bank_mask:0xf
	v_mov_b32_dpp v200, v150 row_ror:2 row_mask:0xf bank_mask:0xf
	v_mov_b32_dpp v197, v151 row_ror:1 row_mask:0xf bank_mask:0xf
	v_mov_b32_dpp v201, v151 row_ror:2 row_mask:0xf bank_mask:0xf
	v_cmp_lt_i32_e32 vcc, 0, v184
	v_cmp_lt_i32_e64 s[0:1], 1, v184
	v_pk_mul_f32 v[146:147], v[146:147], v[226:227]
	v_pk_mul_f32 v[144:145], v[144:145], v[204:205]
	s_and_saveexec_b64 s[4:5], s[6:7]
	s_xor_b64 s[4:5], exec, s[4:5]
	s_cbranch_execz .LBB0_930
	s_waitcnt lgkmcnt(14)
	v_cndmask_b32_e64 v204, 0, v219, s[0:1]
	s_waitcnt lgkmcnt(12)
	v_cndmask_b32_e64 v205, 0, v221, s[0:1]
	v_cndmask_b32_e32 v202, 0, v218, vcc
	v_cndmask_b32_e32 v203, 0, v220, vcc
	s_waitcnt lgkmcnt(10)
	v_cndmask_b32_e64 v228, 0, v223, s[0:1]
	s_waitcnt lgkmcnt(8)
	v_cndmask_b32_e64 v229, 0, v225, s[0:1]
	v_pk_fma_f32 v[204:205], v[72:73], v[204:205], v[76:77]
	v_cndmask_b32_e32 v226, 0, v222, vcc
	v_cndmask_b32_e32 v227, 0, v224, vcc
	v_pk_fma_f32 v[228:229], v[74:75], v[228:229], v[78:79]
	v_pk_fma_f32 v[202:203], v[64:65], v[202:203], v[204:205]
	v_pk_fma_f32 v[226:227], v[66:67], v[226:227], v[228:229]
	v_pk_fma_f32 v[156:157], v[68:69], v[156:157], v[202:203]
	v_pk_fma_f32 v[158:159], v[70:71], v[158:159], v[226:227]
	v_pk_mul_f32 v[204:205], v[156:157], v[156:157]
	v_pk_mul_f32 v[202:203], v[158:159], v[158:159]
	v_fmamk_f32 v168, v204, 0xbdd2d3e8, v216
	v_mul_f32_e32 v168, v156, v168
	v_fmamk_f32 v204, v205, 0xbdd2d3e8, v216
	v_fmamk_f32 v202, v202, 0xbdd2d3e8, v216
	v_exp_f32_e32 v168, v168
	v_mul_f32_e32 v204, v157, v204
	v_mul_f32_e32 v202, v158, v202
	v_exp_f32_e32 v204, v204
	v_exp_f32_e32 v205, v202
	v_fmamk_f32 v202, v203, 0xbdd2d3e8, v216
	v_mul_f32_e32 v202, v159, v202
	v_exp_f32_e32 v226, v202
	v_add_f32_e32 v168, 1.0, v168
	v_rcp_f32_e32 v202, v168
	v_add_f32_e32 v168, 1.0, v204
	v_rcp_f32_e32 v203, v168
	v_add_f32_e32 v168, 1.0, v205
	v_rcp_f32_e32 v204, v168
	v_add_f32_e32 v168, 1.0, v226
	v_rcp_f32_e32 v205, v168
	v_pk_mul_f32 v[156:157], v[156:157], v[202:203]
	s_waitcnt lgkmcnt(0)
	v_pk_fma_f32 v[202:203], v[94:95], v[200:201], v[98:99]
	v_pk_mul_f32 v[152:153], v[152:153], v[156:157]
	v_pk_mul_f32 v[158:159], v[158:159], v[204:205]
	v_pk_fma_f32 v[204:205], v[92:93], v[198:199], v[96:97]
	v_pk_fma_f32 v[202:203], v[86:87], v[196:197], v[202:203]
	v_pk_fma_f32 v[204:205], v[84:85], v[194:195], v[204:205]
	v_pk_fma_f32 v[150:151], v[90:91], v[150:151], v[202:203]
	v_pk_fma_f32 v[148:149], v[88:89], v[148:149], v[204:205]
	v_pk_mul_f32 v[202:203], v[150:151], v[150:151]
	v_pk_mul_f32 v[204:205], v[148:149], v[148:149]
	v_fmamk_f32 v202, v202, 0xbdd2d3e8, v216
	v_fmamk_f32 v168, v204, 0xbdd2d3e8, v216
	v_mul_f32_e32 v168, v148, v168
	v_exp_f32_e32 v168, v168
	v_fmamk_f32 v203, v203, 0xbdd2d3e8, v216
	v_mul_f32_e32 v202, v150, v202
	v_mul_f32_e32 v203, v151, v203
	v_add_f32_e32 v168, 1.0, v168
	v_rcp_f32_e32 v204, v168
	v_fmamk_f32 v168, v205, 0xbdd2d3e8, v216
	v_mul_f32_e32 v168, v149, v168
	v_exp_f32_e32 v168, v168
	v_exp_f32_e32 v202, v202
	v_exp_f32_e32 v203, v203
	v_pk_mul_f32 v[154:155], v[154:155], v[158:159]
	v_add_f32_e32 v168, 1.0, v168
	v_add_f32_e32 v202, 1.0, v202
	v_add_f32_e32 v203, 1.0, v203
	v_rcp_f32_e32 v202, v202
	v_rcp_f32_e32 v203, v203
	v_rcp_f32_e32 v205, v168
	v_pk_mul_f32 v[150:151], v[150:151], v[202:203]
	v_pk_mul_f32 v[148:149], v[148:149], v[204:205]
	v_pk_mul_f32 v[150:151], v[146:147], v[150:151]
	v_pk_mul_f32 v[146:147], v[144:145], v[148:149]
	v_mov_b64_e32 v[148:149], s[10:11]
	v_mad_i64_i32 v[148:149], s[12:13], v192, s66, v[148:149]
	v_cvt_pk_bf16_f32 v144, v152, v153
	v_cvt_pk_bf16_f32 v145, v154, v155
	v_cvt_pk_bf16_f32 v146, v146, v147
	v_cvt_pk_bf16_f32 v147, v150, v151
	v_lshl_add_u64 v[148:149], v[174:175], 1, v[148:149]
	global_store_dwordx4 v[148:149], v[144:147], off

; __device__ __forceinline__ unsigned cvt_pk_bf16(float lo, float hi) { unsigned r; asm volatile("v_cvt_pk_bf16_f32 %0, %1, %2" : "=v"(r) : "v"(lo), "v"(hi)); return r; }
;     __device__ __forceinline__ void operator()(EPI_ARGS) const {
;     ...
;             for (int m = 0; m < 4; ++m) {
;                 const int row = ROW_OF(ai, m);
;                 const float rs = __builtin_amdgcn_rsqf(rsv[ai][m] * (1.0f / D) + EPS);
;                 f32x4 o[2];
; #pragma unroll
;                 for (int n = 0; n < 2; ++n) {
;                     const f32x4 gv = acc[ai][0][m][n] * rs, vv = acc[ai][1][m][n] * rs;
;                     f32x4 r1, r2;
; #pragma unroll
;                     for (int j = 0; j < 4; ++j) { r1[j] = __shfl(gv[j], src1); r2[j] = __shfl(gv[j], src2); }
;                     f32x4 p1, p2;
; #pragma unroll
;                     for (int j = 0; j < 4; ++j) { p1[j] = fr >= 1 ? r1[j] : q1[n][j]; p2[j] = fr >= 2 ? r2[j] : q2[n][j]; }
;                     q1[n] = r1; q2[n] = r2;
;                     const f32x4 cv = bb[n] + w0[n] * p2 + w1[n] * p1 + w2[n] * gv;
;                     o[n] = gelu4(cv) * vv;
;                     if (m == 0 && fr < 2) { const size_t so = ((size_t)blk * 2 + fr) * FF + f0 + 4 * n; *(f32x4*)(headg + so) = gv; *(f32x4*)(headv + so) = vv; }
;                     if (m == 3 && fr >= 14) { const size_t so = ((size_t)blk * 2 + (fr - 14)) * FF + f0 + 4 * n; *(f32x4*)(tailg + so) = gv; }
;                 }
;                 if (!(m == 0 && fr < 2)) {
;                     u32x4 w; w.x = cvt_pk_bf16(o[0][0], o[0][1]); w.y = cvt_pk_bf16(o[0][2], o[0][3]); w.z = cvt_pk_bf16(o[1][0], o[1][1]); w.w = cvt_pk_bf16(o[1][2], o[1][3]);
;                     *(u32x4*)(act + (size_t)row * FF + f0) = w;
.LBB0_932:
	s_or_b64 exec, exec, s[4:5]
	s_nop 0
	v_fmamk_f32 v144, v217, 0x3a000000, v215
	v_rsq_f32_e32 v148, v144
	v_add_u32_e32 v168, -14, v184
	v_lshl_add_u64 v[146:147], s[62:63], 0, v[168:169]
	v_mad_u64_u32 v[144:145], s[12:13], v146, s30, 0
	v_pk_mul_f32 v[142:143], v[142:143], v[148:149] op_sel_hi:[1,0]
	v_pk_mul_f32 v[140:141], v[140:141], v[148:149] op_sel_hi:[1,0]
	s_nop 1
	v_mov_b32_dpp v192, v142 row_ror:2 row_mask:0xf bank_mask:0xf
	v_mov_b32_dpp v203, v143 row_ror:2 row_mask:0xf bank_mask:0xf
	v_mov_b32_dpp v156, v140 row_ror:2 row_mask:0xf bank_mask:0xf
	v_mov_b32_dpp v158, v141 row_ror:2 row_mask:0xf bank_mask:0xf
	v_mov_b32_dpp v159, v142 row_ror:1 row_mask:0xf bank_mask:0xf
	v_mov_b32_dpp v202, v143 row_ror:1 row_mask:0xf bank_mask:0xf
	v_mov_b32_dpp v149, v140 row_ror:1 row_mask:0xf bank_mask:0xf
	v_mov_b32_dpp v157, v141 row_ror:1 row_mask:0xf bank_mask:0xf
	s_waitcnt lgkmcnt(7)
	v_cndmask_b32_e64 v154, v223, v192, s[0:1]
	s_waitcnt lgkmcnt(6)
	v_cndmask_b32_e64 v155, v225, v203, s[0:1]
	s_waitcnt lgkmcnt(5)
	v_cndmask_b32_e64 v150, v219, v156, s[0:1]
	s_waitcnt lgkmcnt(4)
	v_cndmask_b32_e64 v151, v221, v158, s[0:1]
	s_waitcnt lgkmcnt(3)
	v_cndmask_b32_e32 v152, v222, v159, vcc
	s_waitcnt lgkmcnt(2)
	v_cndmask_b32_e32 v153, v224, v202, vcc
	v_pk_fma_f32 v[154:155], v[74:75], v[154:155], v[78:79]
	v_mad_i32_i24 v145, v147, s30, v145
	s_waitcnt lgkmcnt(1)
	v_cndmask_b32_e32 v146, v218, v149, vcc
	s_waitcnt lgkmcnt(0)
	v_cndmask_b32_e32 v147, v220, v157, vcc
	v_pk_fma_f32 v[150:151], v[72:73], v[150:151], v[76:77]
	v_pk_fma_f32 v[152:153], v[66:67], v[152:153], v[154:155]
	v_pk_fma_f32 v[146:147], v[64:65], v[146:147], v[150:151]
	v_pk_fma_f32 v[142:143], v[70:71], v[142:143], v[152:153]
	v_pk_fma_f32 v[140:141], v[68:69], v[140:141], v[146:147]
	v_pk_mul_f32 v[146:147], v[142:143], v[142:143]
	v_pk_mul_f32 v[150:151], v[140:141], v[140:141]
	v_fmamk_f32 v146, v146, 0xbdd2d3e8, v216
	v_mul_f32_e32 v146, v142, v146
	v_fmamk_f32 v150, v150, 0xbdd2d3e8, v216
	v_fmamk_f32 v151, v151, 0xbdd2d3e8, v216
	v_exp_f32_e32 v152, v146
	v_fmamk_f32 v146, v147, 0xbdd2d3e8, v216
	v_mul_f32_e32 v150, v140, v150
	v_mul_f32_e32 v151, v141, v151
	v_mul_f32_e32 v146, v143, v146
	v_exp_f32_e32 v150, v150
	v_exp_f32_e32 v151, v151
	v_exp_f32_e32 v153, v146
	v_pk_mul_f32 v[138:139], v[138:139], v[148:149] op_sel_hi:[1,0]
	v_add_f32_e32 v146, 1.0, v150
	v_add_f32_e32 v147, 1.0, v151
	v_add_f32_e32 v150, 1.0, v152
	v_add_f32_e32 v151, 1.0, v153
	v_pk_mul_f32 v[136:137], v[136:137], v[148:149] op_sel_hi:[1,0]
	s_nop 1
	v_mov_b32_dpp v205, v138 row_ror:2 row_mask:0xf bank_mask:0xf
	v_mov_b32_dpp v218, v139 row_ror:2 row_mask:0xf bank_mask:0xf
	v_rcp_f32_e32 v150, v150
	v_rcp_f32_e32 v151, v151
	s_nop 1
	v_mov_b32_dpp v153, v136 row_ror:2 row_mask:0xf bank_mask:0xf
	v_mov_b32_dpp v155, v137 row_ror:2 row_mask:0xf bank_mask:0xf
	v_mov_b32_dpp v204, v138 row_ror:1 row_mask:0xf bank_mask:0xf
	v_mov_b32_dpp v217, v139 row_ror:1 row_mask:0xf bank_mask:0xf
	v_rcp_f32_e32 v146, v146
	v_rcp_f32_e32 v147, v147
	s_nop 1
	v_mov_b32_dpp v152, v136 row_ror:1 row_mask:0xf bank_mask:0xf
	v_mov_b32_dpp v154, v137 row_ror:1 row_mask:0xf bank_mask:0xf
	v_pk_mul_f32 v[134:135], v[134:135], v[148:149] op_sel_hi:[1,0]
	v_pk_mul_f32 v[142:143], v[142:143], v[150:151]
	s_waitcnt lgkmcnt(7)
	v_cndmask_b32_e64 v150, v200, v205, s[0:1]
	s_waitcnt lgkmcnt(6)
	v_cndmask_b32_e64 v151, v201, v218, s[0:1]
	v_pk_mul_f32 v[132:133], v[132:133], v[148:149] op_sel_hi:[1,0]
	v_pk_mul_f32 v[140:141], v[140:141], v[146:147]
	v_pk_mul_f32 v[134:135], v[134:135], v[142:143]
	s_waitcnt lgkmcnt(5)
	v_cndmask_b32_e64 v142, v198, v153, s[0:1]
	s_waitcnt lgkmcnt(4)
	v_cndmask_b32_e64 v143, v199, v155, s[0:1]
	s_waitcnt lgkmcnt(3)
	v_cndmask_b32_e32 v146, v196, v204, vcc
	s_waitcnt lgkmcnt(2)
	v_cndmask_b32_e32 v147, v197, v217, vcc
	v_pk_fma_f32 v[150:151], v[94:95], v[150:151], v[98:99]
	v_pk_mul_f32 v[132:133], v[132:133], v[140:141]
	s_waitcnt lgkmcnt(1)
	v_cndmask_b32_e32 v140, v194, v152, vcc
	s_waitcnt lgkmcnt(0)
	v_cndmask_b32_e32 v141, v195, v154, vcc
	v_pk_fma_f32 v[142:143], v[92:93], v[142:143], v[96:97]
	v_pk_fma_f32 v[146:147], v[86:87], v[146:147], v[150:151]
	v_pk_fma_f32 v[140:141], v[84:85], v[140:141], v[142:143]
	v_pk_fma_f32 v[138:139], v[90:91], v[138:139], v[146:147]
	v_pk_fma_f32 v[136:137], v[88:89], v[136:137], v[140:141]
	v_pk_mul_f32 v[140:141], v[138:139], v[138:139]
	v_pk_mul_f32 v[142:143], v[136:137], v[136:137]
	v_fmamk_f32 v140, v140, 0xbdd2d3e8, v216
	v_fmamk_f32 v142, v142, 0xbdd2d3e8, v216
	v_fmamk_f32 v143, v143, 0xbdd2d3e8, v216
	v_mul_f32_e32 v140, v138, v140
	v_mul_f32_e32 v142, v136, v142
	v_mul_f32_e32 v143, v137, v143
	v_exp_f32_e32 v146, v140
	v_fmamk_f32 v140, v141, 0xbdd2d3e8, v216
	v_exp_f32_e32 v142, v142
	v_exp_f32_e32 v143, v143
	v_mul_f32_e32 v140, v139, v140
	v_exp_f32_e32 v147, v140
	v_add_f32_e32 v140, 1.0, v142
	v_add_f32_e32 v141, 1.0, v143
	v_rcp_f32_e32 v140, v140
	v_rcp_f32_e32 v141, v141
	v_add_f32_e32 v142, 1.0, v146
	v_add_f32_e32 v143, 1.0, v147
	v_rcp_f32_e32 v142, v142
	v_rcp_f32_e32 v143, v143
	v_pk_mul_f32 v[128:129], v[128:129], v[148:149] op_sel_hi:[1,0]
	v_pk_mul_f32 v[136:137], v[136:137], v[140:141]
	v_pk_mul_f32 v[130:131], v[130:131], v[148:149] op_sel_hi:[1,0]
	v_pk_mul_f32 v[138:139], v[138:139], v[142:143]
	v_pk_mul_f32 v[128:129], v[128:129], v[136:137]
	v_pk_mul_f32 v[138:139], v[130:131], v[138:139]
	v_cvt_pk_bf16_f32 v130, v132, v133
	v_cvt_pk_bf16_f32 v131, v134, v135
	v_cvt_pk_bf16_f32 v132, v128, v129
	v_fmamk_f32 v128, v193, 0x3a000000, v215
	v_cvt_pk_bf16_f32 v133, v138, v139
	v_rsq_f32_e32 v138, v128
	v_mov_b64_e32 v[136:137], s[10:11]
	v_mad_i64_i32 v[134:135], s[12:13], v190, s66, v[136:137]
	v_lshlrev_b64 v[128:129], 1, v[174:175]
	v_lshl_add_u64 v[134:135], v[134:135], 0, v[128:129]
	v_pk_mul_f32 v[140:141], v[124:125], v[138:139] op_sel_hi:[1,0]
	global_store_dwordx4 v[134:135], v[130:133], off
	v_pk_mul_f32 v[134:135], v[126:127], v[138:139] op_sel_hi:[1,0]
	s_nop 1
	v_mov_b32_dpp v125, v140 row_ror:2 row_mask:0xf bank_mask:0xf
	v_mov_b32_dpp v127, v141 row_ror:2 row_mask:0xf bank_mask:0xf
	v_mov_b32_dpp v124, v140 row_ror:1 row_mask:0xf bank_mask:0xf
	v_mov_b32_dpp v126, v141 row_ror:1 row_mask:0xf bank_mask:0xf
	v_mov_b32_dpp v131, v134 row_ror:2 row_mask:0xf bank_mask:0xf
	v_mov_b32_dpp v133, v135 row_ror:2 row_mask:0xf bank_mask:0xf
	v_mov_b32_dpp v130, v134 row_ror:1 row_mask:0xf bank_mask:0xf
	v_mov_b32_dpp v132, v135 row_ror:1 row_mask:0xf bank_mask:0xf
	s_waitcnt lgkmcnt(7)
; __device__ __forceinline__ unsigned cvt_pk_bf16(float lo, float hi) { unsigned r; asm volatile("v_cvt_pk_bf16_f32 %0, %1, %2" : "=v"(r) : "v"(lo), "v"(hi)); return r; }
;     __device__ __forceinline__ void operator()(EPI_ARGS) const {
;     ...
;             for (int m = 0; m < 4; ++m) {
;                 const int row = ROW_OF(ai, m);
;                 const float rs = __builtin_amdgcn_rsqf(rsv[ai][m] * (1.0f / D) + EPS);
;                 f32x4 o[2];
; #pragma unroll
;                 for (int n = 0; n < 2; ++n) {
;                     const f32x4 gv = acc[ai][0][m][n] * rs, vv = acc[ai][1][m][n] * rs;
;                     f32x4 r1, r2;
; #pragma unroll
;                     for (int j = 0; j < 4; ++j) { r1[j] = __shfl(gv[j], src1); r2[j] = __shfl(gv[j], src2); }
;                     f32x4 p1, p2;
; #pragma unroll
;                     for (int j = 0; j < 4; ++j) { p1[j] = fr >= 1 ? r1[j] : q1[n][j]; p2[j] = fr >= 2 ? r2[j] : q2[n][j]; }
;                     q1[n] = r1; q2[n] = r2;
;                     const f32x4 cv = bb[n] + w0[n] * p2 + w1[n] * p1 + w2[n] * gv;
;                     o[n] = gelu4(cv) * vv;
;                     if (m == 0 && fr < 2) { const size_t so = ((size_t)blk * 2 + fr) * FF + f0 + 4 * n; *(f32x4*)(headg + so) = gv; *(f32x4*)(headv + so) = vv; }
;                     if (m == 3 && fr >= 14) { const size_t so = ((size_t)blk * 2 + (fr - 14)) * FF + f0 + 4 * n; *(f32x4*)(tailg + so) = gv; }
;                 }
;                 if (!(m == 0 && fr < 2)) {
;                     u32x4 w; w.x = cvt_pk_bf16(o[0][0], o[0][1]); w.y = cvt_pk_bf16(o[0][2], o[0][3]); w.z = cvt_pk_bf16(o[1][0], o[1][1]); w.w = cvt_pk_bf16(o[1][2], o[1][3]);
;                     *(u32x4*)(act + (size_t)row * FF + f0) = w;
	v_cndmask_b32_e64 v146, v156, v125, s[0:1]
	s_waitcnt lgkmcnt(6)
	v_cndmask_b32_e64 v147, v158, v127, s[0:1]
	s_waitcnt lgkmcnt(5)
	v_cndmask_b32_e32 v142, v149, v124, vcc
	s_waitcnt lgkmcnt(4)
	v_cndmask_b32_e32 v143, v157, v126, vcc
	s_waitcnt lgkmcnt(3)
	v_cndmask_b32_e64 v150, v192, v131, s[0:1]
	s_waitcnt lgkmcnt(2)
	v_cndmask_b32_e64 v151, v203, v133, s[0:1]
	v_pk_fma_f32 v[146:147], v[72:73], v[146:147], v[76:77]
	s_waitcnt lgkmcnt(1)
	v_cndmask_b32_e32 v148, v159, v130, vcc
	s_waitcnt lgkmcnt(0)
	v_cndmask_b32_e32 v149, v202, v132, vcc
	v_pk_fma_f32 v[150:151], v[74:75], v[150:151], v[78:79]
	v_pk_fma_f32 v[142:143], v[64:65], v[142:143], v[146:147]
	v_pk_fma_f32 v[148:149], v[66:67], v[148:149], v[150:151]
	v_pk_fma_f32 v[140:141], v[68:69], v[140:141], v[142:143]
	v_pk_fma_f32 v[134:135], v[70:71], v[134:135], v[148:149]
	v_pk_mul_f32 v[146:147], v[140:141], v[140:141]
	v_pk_mul_f32 v[142:143], v[134:135], v[134:135]
	v_fmamk_f32 v139, v146, 0xbdd2d3e8, v216
	v_mul_f32_e32 v139, v140, v139
	v_fmamk_f32 v146, v147, 0xbdd2d3e8, v216
	v_fmamk_f32 v142, v142, 0xbdd2d3e8, v216
	v_exp_f32_e32 v139, v139
	v_mul_f32_e32 v146, v141, v146
	v_mul_f32_e32 v142, v134, v142
	v_exp_f32_e32 v146, v146
	v_exp_f32_e32 v147, v142
	v_fmamk_f32 v142, v143, 0xbdd2d3e8, v216
	v_mul_f32_e32 v142, v135, v142
	v_exp_f32_e32 v148, v142
	v_add_f32_e32 v139, 1.0, v139
	v_rcp_f32_e32 v142, v139
	v_add_f32_e32 v139, 1.0, v146
	v_rcp_f32_e32 v143, v139
	v_add_f32_e32 v139, 1.0, v147
	v_rcp_f32_e32 v146, v139
	v_add_f32_e32 v139, 1.0, v148
	v_rcp_f32_e32 v147, v139
	v_pk_mul_f32 v[116:117], v[116:117], v[138:139] op_sel_hi:[1,0]
	v_pk_mul_f32 v[118:119], v[118:119], v[138:139] op_sel_hi:[1,0]
	v_pk_mul_f32 v[140:141], v[140:141], v[142:143]
	v_pk_mul_f32 v[134:135], v[134:135], v[146:147]
	v_pk_mul_f32 v[146:147], v[120:121], v[138:139] op_sel_hi:[1,0]
	v_pk_mul_f32 v[142:143], v[118:119], v[134:135]
	v_pk_mul_f32 v[116:117], v[116:117], v[140:141]
	v_pk_mul_f32 v[140:141], v[122:123], v[138:139] op_sel_hi:[1,0]
	s_nop 1
	v_mov_b32_dpp v119, v146 row_ror:2 row_mask:0xf bank_mask:0xf
	v_mov_b32_dpp v121, v147 row_ror:2 row_mask:0xf bank_mask:0xf
	v_mov_b32_dpp v118, v146 row_ror:1 row_mask:0xf bank_mask:0xf
	v_mov_b32_dpp v120, v147 row_ror:1 row_mask:0xf bank_mask:0xf
	v_mov_b32_dpp v123, v140 row_ror:2 row_mask:0xf bank_mask:0xf
	v_mov_b32_dpp v135, v141 row_ror:2 row_mask:0xf bank_mask:0xf
	v_mov_b32_dpp v122, v140 row_ror:1 row_mask:0xf bank_mask:0xf
	v_mov_b32_dpp v134, v141 row_ror:1 row_mask:0xf bank_mask:0xf
	s_waitcnt lgkmcnt(7)
	v_cndmask_b32_e64 v150, v153, v119, s[0:1]
	s_waitcnt lgkmcnt(6)
	v_cndmask_b32_e64 v151, v155, v121, s[0:1]
	s_waitcnt lgkmcnt(5)
	v_cndmask_b32_e32 v148, v152, v118, vcc
	s_waitcnt lgkmcnt(4)
	v_cndmask_b32_e32 v149, v154, v120, vcc
	s_waitcnt lgkmcnt(3)
	v_cndmask_b32_e64 v154, v205, v123, s[0:1]
	s_waitcnt lgkmcnt(2)
	v_cndmask_b32_e64 v155, v218, v135, s[0:1]
	v_pk_fma_f32 v[150:151], v[92:93], v[150:151], v[96:97]
	s_waitcnt lgkmcnt(1)
	v_cndmask_b32_e32 v152, v204, v122, vcc
	s_waitcnt lgkmcnt(0)
	v_cndmask_b32_e32 v153, v217, v134, vcc
	v_pk_fma_f32 v[154:155], v[94:95], v[154:155], v[98:99]
	v_pk_fma_f32 v[148:149], v[84:85], v[148:149], v[150:151]
	v_pk_fma_f32 v[152:153], v[86:87], v[152:153], v[154:155]
	v_pk_fma_f32 v[146:147], v[88:89], v[146:147], v[148:149]
	v_pk_fma_f32 v[140:141], v[90:91], v[140:141], v[152:153]
	v_pk_mul_f32 v[150:151], v[146:147], v[146:147]
	v_pk_mul_f32 v[148:149], v[140:141], v[140:141]
	v_fmamk_f32 v139, v150, 0xbdd2d3e8, v216
	v_mul_f32_e32 v139, v146, v139
	v_fmamk_f32 v150, v151, 0xbdd2d3e8, v216
	v_fmamk_f32 v148, v148, 0xbdd2d3e8, v216
	v_exp_f32_e32 v139, v139
	v_mul_f32_e32 v150, v147, v150
	v_mul_f32_e32 v148, v140, v148
	v_exp_f32_e32 v150, v150
	v_exp_f32_e32 v151, v148
	v_fmamk_f32 v148, v149, 0xbdd2d3e8, v216
	v_mul_f32_e32 v148, v141, v148
	v_exp_f32_e32 v152, v148
	v_add_f32_e32 v139, 1.0, v139
	v_rcp_f32_e32 v148, v139
	v_add_f32_e32 v139, 1.0, v150
	v_rcp_f32_e32 v149, v139
	v_add_f32_e32 v139, 1.0, v151
	v_rcp_f32_e32 v150, v139
	v_add_f32_e32 v139, 1.0, v152
	v_rcp_f32_e32 v151, v139
	v_pk_mul_f32 v[112:113], v[112:113], v[138:139] op_sel_hi:[1,0]
	v_pk_mul_f32 v[114:115], v[114:115], v[138:139] op_sel_hi:[1,0]
	v_pk_mul_f32 v[138:139], v[146:147], v[148:149]
	v_pk_mul_f32 v[140:141], v[140:141], v[150:151]
	v_pk_mul_f32 v[112:113], v[112:113], v[138:139]
	v_pk_mul_f32 v[140:141], v[114:115], v[140:141]
	v_cvt_pk_bf16_f32 v114, v116, v117
	v_cvt_pk_bf16_f32 v115, v142, v143
	v_cvt_pk_bf16_f32 v116, v112, v113
	v_fmamk_f32 v112, v191, 0x3a000000, v215
	v_rsq_f32_e32 v112, v112
	v_cvt_pk_bf16_f32 v117, v140, v141
	v_mad_i64_i32 v[146:147], s[12:13], v188, s66, v[136:137]
	v_pk_mul_f32 v[110:111], v[110:111], v[112:113] op_sel_hi:[1,0]
	v_pk_mul_f32 v[108:109], v[108:109], v[112:113] op_sel_hi:[1,0]
	s_nop 1
	v_mov_b32_dpp v136, v108 row_ror:1 row_mask:0xf bank_mask:0xf
	v_mov_b32_dpp v137, v108 row_ror:2 row_mask:0xf bank_mask:0xf
	v_mov_b32_dpp v138, v109 row_ror:1 row_mask:0xf bank_mask:0xf
	v_mov_b32_dpp v139, v109 row_ror:2 row_mask:0xf bank_mask:0xf
	v_mov_b32_dpp v140, v110 row_ror:1 row_mask:0xf bank_mask:0xf
	v_mov_b32_dpp v141, v110 row_ror:2 row_mask:0xf bank_mask:0xf
	v_mov_b32_dpp v142, v111 row_ror:1 row_mask:0xf bank_mask:0xf
	v_mov_b32_dpp v143, v111 row_ror:2 row_mask:0xf bank_mask:0xf
	v_lshl_add_u64 v[146:147], v[146:147], 0, v[128:129]
	global_store_dwordx4 v[146:147], v[114:117], off
	v_cmp_lt_i32_e64 s[4:5], 13, v184
	s_nop 0
	v_lshl_add_u64 v[114:115], s[40:41], 0, v[144:145]
	v_lshl_add_u64 v[116:117], v[174:175], 2, v[114:115]
	s_and_saveexec_b64 s[12:13], s[4:5]
	s_cbranch_execz .LBB0_934
	global_store_dwordx4 v[116:117], v[108:111], off
; __device__ __forceinline__ unsigned cvt_pk_bf16(float lo, float hi) { unsigned r; asm volatile("v_cvt_pk_bf16_f32 %0, %1, %2" : "=v"(r) : "v"(lo), "v"(hi)); return r; }
;     __device__ __forceinline__ void operator()(EPI_ARGS) const {
;     ...
;             for (int m = 0; m < 4; ++m) {
;                 const int row = ROW_OF(ai, m);
;                 const float rs = __builtin_amdgcn_rsqf(rsv[ai][m] * (1.0f / D) + EPS);
;                 f32x4 o[2];
; #pragma unroll
;                 for (int n = 0; n < 2; ++n) {
;                     const f32x4 gv = acc[ai][0][m][n] * rs, vv = acc[ai][1][m][n] * rs;
;                     f32x4 r1, r2;
; #pragma unroll
;                     for (int j = 0; j < 4; ++j) { r1[j] = __shfl(gv[j], src1); r2[j] = __shfl(gv[j], src2); }
;                     f32x4 p1, p2;
; #pragma unroll
;                     for (int j = 0; j < 4; ++j) { p1[j] = fr >= 1 ? r1[j] : q1[n][j]; p2[j] = fr >= 2 ? r2[j] : q2[n][j]; }
;                     q1[n] = r1; q2[n] = r2;
;                     const f32x4 cv = bb[n] + w0[n] * p2 + w1[n] * p1 + w2[n] * gv;
;                     o[n] = gelu4(cv) * vv;
;                     if (m == 0 && fr < 2) { const size_t so = ((size_t)blk * 2 + fr) * FF + f0 + 4 * n; *(f32x4*)(headg + so) = gv; *(f32x4*)(headv + so) = vv; }
;                     if (m == 3 && fr >= 14) { const size_t so = ((size_t)blk * 2 + (fr - 14)) * FF + f0 + 4 * n; *(f32x4*)(tailg + so) = gv; }
;                 }
;                 if (!(m == 0 && fr < 2)) {
;                     u32x4 w; w.x = cvt_pk_bf16(o[0][0], o[0][1]); w.y = cvt_pk_bf16(o[0][2], o[0][3]); w.z = cvt_pk_bf16(o[1][0], o[1][1]); w.w = cvt_pk_bf16(o[1][2], o[1][3]);
;                     *(u32x4*)(act + (size_t)row * FF + f0) = w;
.LBB0_934:
	s_or_b64 exec, exec, s[12:13]
	v_mov_b32_e32 v113, v112
	v_mov_b32_e32 v114, v112
	v_mov_b32_e32 v115, v112
	v_pk_mul_f32 v[106:107], v[106:107], v[114:115]
	v_pk_mul_f32 v[104:105], v[104:105], v[112:113]
	s_nop 1
	v_mov_b32_dpp v144, v104 row_ror:1 row_mask:0xf bank_mask:0xf
	v_mov_b32_dpp v145, v104 row_ror:2 row_mask:0xf bank_mask:0xf
	v_mov_b32_dpp v146, v105 row_ror:1 row_mask:0xf bank_mask:0xf
	v_mov_b32_dpp v147, v105 row_ror:2 row_mask:0xf bank_mask:0xf
	v_mov_b32_dpp v148, v106 row_ror:1 row_mask:0xf bank_mask:0xf
	v_mov_b32_dpp v149, v106 row_ror:2 row_mask:0xf bank_mask:0xf
	v_mov_b32_dpp v150, v107 row_ror:1 row_mask:0xf bank_mask:0xf
	v_mov_b32_dpp v151, v107 row_ror:2 row_mask:0xf bank_mask:0xf
	s_and_saveexec_b64 s[12:13], s[4:5]
	s_cbranch_execz .LBB0_936
	global_store_dwordx4 v[116:117], v[104:107], off offset:16
.LBB0_936:
	s_or_b64 exec, exec, s[12:13]
	s_waitcnt lgkmcnt(5)
	v_cndmask_b32_e32 v117, v120, v146, vcc
	s_waitcnt lgkmcnt(3)
	v_cndmask_b32_e32 v120, v122, v148, vcc
	s_waitcnt lgkmcnt(2)
	v_cndmask_b32_e64 v122, v123, v149, s[0:1]
	s_waitcnt lgkmcnt(0)
	v_cndmask_b32_e64 v123, v135, v151, s[0:1]
	v_cndmask_b32_e32 v116, v118, v144, vcc
	v_cndmask_b32_e64 v118, v119, v145, s[0:1]
	v_cndmask_b32_e64 v119, v121, v147, s[0:1]
	v_cndmask_b32_e32 v121, v134, v150, vcc
	v_pk_fma_f32 v[122:123], v[94:95], v[122:123], v[98:99]
	v_pk_fma_f32 v[118:119], v[92:93], v[118:119], v[96:97]
	v_pk_fma_f32 v[120:121], v[86:87], v[120:121], v[122:123]
	v_pk_fma_f32 v[116:117], v[84:85], v[116:117], v[118:119]
	v_pk_fma_f32 v[106:107], v[90:91], v[106:107], v[120:121]
	v_pk_fma_f32 v[104:105], v[88:89], v[104:105], v[116:117]
	v_pk_mul_f32 v[116:117], v[106:107], v[106:107]
	v_pk_mul_f32 v[118:119], v[104:105], v[104:105]
	v_fmamk_f32 v116, v116, 0xbdd2d3e8, v216
	v_mul_f32_e32 v116, v106, v116
	v_fmamk_f32 v118, v118, 0xbdd2d3e8, v216
	v_fmamk_f32 v119, v119, 0xbdd2d3e8, v216
	v_exp_f32_e32 v120, v116
	v_fmamk_f32 v116, v117, 0xbdd2d3e8, v216
	v_mul_f32_e32 v118, v104, v118
	v_mul_f32_e32 v119, v105, v119
	v_mul_f32_e32 v116, v107, v116
	v_exp_f32_e32 v118, v118
	v_exp_f32_e32 v119, v119
	v_exp_f32_e32 v121, v116
	v_pk_mul_f32 v[102:103], v[102:103], v[114:115]
	v_add_f32_e32 v116, 1.0, v118
	v_add_f32_e32 v117, 1.0, v119
	v_add_f32_e32 v118, 1.0, v120
	v_add_f32_e32 v119, 1.0, v121
	v_rcp_f32_e32 v118, v118
	v_rcp_f32_e32 v119, v119
	v_rcp_f32_e32 v116, v116
	v_rcp_f32_e32 v117, v117
	v_pk_mul_f32 v[100:101], v[100:101], v[112:113]
	v_pk_mul_f32 v[106:107], v[106:107], v[118:119]
	v_cndmask_b32_e64 v118, v131, v141, s[0:1]
	v_cndmask_b32_e64 v119, v133, v143, s[0:1]
	v_pk_mul_f32 v[104:105], v[104:105], v[116:117]
	v_pk_mul_f32 v[102:103], v[102:103], v[106:107]
	v_cndmask_b32_e64 v106, v125, v137, s[0:1]
	v_cndmask_b32_e64 v107, v127, v139, s[0:1]
	v_cndmask_b32_e32 v116, v130, v140, vcc
	v_cndmask_b32_e32 v117, v132, v142, vcc
	v_pk_fma_f32 v[118:119], v[74:75], v[118:119], v[78:79]
	v_pk_mul_f32 v[100:101], v[100:101], v[104:105]
	v_cndmask_b32_e32 v104, v124, v136, vcc
	v_cndmask_b32_e32 v105, v126, v138, vcc
	v_pk_fma_f32 v[106:107], v[72:73], v[106:107], v[76:77]
	v_pk_fma_f32 v[116:117], v[66:67], v[116:117], v[118:119]
	v_pk_fma_f32 v[104:105], v[64:65], v[104:105], v[106:107]
	v_pk_fma_f32 v[106:107], v[70:71], v[110:111], v[116:117]
	v_pk_fma_f32 v[104:105], v[68:69], v[108:109], v[104:105]
	v_pk_mul_f32 v[108:109], v[106:107], v[106:107]
	v_pk_mul_f32 v[110:111], v[104:105], v[104:105]
	v_fmamk_f32 v108, v108, 0xbdd2d3e8, v216
	v_mul_f32_e32 v108, v106, v108
	v_fmamk_f32 v110, v110, 0xbdd2d3e8, v216
	v_fmamk_f32 v111, v111, 0xbdd2d3e8, v216
	v_exp_f32_e32 v116, v108
	v_fmamk_f32 v108, v109, 0xbdd2d3e8, v216
	v_mul_f32_e32 v110, v104, v110
	v_mul_f32_e32 v111, v105, v111
	v_mul_f32_e32 v108, v107, v108
	v_exp_f32_e32 v110, v110
	v_exp_f32_e32 v111, v111
	v_exp_f32_e32 v117, v108
	v_pk_mul_f32 v[82:83], v[82:83], v[114:115]
	v_add_f32_e32 v108, 1.0, v110
	v_add_f32_e32 v109, 1.0, v111
	v_add_f32_e32 v110, 1.0, v116
	v_add_f32_e32 v111, 1.0, v117
	v_rcp_f32_e32 v108, v108
	v_rcp_f32_e32 v109, v109
	v_rcp_f32_e32 v110, v110
	v_rcp_f32_e32 v111, v111
	v_pk_mul_f32 v[80:81], v[80:81], v[112:113]
	v_pk_mul_f32 v[104:105], v[104:105], v[108:109]
	v_pk_mul_f32 v[106:107], v[106:107], v[110:111]
	s_nop 0
	v_pk_mul_f32 v[82:83], v[82:83], v[106:107]
	v_pk_mul_f32 v[80:81], v[80:81], v[104:105]
	s_nop 0
	v_cvt_pk_bf16_f32 v80, v80, v81
	v_cvt_pk_bf16_f32 v81, v82, v83
	v_cvt_pk_bf16_f32 v82, v100, v101
	v_mov_b64_e32 v[100:101], s[10:11]
	v_mad_i64_i32 v[100:101], s[12:13], v186, s66, v[100:101]
	v_lshl_add_u64 v[100:101], v[174:175], 1, v[100:101]
	v_cvt_pk_bf16_f32 v83, v102, v103
	global_store_dwordx4 v[100:101], v[80:83], off
	s_add_i32 s12, s60, 2
	s_ashr_i32 s13, s12, 31
	v_fmamk_f32 v80, v189, 0x3a000000, v215
	v_rsq_f32_e32 v106, v80
	s_lshl_b64 s[60:61], s[12:13], 1
	v_lshl_add_u64 v[80:81], s[60:61], 0, v[184:185]
	v_mad_u64_u32 v[82:83], s[12:13], v80, s65, v[174:175]
	v_pk_mul_f32 v[62:63], v[62:63], v[106:107] op_sel_hi:[1,0]
	v_pk_mul_f32 v[60:61], v[60:61], v[106:107] op_sel_hi:[1,0]
	s_nop 1
	v_mov_b32_dpp v108, v60 row_ror:1 row_mask:0xf bank_mask:0xf
	v_mov_b32_dpp v109, v60 row_ror:2 row_mask:0xf bank_mask:0xf
	v_mov_b32_dpp v110, v61 row_ror:1 row_mask:0xf bank_mask:0xf
	v_mov_b32_dpp v111, v61 row_ror:2 row_mask:0xf bank_mask:0xf
	v_mov_b32_dpp v112, v62 row_ror:1 row_mask:0xf bank_mask:0xf
	v_mov_b32_dpp v113, v62 row_ror:2 row_mask:0xf bank_mask:0xf
	v_mov_b32_dpp v114, v63 row_ror:1 row_mask:0xf bank_mask:0xf
	v_mov_b32_dpp v115, v63 row_ror:2 row_mask:0xf bank_mask:0xf
	v_mad_i32_i24 v83, v81, s65, v83
	v_pk_mul_f32 v[54:55], v[54:55], v[106:107] op_sel_hi:[1,0]
	v_pk_mul_f32 v[52:53], v[52:53], v[106:107] op_sel_hi:[1,0]
	v_lshlrev_b64 v[104:105], 2, v[82:83]
	s_and_saveexec_b64 s[12:13], s[8:9]
	s_cbranch_execz .LBB0_938
	v_lshl_add_u64 v[82:83], s[24:25], 0, v[104:105]
	v_lshl_add_u64 v[80:81], s[38:39], 0, v[104:105]
	global_store_dwordx4 v[82:83], v[60:63], off
	global_store_dwordx4 v[80:81], v[52:55], off
; __device__ __forceinline__ unsigned cvt_pk_bf16(float lo, float hi) { unsigned r; asm volatile("v_cvt_pk_bf16_f32 %0, %1, %2" : "=v"(r) : "v"(lo), "v"(hi)); return r; }
;     __device__ __forceinline__ void operator()(EPI_ARGS) const {
;     ...
;             for (int m = 0; m < 4; ++m) {
;                 const int row = ROW_OF(ai, m);
;                 const float rs = __builtin_amdgcn_rsqf(rsv[ai][m] * (1.0f / D) + EPS);
;                 f32x4 o[2];
; #pragma unroll
;                 for (int n = 0; n < 2; ++n) {
;                     const f32x4 gv = acc[ai][0][m][n] * rs, vv = acc[ai][1][m][n] * rs;
;                     f32x4 r1, r2;
; #pragma unroll
;                     for (int j = 0; j < 4; ++j) { r1[j] = __shfl(gv[j], src1); r2[j] = __shfl(gv[j], src2); }
;                     f32x4 p1, p2;
; #pragma unroll
;                     for (int j = 0; j < 4; ++j) { p1[j] = fr >= 1 ? r1[j] : q1[n][j]; p2[j] = fr >= 2 ? r2[j] : q2[n][j]; }
;                     q1[n] = r1; q2[n] = r2;
;                     const f32x4 cv = bb[n] + w0[n] * p2 + w1[n] * p1 + w2[n] * gv;
;                     o[n] = gelu4(cv) * vv;
;                     if (m == 0 && fr < 2) { const size_t so = ((size_t)blk * 2 + fr) * FF + f0 + 4 * n; *(f32x4*)(headg + so) = gv; *(f32x4*)(headv + so) = vv; }
;                     if (m == 3 && fr >= 14) { const size_t so = ((size_t)blk * 2 + (fr - 14)) * FF + f0 + 4 * n; *(f32x4*)(tailg + so) = gv; }
;                 }
;                 if (!(m == 0 && fr < 2)) {
;                     u32x4 w; w.x = cvt_pk_bf16(o[0][0], o[0][1]); w.y = cvt_pk_bf16(o[0][2], o[0][3]); w.z = cvt_pk_bf16(o[1][0], o[1][1]); w.w = cvt_pk_bf16(o[1][2], o[1][3]);
;                     *(u32x4*)(act + (size_t)row * FF + f0) = w;
.LBB0_938:
	s_or_b64 exec, exec, s[12:13]
	v_mov_b32_e32 v107, v106
	v_mov_b32_e32 v116, v106
	v_mov_b32_e32 v117, v106
	v_pk_mul_f32 v[58:59], v[58:59], v[116:117]
	v_pk_mul_f32 v[56:57], v[56:57], v[106:107]
	s_nop 1
	v_mov_b32_dpp v80, v56 row_ror:1 row_mask:0xf bank_mask:0xf
	v_mov_b32_dpp v100, v56 row_ror:2 row_mask:0xf bank_mask:0xf
	v_mov_b32_dpp v81, v57 row_ror:1 row_mask:0xf bank_mask:0xf
	v_mov_b32_dpp v101, v57 row_ror:2 row_mask:0xf bank_mask:0xf
	v_mov_b32_dpp v82, v58 row_ror:1 row_mask:0xf bank_mask:0xf
	v_mov_b32_dpp v102, v58 row_ror:2 row_mask:0xf bank_mask:0xf
	v_mov_b32_dpp v83, v59 row_ror:1 row_mask:0xf bank_mask:0xf
	v_mov_b32_dpp v103, v59 row_ror:2 row_mask:0xf bank_mask:0xf
	v_pk_mul_f32 v[50:51], v[50:51], v[116:117]
	v_pk_mul_f32 v[48:49], v[48:49], v[106:107]
	s_and_saveexec_b64 s[8:9], s[6:7]
	s_xor_b64 s[6:7], exec, s[8:9]
	s_cbranch_execz .LBB0_940
	s_waitcnt lgkmcnt(10)
	v_cndmask_b32_e64 v118, 0, v113, s[0:1]
	s_waitcnt lgkmcnt(8)
	v_cndmask_b32_e64 v119, 0, v115, s[0:1]
	v_cndmask_b32_e64 v106, 0, v109, s[0:1]
	v_cndmask_b32_e64 v107, 0, v111, s[0:1]
	v_cndmask_b32_e32 v116, 0, v112, vcc
	v_cndmask_b32_e32 v117, 0, v114, vcc
	v_pk_fma_f32 v[118:119], v[74:75], v[118:119], v[78:79]
	v_cndmask_b32_e32 v104, 0, v108, vcc
	v_cndmask_b32_e32 v105, 0, v110, vcc
	v_pk_fma_f32 v[106:107], v[72:73], v[106:107], v[76:77]
	v_pk_fma_f32 v[116:117], v[66:67], v[116:117], v[118:119]
	v_pk_fma_f32 v[104:105], v[64:65], v[104:105], v[106:107]
	v_pk_fma_f32 v[62:63], v[70:71], v[62:63], v[116:117]
	v_pk_fma_f32 v[60:61], v[68:69], v[60:61], v[104:105]
	v_pk_mul_f32 v[104:105], v[62:63], v[62:63]
	v_pk_mul_f32 v[106:107], v[60:61], v[60:61]
	v_fmamk_f32 v104, v104, 0xbdd2d3e8, v216
	v_mul_f32_e32 v104, v62, v104
	v_fmamk_f32 v106, v106, 0xbdd2d3e8, v216
	v_fmamk_f32 v107, v107, 0xbdd2d3e8, v216
	v_exp_f32_e32 v116, v104
	v_fmamk_f32 v104, v105, 0xbdd2d3e8, v216
	v_mul_f32_e32 v106, v60, v106
	v_mul_f32_e32 v107, v61, v107
	v_mul_f32_e32 v104, v63, v104
	v_exp_f32_e32 v106, v106
	v_exp_f32_e32 v107, v107
	v_exp_f32_e32 v117, v104
	v_add_f32_e32 v104, 1.0, v106
	v_add_f32_e32 v105, 1.0, v107
	v_add_f32_e32 v106, 1.0, v116
	v_add_f32_e32 v107, 1.0, v117
	v_rcp_f32_e32 v104, v104
	v_rcp_f32_e32 v105, v105
	v_rcp_f32_e32 v106, v106
	v_rcp_f32_e32 v107, v107
	v_pk_mul_f32 v[60:61], v[60:61], v[104:105]
	s_waitcnt lgkmcnt(0)
	v_pk_fma_f32 v[104:105], v[94:95], v[102:103], v[98:99]
	v_pk_mul_f32 v[62:63], v[62:63], v[106:107]
	v_pk_fma_f32 v[106:107], v[92:93], v[100:101], v[96:97]
	v_pk_fma_f32 v[104:105], v[86:87], v[82:83], v[104:105]
	v_pk_fma_f32 v[106:107], v[84:85], v[80:81], v[106:107]
	v_pk_fma_f32 v[58:59], v[90:91], v[58:59], v[104:105]
	v_pk_fma_f32 v[56:57], v[88:89], v[56:57], v[106:107]
	v_pk_mul_f32 v[104:105], v[58:59], v[58:59]
	v_pk_mul_f32 v[106:107], v[56:57], v[56:57]
	v_fmamk_f32 v104, v104, 0xbdd2d3e8, v216
	v_fmamk_f32 v106, v106, 0xbdd2d3e8, v216
	v_fmamk_f32 v107, v107, 0xbdd2d3e8, v216
	v_fmamk_f32 v105, v105, 0xbdd2d3e8, v216
	v_mul_f32_e32 v106, v56, v106
	v_mul_f32_e32 v107, v57, v107
	v_mul_f32_e32 v104, v58, v104
	v_mul_f32_e32 v105, v59, v105
	v_exp_f32_e32 v106, v106
	v_exp_f32_e32 v107, v107
	v_exp_f32_e32 v104, v104
	v_exp_f32_e32 v105, v105
	v_add_f32_e32 v106, 1.0, v106
	v_add_f32_e32 v107, 1.0, v107
	v_add_f32_e32 v104, 1.0, v104
	v_add_f32_e32 v105, 1.0, v105
	v_rcp_f32_e32 v106, v106
	v_rcp_f32_e32 v104, v104
	v_rcp_f32_e32 v105, v105
	v_rcp_f32_e32 v107, v107
	v_pk_mul_f32 v[52:53], v[52:53], v[60:61]
	v_pk_mul_f32 v[54:55], v[54:55], v[62:63]
	v_pk_mul_f32 v[58:59], v[58:59], v[104:105]
	v_pk_mul_f32 v[56:57], v[56:57], v[106:107]
	v_pk_mul_f32 v[58:59], v[50:51], v[58:59]
	v_pk_mul_f32 v[50:51], v[48:49], v[56:57]
	v_cvt_pk_bf16_f32 v48, v52, v53
	v_mov_b64_e32 v[52:53], s[10:11]
	v_mad_i64_i32 v[52:53], s[8:9], v182, s66, v[52:53]
	v_cvt_pk_bf16_f32 v49, v54, v55
	v_cvt_pk_bf16_f32 v50, v50, v51
	v_cvt_pk_bf16_f32 v51, v58, v59
	v_lshl_add_u64 v[52:53], v[174:175], 1, v[52:53]
	global_store_dwordx4 v[52:53], v[48:51], off

;     __device__ __forceinline__ void operator()(EPI_ARGS) const {
;     ...
;         for (int ai = 0; ai < 2; ++ai) {
;             const int blk = u.pm * 4 + ai * 2 + wr;
;             f32x4 q1[2], q2[2];
; #pragma unroll
;             for (int n = 0; n < 2; ++n) { q1[n] = (f32x4){0.f, 0.f, 0.f, 0.f}; q2[n] = (f32x4){0.f, 0.f, 0.f, 0.f}; }
; #pragma unroll
;             for (int m = 0; m < 4; ++m) {
;                 const int row = ROW_OF(ai, m);
;                 const float rs = __builtin_amdgcn_rsqf(rsv[ai][m] * (1.0f / D) + EPS);
;                 f32x4 o[2];
; #pragma unroll
;                 for (int n = 0; n < 2; ++n) {
;                     const f32x4 gv = acc[ai][0][m][n] * rs, vv = acc[ai][1][m][n] * rs;
;                     f32x4 r1, r2;
; #pragma unroll
;                     for (int j = 0; j < 4; ++j) { r1[j] = __shfl(gv[j], src1); r2[j] = __shfl(gv[j], src2); }
;                     f32x4 p1, p2;
; #pragma unroll
;                     for (int j = 0; j < 4; ++j) { p1[j] = fr >= 1 ? r1[j] : q1[n][j]; p2[j] = fr >= 2 ? r2[j] : q2[n][j]; }
;                     q1[n] = r1; q2[n] = r2;
;                     const f32x4 cv = bb[n] + w0[n] * p2 + w1[n] * p1 + w2[n] * gv;
;                     o[n] = gelu4(cv) * vv;
.LBB0_942:
	s_or_b64 exec, exec, s[6:7]
	s_nop 0
	v_fmamk_f32 v48, v187, 0x3a000000, v215
	v_rsq_f32_e32 v52, v48
	v_lshl_add_u64 v[50:51], s[60:61], 0, v[168:169]
	v_mad_u64_u32 v[48:49], s[6:7], v50, s30, 0
	v_pk_mul_f32 v[46:47], v[46:47], v[52:53] op_sel_hi:[1,0]
	v_pk_mul_f32 v[44:45], v[44:45], v[52:53] op_sel_hi:[1,0]
	s_nop 1
	v_mov_b32_dpp v104, v46 row_ror:2 row_mask:0xf bank_mask:0xf
	v_mov_b32_dpp v106, v47 row_ror:2 row_mask:0xf bank_mask:0xf
	v_mov_b32_dpp v60, v44 row_ror:2 row_mask:0xf bank_mask:0xf
	v_mov_b32_dpp v62, v45 row_ror:2 row_mask:0xf bank_mask:0xf
	v_mov_b32_dpp v63, v46 row_ror:1 row_mask:0xf bank_mask:0xf
	v_mov_b32_dpp v105, v47 row_ror:1 row_mask:0xf bank_mask:0xf
	v_mov_b32_dpp v53, v44 row_ror:1 row_mask:0xf bank_mask:0xf
	v_mov_b32_dpp v61, v45 row_ror:1 row_mask:0xf bank_mask:0xf
	s_waitcnt lgkmcnt(7)
	v_cndmask_b32_e64 v58, v113, v104, s[0:1]
	s_waitcnt lgkmcnt(6)
	v_cndmask_b32_e64 v59, v115, v106, s[0:1]
	s_waitcnt lgkmcnt(5)
	v_cndmask_b32_e64 v54, v109, v60, s[0:1]
	s_waitcnt lgkmcnt(4)
	v_cndmask_b32_e64 v55, v111, v62, s[0:1]
	s_waitcnt lgkmcnt(3)
	v_cndmask_b32_e32 v56, v112, v63, vcc
	s_waitcnt lgkmcnt(2)
	v_cndmask_b32_e32 v57, v114, v105, vcc
	v_pk_fma_f32 v[58:59], v[74:75], v[58:59], v[78:79]
	v_mad_i32_i24 v49, v51, s30, v49
	s_waitcnt lgkmcnt(1)
	v_cndmask_b32_e32 v50, v108, v53, vcc
	s_waitcnt lgkmcnt(0)
	v_cndmask_b32_e32 v51, v110, v61, vcc
	v_pk_fma_f32 v[54:55], v[72:73], v[54:55], v[76:77]
	v_pk_fma_f32 v[56:57], v[66:67], v[56:57], v[58:59]
	v_pk_fma_f32 v[50:51], v[64:65], v[50:51], v[54:55]
	v_pk_fma_f32 v[46:47], v[70:71], v[46:47], v[56:57]
	v_pk_fma_f32 v[44:45], v[68:69], v[44:45], v[50:51]
	v_pk_mul_f32 v[50:51], v[46:47], v[46:47]
	v_pk_mul_f32 v[54:55], v[44:45], v[44:45]
	v_fmamk_f32 v50, v50, 0xbdd2d3e8, v216
	v_mul_f32_e32 v50, v46, v50
	v_fmamk_f32 v54, v54, 0xbdd2d3e8, v216
	v_fmamk_f32 v55, v55, 0xbdd2d3e8, v216
	v_exp_f32_e32 v56, v50
	v_fmamk_f32 v50, v51, 0xbdd2d3e8, v216
	v_mul_f32_e32 v54, v44, v54
	v_mul_f32_e32 v55, v45, v55
	v_mul_f32_e32 v50, v47, v50
	v_exp_f32_e32 v54, v54
	v_exp_f32_e32 v55, v55
	v_exp_f32_e32 v57, v50
	v_pk_mul_f32 v[42:43], v[42:43], v[52:53] op_sel_hi:[1,0]
	v_add_f32_e32 v50, 1.0, v54
	v_add_f32_e32 v51, 1.0, v55
	v_add_f32_e32 v54, 1.0, v56
	v_add_f32_e32 v55, 1.0, v57
	v_pk_mul_f32 v[40:41], v[40:41], v[52:53] op_sel_hi:[1,0]
	s_nop 1
	v_mov_b32_dpp v108, v42 row_ror:2 row_mask:0xf bank_mask:0xf
	v_mov_b32_dpp v110, v43 row_ror:2 row_mask:0xf bank_mask:0xf
	v_rcp_f32_e32 v54, v54
	v_rcp_f32_e32 v55, v55
	s_nop 1
	v_mov_b32_dpp v57, v40 row_ror:2 row_mask:0xf bank_mask:0xf
	v_mov_b32_dpp v59, v41 row_ror:2 row_mask:0xf bank_mask:0xf
	v_mov_b32_dpp v107, v42 row_ror:1 row_mask:0xf bank_mask:0xf
	v_mov_b32_dpp v109, v43 row_ror:1 row_mask:0xf bank_mask:0xf
	v_rcp_f32_e32 v50, v50
	v_rcp_f32_e32 v51, v51
	s_nop 1
	v_mov_b32_dpp v56, v40 row_ror:1 row_mask:0xf bank_mask:0xf
	v_mov_b32_dpp v58, v41 row_ror:1 row_mask:0xf bank_mask:0xf
	v_pk_mul_f32 v[38:39], v[38:39], v[52:53] op_sel_hi:[1,0]
	v_pk_mul_f32 v[46:47], v[46:47], v[54:55]
	s_waitcnt lgkmcnt(7)
	v_cndmask_b32_e64 v54, v102, v108, s[0:1]
	s_waitcnt lgkmcnt(6)
	v_cndmask_b32_e64 v55, v103, v110, s[0:1]
	v_pk_mul_f32 v[36:37], v[36:37], v[52:53] op_sel_hi:[1,0]
	v_pk_mul_f32 v[44:45], v[44:45], v[50:51]
	v_pk_mul_f32 v[38:39], v[38:39], v[46:47]
	s_waitcnt lgkmcnt(5)
	v_cndmask_b32_e64 v46, v100, v57, s[0:1]
	s_waitcnt lgkmcnt(4)
	v_cndmask_b32_e64 v47, v101, v59, s[0:1]
	s_waitcnt lgkmcnt(3)
	v_cndmask_b32_e32 v50, v82, v107, vcc
	s_waitcnt lgkmcnt(2)
	v_cndmask_b32_e32 v51, v83, v109, vcc
	v_pk_fma_f32 v[54:55], v[94:95], v[54:55], v[98:99]
	v_pk_mul_f32 v[36:37], v[36:37], v[44:45]
	s_waitcnt lgkmcnt(1)
	v_cndmask_b32_e32 v44, v80, v56, vcc
	s_waitcnt lgkmcnt(0)
	v_cndmask_b32_e32 v45, v81, v58, vcc
	v_pk_fma_f32 v[46:47], v[92:93], v[46:47], v[96:97]
	v_pk_fma_f32 v[50:51], v[86:87], v[50:51], v[54:55]
	v_pk_fma_f32 v[44:45], v[84:85], v[44:45], v[46:47]
	v_pk_fma_f32 v[42:43], v[90:91], v[42:43], v[50:51]
	v_pk_fma_f32 v[40:41], v[88:89], v[40:41], v[44:45]
	v_pk_mul_f32 v[44:45], v[42:43], v[42:43]
	v_pk_mul_f32 v[46:47], v[40:41], v[40:41]
	v_fmamk_f32 v44, v44, 0xbdd2d3e8, v216
	v_mul_f32_e32 v44, v42, v44
	v_fmamk_f32 v46, v46, 0xbdd2d3e8, v216
	v_fmamk_f32 v47, v47, 0xbdd2d3e8, v216
	v_exp_f32_e32 v50, v44
	v_fmamk_f32 v44, v45, 0xbdd2d3e8, v216
	v_mul_f32_e32 v46, v40, v46
	v_mul_f32_e32 v47, v41, v47
	v_mul_f32_e32 v44, v43, v44
	v_exp_f32_e32 v46, v46
	v_exp_f32_e32 v47, v47
	v_exp_f32_e32 v51, v44
	v_pk_mul_f32 v[32:33], v[32:33], v[52:53] op_sel_hi:[1,0]
	v_add_f32_e32 v44, 1.0, v46
	v_add_f32_e32 v45, 1.0, v47
	v_add_f32_e32 v46, 1.0, v50
	v_add_f32_e32 v47, 1.0, v51
	v_rcp_f32_e32 v44, v44
	v_rcp_f32_e32 v45, v45
	v_rcp_f32_e32 v46, v46
	v_rcp_f32_e32 v47, v47
	v_pk_mul_f32 v[34:35], v[34:35], v[52:53] op_sel_hi:[1,0]
	v_pk_mul_f32 v[40:41], v[40:41], v[44:45]
	v_pk_mul_f32 v[42:43], v[42:43], v[46:47]
	s_nop 0
	v_pk_mul_f32 v[42:43], v[34:35], v[42:43]
	v_pk_mul_f32 v[34:35], v[32:33], v[40:41]
	v_cvt_pk_bf16_f32 v32, v36, v37
	v_fmamk_f32 v36, v183, 0x3a000000, v215
	v_rsq_f32_e32 v44, v36
	v_cvt_pk_bf16_f32 v33, v38, v39
	v_cvt_pk_bf16_f32 v34, v34, v35
	v_cvt_pk_bf16_f32 v35, v42, v43
	v_mov_b64_e32 v[42:43], s[10:11]
	v_mad_i64_i32 v[36:37], s[6:7], v180, s66, v[42:43]
	v_lshl_add_u64 v[36:37], v[36:37], 0, v[128:129]
	global_store_dwordx4 v[36:37], v[32:35], off
	v_pk_mul_f32 v[36:37], v[30:31], v[44:45] op_sel_hi:[1,0]
	v_pk_mul_f32 v[38:39], v[28:29], v[44:45] op_sel_hi:[1,0]
	s_nop 1
	v_mov_b32_dpp v28, v38 row_ror:1 row_mask:0xf bank_mask:0xf
	v_mov_b32_dpp v34, v36 row_ror:2 row_mask:0xf bank_mask:0xf
	v_mov_b32_dpp v35, v37 row_ror:2 row_mask:0xf bank_mask:0xf
	v_mov_b32_dpp v32, v38 row_ror:2 row_mask:0xf bank_mask:0xf
	v_mov_b32_dpp v33, v39 row_ror:2 row_mask:0xf bank_mask:0xf
	v_mov_b32_dpp v30, v36 row_ror:1 row_mask:0xf bank_mask:0xf
	v_mov_b32_dpp v31, v37 row_ror:1 row_mask:0xf bank_mask:0xf
	v_mov_b32_dpp v29, v39 row_ror:1 row_mask:0xf bank_mask:0xf
	s_waitcnt lgkmcnt(7)
; __device__ __forceinline__ unsigned cvt_pk_bf16(float lo, float hi) { unsigned r; asm volatile("v_cvt_pk_bf16_f32 %0, %1, %2" : "=v"(r) : "v"(lo), "v"(hi)); return r; }
;     __device__ __forceinline__ void operator()(EPI_ARGS) const {
;     ...
; #pragma unroll
;             for (int m = 0; m < 4; ++m) {
;                 const int row = ROW_OF(ai, m);
;                 const float rs = __builtin_amdgcn_rsqf(rsv[ai][m] * (1.0f / D) + EPS);
;                 f32x4 o[2];
; #pragma unroll
;                 for (int n = 0; n < 2; ++n) {
;                     const f32x4 gv = acc[ai][0][m][n] * rs, vv = acc[ai][1][m][n] * rs;
;                     f32x4 r1, r2;
; #pragma unroll
;                     for (int j = 0; j < 4; ++j) { r1[j] = __shfl(gv[j], src1); r2[j] = __shfl(gv[j], src2); }
;                     f32x4 p1, p2;
; #pragma unroll
;                     for (int j = 0; j < 4; ++j) { p1[j] = fr >= 1 ? r1[j] : q1[n][j]; p2[j] = fr >= 2 ? r2[j] : q2[n][j]; }
;                     q1[n] = r1; q2[n] = r2;
;                     const f32x4 cv = bb[n] + w0[n] * p2 + w1[n] * p1 + w2[n] * gv;
;                     o[n] = gelu4(cv) * vv;
;                     if (m == 0 && fr < 2) { const size_t so = ((size_t)blk * 2 + fr) * FF + f0 + 4 * n; *(f32x4*)(headg + so) = gv; *(f32x4*)(headv + so) = vv; }
;                     if (m == 3 && fr >= 14) { const size_t so = ((size_t)blk * 2 + (fr - 14)) * FF + f0 + 4 * n; *(f32x4*)(tailg + so) = gv; }
;                 }
;                 if (!(m == 0 && fr < 2)) {
;                     u32x4 w; w.x = cvt_pk_bf16(o[0][0], o[0][1]); w.y = cvt_pk_bf16(o[0][2], o[0][3]); w.z = cvt_pk_bf16(o[1][0], o[1][1]); w.w = cvt_pk_bf16(o[1][2], o[1][3]);
;                     *(u32x4*)(act + (size_t)row * FF + f0) = w;
	v_cndmask_b32_e32 v40, v53, v28, vcc
	s_waitcnt lgkmcnt(6)
	v_cndmask_b32_e64 v52, v104, v34, s[0:1]
	s_waitcnt lgkmcnt(5)
	v_cndmask_b32_e64 v53, v106, v35, s[0:1]
	s_waitcnt lgkmcnt(4)
	v_cndmask_b32_e64 v46, v60, v32, s[0:1]
	s_waitcnt lgkmcnt(3)
	v_cndmask_b32_e64 v47, v62, v33, s[0:1]
	s_waitcnt lgkmcnt(2)
	v_cndmask_b32_e32 v50, v63, v30, vcc
	s_waitcnt lgkmcnt(1)
	v_cndmask_b32_e32 v51, v105, v31, vcc
	v_pk_fma_f32 v[52:53], v[74:75], v[52:53], v[78:79]
	s_waitcnt lgkmcnt(0)
	v_cndmask_b32_e32 v41, v61, v29, vcc
	v_pk_fma_f32 v[46:47], v[72:73], v[46:47], v[76:77]
	v_pk_fma_f32 v[50:51], v[66:67], v[50:51], v[52:53]
	v_pk_fma_f32 v[40:41], v[64:65], v[40:41], v[46:47]
	v_pk_fma_f32 v[36:37], v[70:71], v[36:37], v[50:51]
	v_pk_fma_f32 v[38:39], v[68:69], v[38:39], v[40:41]
	v_pk_mul_f32 v[40:41], v[36:37], v[36:37]
	v_pk_mul_f32 v[46:47], v[38:39], v[38:39]
	v_fmamk_f32 v40, v40, 0xbdd2d3e8, v216
	v_fmamk_f32 v45, v46, 0xbdd2d3e8, v216
	v_mul_f32_e32 v40, v36, v40
	v_mul_f32_e32 v45, v38, v45
	v_fmamk_f32 v46, v47, 0xbdd2d3e8, v216
	v_exp_f32_e32 v47, v40
	v_fmamk_f32 v40, v41, 0xbdd2d3e8, v216
	v_exp_f32_e32 v45, v45
	v_mul_f32_e32 v46, v39, v46
	v_mul_f32_e32 v40, v37, v40
	v_exp_f32_e32 v46, v46
	v_exp_f32_e32 v50, v40
	v_add_f32_e32 v40, 1.0, v45
	v_add_f32_e32 v45, 1.0, v47
	v_add_f32_e32 v41, 1.0, v46
	v_rcp_f32_e32 v46, v45
	v_add_f32_e32 v45, 1.0, v50
	v_rcp_f32_e32 v47, v45
	v_rcp_f32_e32 v40, v40
	v_rcp_f32_e32 v41, v41
	v_pk_mul_f32 v[22:23], v[22:23], v[44:45] op_sel_hi:[1,0]
	v_pk_mul_f32 v[36:37], v[36:37], v[46:47]
	v_pk_mul_f32 v[52:53], v[24:25], v[44:45] op_sel_hi:[1,0]
	v_pk_mul_f32 v[46:47], v[22:23], v[36:37]
	v_pk_mul_f32 v[50:51], v[26:27], v[44:45] op_sel_hi:[1,0]
	s_nop 1
	v_mov_b32_dpp v22, v52 row_ror:1 row_mask:0xf bank_mask:0xf
	v_mov_b32_dpp v26, v52 row_ror:2 row_mask:0xf bank_mask:0xf
	v_mov_b32_dpp v36, v53 row_ror:2 row_mask:0xf bank_mask:0xf
	v_pk_mul_f32 v[20:21], v[20:21], v[44:45] op_sel_hi:[1,0]
	v_pk_mul_f32 v[38:39], v[38:39], v[40:41]
	s_nop 1
	v_mov_b32_dpp v23, v53 row_ror:1 row_mask:0xf bank_mask:0xf
	v_pk_mul_f32 v[20:21], v[20:21], v[38:39]
	s_nop 1
	v_mov_b32_dpp v38, v50 row_ror:2 row_mask:0xf bank_mask:0xf
	v_mov_b32_dpp v40, v51 row_ror:2 row_mask:0xf bank_mask:0xf
	v_mov_b32_dpp v24, v50 row_ror:1 row_mask:0xf bank_mask:0xf
	v_mov_b32_dpp v25, v51 row_ror:1 row_mask:0xf bank_mask:0xf
	s_waitcnt lgkmcnt(7)
	v_cndmask_b32_e32 v54, v56, v22, vcc
	s_waitcnt lgkmcnt(6)
	v_cndmask_b32_e64 v56, v57, v26, s[0:1]
	s_waitcnt lgkmcnt(5)
	v_cndmask_b32_e64 v57, v59, v36, s[0:1]
	s_waitcnt lgkmcnt(4)
	v_cndmask_b32_e32 v55, v58, v23, vcc
	v_pk_fma_f32 v[56:57], v[92:93], v[56:57], v[96:97]
	s_waitcnt lgkmcnt(3)
	v_cndmask_b32_e64 v60, v108, v38, s[0:1]
	s_waitcnt lgkmcnt(2)
	v_cndmask_b32_e64 v61, v110, v40, s[0:1]
	v_pk_fma_f32 v[54:55], v[84:85], v[54:55], v[56:57]
	s_waitcnt lgkmcnt(1)
	v_cndmask_b32_e32 v58, v107, v24, vcc
	s_waitcnt lgkmcnt(0)
	v_cndmask_b32_e32 v59, v109, v25, vcc
	v_pk_fma_f32 v[60:61], v[94:95], v[60:61], v[98:99]
	v_pk_fma_f32 v[52:53], v[88:89], v[52:53], v[54:55]
	v_pk_fma_f32 v[58:59], v[86:87], v[58:59], v[60:61]
	v_pk_mul_f32 v[56:57], v[52:53], v[52:53]
	v_pk_fma_f32 v[50:51], v[90:91], v[50:51], v[58:59]
	v_fmamk_f32 v27, v56, 0xbdd2d3e8, v216
	v_pk_mul_f32 v[54:55], v[50:51], v[50:51]
	v_mul_f32_e32 v27, v52, v27
	v_fmamk_f32 v37, v57, 0xbdd2d3e8, v216
	v_exp_f32_e32 v27, v27
	v_mul_f32_e32 v37, v53, v37
	v_fmamk_f32 v39, v54, 0xbdd2d3e8, v216
	v_exp_f32_e32 v37, v37
	v_mul_f32_e32 v39, v50, v39
	v_fmamk_f32 v41, v55, 0xbdd2d3e8, v216
	v_exp_f32_e32 v39, v39
	v_mul_f32_e32 v41, v51, v41
	v_exp_f32_e32 v41, v41
	v_add_f32_e32 v27, 1.0, v27
	v_rcp_f32_e32 v54, v27
	v_add_f32_e32 v27, 1.0, v37
	v_rcp_f32_e32 v55, v27
	v_add_f32_e32 v27, 1.0, v39
	v_rcp_f32_e32 v56, v27
	v_add_f32_e32 v27, 1.0, v41
	v_rcp_f32_e32 v57, v27
	v_pk_mul_f32 v[16:17], v[16:17], v[44:45] op_sel_hi:[1,0]
	v_pk_mul_f32 v[18:19], v[18:19], v[44:45] op_sel_hi:[1,0]
	v_pk_mul_f32 v[44:45], v[52:53], v[54:55]
	v_pk_mul_f32 v[50:51], v[50:51], v[56:57]
	v_pk_mul_f32 v[16:17], v[16:17], v[44:45]
	v_pk_mul_f32 v[50:51], v[18:19], v[50:51]
	v_cvt_pk_bf16_f32 v18, v20, v21
	v_cvt_pk_bf16_f32 v19, v46, v47
	v_cvt_pk_bf16_f32 v20, v16, v17
	v_fmamk_f32 v16, v181, 0x3a000000, v215
	v_rsq_f32_e32 v16, v16
	v_mad_i64_i32 v[46:47], s[6:7], v178, s66, v[42:43]
	v_lshl_add_u64 v[46:47], v[46:47], 0, v[128:129]
	v_pk_mul_f32 v[14:15], v[14:15], v[16:17] op_sel_hi:[1,0]
	v_pk_mul_f32 v[12:13], v[12:13], v[16:17] op_sel_hi:[1,0]
	s_nop 1
	v_mov_b32_dpp v27, v12 row_ror:1 row_mask:0xf bank_mask:0xf
	v_mov_b32_dpp v42, v12 row_ror:2 row_mask:0xf bank_mask:0xf
	v_mov_b32_dpp v37, v13 row_ror:1 row_mask:0xf bank_mask:0xf
	v_mov_b32_dpp v43, v13 row_ror:2 row_mask:0xf bank_mask:0xf
	v_mov_b32_dpp v39, v14 row_ror:1 row_mask:0xf bank_mask:0xf
	v_mov_b32_dpp v44, v14 row_ror:2 row_mask:0xf bank_mask:0xf
	v_mov_b32_dpp v41, v15 row_ror:1 row_mask:0xf bank_mask:0xf
	v_mov_b32_dpp v45, v15 row_ror:2 row_mask:0xf bank_mask:0xf
	v_cvt_pk_bf16_f32 v21, v50, v51
	global_store_dwordx4 v[46:47], v[18:21], off
	s_nop 1
	v_lshl_add_u64 v[18:19], s[40:41], 0, v[48:49]
	v_lshl_add_u64 v[20:21], v[174:175], 2, v[18:19]
	s_and_saveexec_b64 s[6:7], s[4:5]
	s_cbranch_execz .LBB0_944
	global_store_dwordx4 v[20:21], v[12:15], off
.LBB0_944:
	s_or_b64 exec, exec, s[6:7]
	v_mov_b32_e32 v17, v16
	v_mov_b32_e32 v18, v16
	v_mov_b32_e32 v19, v16
	v_pk_mul_f32 v[10:11], v[10:11], v[18:19]
	v_pk_mul_f32 v[8:9], v[8:9], v[16:17]
	s_nop 1
	v_mov_b32_dpp v46, v8 row_ror:1 row_mask:0xf bank_mask:0xf
	v_mov_b32_dpp v50, v8 row_ror:2 row_mask:0xf bank_mask:0xf
	v_mov_b32_dpp v47, v9 row_ror:1 row_mask:0xf bank_mask:0xf
	v_mov_b32_dpp v51, v9 row_ror:2 row_mask:0xf bank_mask:0xf
	v_mov_b32_dpp v48, v10 row_ror:1 row_mask:0xf bank_mask:0xf
	v_mov_b32_dpp v52, v10 row_ror:2 row_mask:0xf bank_mask:0xf
	v_mov_b32_dpp v49, v11 row_ror:1 row_mask:0xf bank_mask:0xf
	v_mov_b32_dpp v53, v11 row_ror:2 row_mask:0xf bank_mask:0xf
	s_and_saveexec_b64 s[6:7], s[4:5]
	s_cbranch_execz .LBB0_946
	global_store_dwordx4 v[20:21], v[8:11], off offset:16
